# final LayerNorm fused into last FFN-out epilogue via 4-WG row-stat handshake; early exit; mid-segment setprio pairs removed
# speedup vs baseline: 1.0014x; 1.0014x over previous
.LBB0_180:
	s_add_u32 s28, s50, 0xfffc0080
	s_addc_u32 s29, s51, -1
	s_add_i32 s72, 0, 0x10000
	s_cmp_eq_u32 s71, 12
	s_cselect_b32 s55, s45, s29
	s_cselect_b32 s54, s67, s28
	v_add_u32_e32 v138, s72, v141
	s_cselect_b32 s53, s43, s70
	s_cselect_b32 s52, s68, s69
	s_add_i32 s73, 0, 0x14000
	ds_read_b128 v[158:161], v138
	ds_read_b128 v[162:165], v138 offset:1024
	ds_read_b128 v[166:169], v138 offset:2048
	ds_read_b128 v[170:173], v138 offset:3072
	v_add_u32_e32 v138, s73, v141
	ds_read_b128 v[174:177], v138
	ds_read_b128 v[178:181], v138 offset:1024
	ds_read_b128 v[182:185], v138 offset:2048
	ds_read_b128 v[186:189], v138 offset:3072
	v_lshl_add_u64 v[138:139], s[50:51], 0, v[134:135]
	s_add_i32 m0, s58, 0xc000
	ds_read_b128 v[190:193], v157
	ds_read_b128 v[194:197], v157 offset:1024
	ds_read_b128 v[198:201], v157 offset:2048
	ds_read_b128 v[202:205], v157 offset:3072
	ds_read_b128 v[206:209], v157 offset:4096
	ds_read_b128 v[210:213], v157 offset:5120
	ds_read_b128 v[214:217], v157 offset:6144
	ds_read_b128 v[218:221], v157 offset:7168
	global_load_lds_dwordx4 v[138:139], off
	v_lshl_add_u64 v[138:139], s[50:51], 0, v[136:137]
	s_add_i32 m0, s58, 0xe000
	s_nop 0
	global_load_lds_dwordx4 v[138:139], off
	s_waitcnt vmcnt(8)
	s_waitcnt lgkmcnt(0)
	s_barrier
	s_setprio 1
	s_waitcnt lgkmcnt(0)
	v_mfma_f32_16x16x32_bf16 v[124:127], v[158:161], v[190:193], v[124:127]
	v_mfma_f32_16x16x32_bf16 v[116:119], v[166:169], v[190:193], v[116:119]
	v_mfma_f32_16x16x32_bf16 v[108:111], v[158:161], v[198:201], v[108:111]
	v_mfma_f32_16x16x32_bf16 v[100:103], v[166:169], v[198:201], v[100:103]
	v_mfma_f32_16x16x32_bf16 v[92:95], v[158:161], v[206:209], v[92:95]
	v_mfma_f32_16x16x32_bf16 v[84:87], v[166:169], v[206:209], v[84:87]
	v_mfma_f32_16x16x32_bf16 v[76:79], v[158:161], v[214:217], v[76:79]
	v_mfma_f32_16x16x32_bf16 v[68:71], v[166:169], v[214:217], v[68:71]
	v_mfma_f32_16x16x32_bf16 v[124:127], v[162:165], v[194:197], v[124:127]
	v_mfma_f32_16x16x32_bf16 v[116:119], v[170:173], v[194:197], v[116:119]
	v_mfma_f32_16x16x32_bf16 v[108:111], v[162:165], v[202:205], v[108:111]
	v_mfma_f32_16x16x32_bf16 v[100:103], v[170:173], v[202:205], v[100:103]
	v_mfma_f32_16x16x32_bf16 v[92:95], v[162:165], v[210:213], v[92:95]
	v_mfma_f32_16x16x32_bf16 v[84:87], v[170:173], v[210:213], v[84:87]
	v_mfma_f32_16x16x32_bf16 v[76:79], v[162:165], v[218:221], v[76:79]
	v_mfma_f32_16x16x32_bf16 v[68:71], v[170:173], v[218:221], v[68:71]
	v_mfma_f32_16x16x32_bf16 v[120:123], v[174:177], v[190:193], v[120:123]
	v_mfma_f32_16x16x32_bf16 v[112:115], v[182:185], v[190:193], v[112:115]
	v_mfma_f32_16x16x32_bf16 v[104:107], v[174:177], v[198:201], v[104:107]
	v_mfma_f32_16x16x32_bf16 v[96:99], v[182:185], v[198:201], v[96:99]
	v_mfma_f32_16x16x32_bf16 v[88:91], v[174:177], v[206:209], v[88:91]
	v_mfma_f32_16x16x32_bf16 v[80:83], v[182:185], v[206:209], v[80:83]
	v_mfma_f32_16x16x32_bf16 v[72:75], v[174:177], v[214:217], v[72:75]
	v_mfma_f32_16x16x32_bf16 v[64:67], v[182:185], v[214:217], v[64:67]
	v_mfma_f32_16x16x32_bf16 v[120:123], v[178:181], v[194:197], v[120:123]
	v_mfma_f32_16x16x32_bf16 v[112:115], v[186:189], v[194:197], v[112:115]
	v_mfma_f32_16x16x32_bf16 v[104:107], v[178:181], v[202:205], v[104:107]
	v_mfma_f32_16x16x32_bf16 v[96:99], v[186:189], v[202:205], v[96:99]
	v_mfma_f32_16x16x32_bf16 v[88:91], v[178:181], v[210:213], v[88:91]
	v_mfma_f32_16x16x32_bf16 v[80:83], v[186:189], v[210:213], v[80:83]
	v_mfma_f32_16x16x32_bf16 v[72:75], v[178:181], v[218:221], v[72:75]
	v_mfma_f32_16x16x32_bf16 v[64:67], v[186:189], v[218:221], v[64:67]
	s_setprio 0
	s_barrier
	s_add_i32 s28, s72, s57
	v_lshl_add_u64 v[138:139], s[52:53], 0, v[142:143]
	s_mov_b32 m0, s28
	ds_read_b128 v[190:193], v157 offset:16384
	ds_read_b128 v[194:197], v157 offset:17408
	ds_read_b128 v[198:201], v157 offset:18432
	ds_read_b128 v[202:205], v157 offset:19456
	ds_read_b128 v[206:209], v157 offset:20480
	ds_read_b128 v[210:213], v157 offset:21504
	ds_read_b128 v[214:217], v157 offset:22528
	ds_read_b128 v[218:221], v157 offset:23552
	global_load_lds_dwordx4 v[138:139], off
	s_add_i32 m0, s28, 0x2000
	s_add_u32 s28, s52, 0x40000
	v_lshl_add_u64 v[230:231], s[52:53], 0, v[128:129]
	s_addc_u32 s29, s53, 0
	s_add_i32 s72, s73, s57
	global_load_lds_dwordx4 v[230:231], off
	v_lshl_add_u64 v[232:233], s[28:29], 0, v[142:143]
	s_mov_b32 m0, s72
	v_lshl_add_u64 v[234:235], s[54:55], 0, v[130:131]
	global_load_lds_dwordx4 v[232:233], off
	v_lshl_add_u64 v[232:233], s[28:29], 0, v[128:129]
	s_add_i32 m0, s72, 0x2000
	s_nop 0
	global_load_lds_dwordx4 v[232:233], off
	v_lshl_add_u64 v[232:233], s[54:55], 0, v[132:133]
	s_mov_b32 m0, s58
	s_nop 0
	global_load_lds_dwordx4 v[232:233], off
	s_mov_b32 m0, s59
	s_nop 0
	global_load_lds_dwordx4 v[234:235], off
	s_waitcnt vmcnt(8)
	s_waitcnt lgkmcnt(0)
	s_barrier
	s_setprio 1
	s_waitcnt lgkmcnt(0)
	v_mfma_f32_16x16x32_bf16 v[60:63], v[158:161], v[190:193], v[60:63]
	v_mfma_f32_16x16x32_bf16 v[52:55], v[166:169], v[190:193], v[52:55]
	v_mfma_f32_16x16x32_bf16 v[44:47], v[158:161], v[198:201], v[44:47]
	v_mfma_f32_16x16x32_bf16 v[36:39], v[166:169], v[198:201], v[36:39]
	v_mfma_f32_16x16x32_bf16 v[28:31], v[158:161], v[206:209], v[28:31]
	v_mfma_f32_16x16x32_bf16 v[20:23], v[166:169], v[206:209], v[20:23]
	v_mfma_f32_16x16x32_bf16 v[12:15], v[158:161], v[214:217], v[12:15]
	v_mfma_f32_16x16x32_bf16 v[4:7], v[166:169], v[214:217], v[4:7]
	v_mfma_f32_16x16x32_bf16 v[60:63], v[162:165], v[194:197], v[60:63]
	v_mfma_f32_16x16x32_bf16 v[52:55], v[170:173], v[194:197], v[52:55]
	v_mfma_f32_16x16x32_bf16 v[44:47], v[162:165], v[202:205], v[44:47]
	v_mfma_f32_16x16x32_bf16 v[36:39], v[170:173], v[202:205], v[36:39]
	v_mfma_f32_16x16x32_bf16 v[28:31], v[162:165], v[210:213], v[28:31]
	v_mfma_f32_16x16x32_bf16 v[20:23], v[170:173], v[210:213], v[20:23]
	v_mfma_f32_16x16x32_bf16 v[12:15], v[162:165], v[218:221], v[12:15]
	v_mfma_f32_16x16x32_bf16 v[4:7], v[170:173], v[218:221], v[4:7]
	v_mfma_f32_16x16x32_bf16 v[56:59], v[174:177], v[190:193], v[56:59]
	v_mfma_f32_16x16x32_bf16 v[48:51], v[182:185], v[190:193], v[48:51]
	v_mfma_f32_16x16x32_bf16 v[40:43], v[174:177], v[198:201], v[40:43]
	v_mfma_f32_16x16x32_bf16 v[32:35], v[182:185], v[198:201], v[32:35]
	v_mfma_f32_16x16x32_bf16 v[24:27], v[174:177], v[206:209], v[24:27]
	v_mfma_f32_16x16x32_bf16 v[16:19], v[182:185], v[206:209], v[16:19]
	v_mfma_f32_16x16x32_bf16 v[8:11], v[174:177], v[214:217], v[8:11]
	v_mfma_f32_16x16x32_bf16 v[0:3], v[182:185], v[214:217], v[0:3]
	v_mfma_f32_16x16x32_bf16 v[56:59], v[178:181], v[194:197], v[56:59]
	v_mfma_f32_16x16x32_bf16 v[48:51], v[186:189], v[194:197], v[48:51]
	v_mfma_f32_16x16x32_bf16 v[40:43], v[178:181], v[202:205], v[40:43]
	v_mfma_f32_16x16x32_bf16 v[32:35], v[186:189], v[202:205], v[32:35]
	v_mfma_f32_16x16x32_bf16 v[24:27], v[178:181], v[210:213], v[24:27]
	v_mfma_f32_16x16x32_bf16 v[16:19], v[186:189], v[210:213], v[16:19]
	v_mfma_f32_16x16x32_bf16 v[8:11], v[178:181], v[218:221], v[8:11]
	v_mfma_f32_16x16x32_bf16 v[0:3], v[186:189], v[218:221], v[0:3]
	s_setprio 0
	s_barrier
	s_add_i32 s72, 0, 0x18000
	s_add_i32 s73, 0, 0x1c000
	v_add_u32_e32 v170, s72, v141
	v_add_u32_e32 v186, s73, v141
	ds_read_b128 v[158:161], v170
	ds_read_b128 v[162:165], v170 offset:1024
	ds_read_b128 v[166:169], v170 offset:2048
	ds_read_b128 v[170:173], v170 offset:3072
	ds_read_b128 v[174:177], v186
	ds_read_b128 v[178:181], v186 offset:1024
	ds_read_b128 v[182:185], v186 offset:2048
	ds_read_b128 v[186:189], v186 offset:3072
	s_add_u32 s28, s54, 0x40000
	s_addc_u32 s29, s55, 0
	s_mov_b32 m0, s60
	v_lshl_add_u64 v[236:237], s[28:29], 0, v[132:133]
	ds_read_b128 v[190:193], v157 offset:32768
	ds_read_b128 v[194:197], v157 offset:33792
	ds_read_b128 v[198:201], v157 offset:34816
	ds_read_b128 v[202:205], v157 offset:35840
	ds_read_b128 v[206:209], v157 offset:36864
	ds_read_b128 v[210:213], v157 offset:37888
	ds_read_b128 v[214:217], v157 offset:38912
	ds_read_b128 v[218:221], v157 offset:39936
	global_load_lds_dwordx4 v[236:237], off
	v_lshl_add_u64 v[236:237], s[28:29], 0, v[130:131]
	s_mov_b32 m0, s61
	s_nop 0
	global_load_lds_dwordx4 v[236:237], off
	s_waitcnt vmcnt(8)
	s_waitcnt lgkmcnt(0)
	s_barrier
	s_setprio 1
	s_waitcnt lgkmcnt(0)
	v_mfma_f32_16x16x32_bf16 v[124:127], v[158:161], v[190:193], v[124:127]
	v_mfma_f32_16x16x32_bf16 v[116:119], v[166:169], v[190:193], v[116:119]
	v_mfma_f32_16x16x32_bf16 v[108:111], v[158:161], v[198:201], v[108:111]
	v_mfma_f32_16x16x32_bf16 v[100:103], v[166:169], v[198:201], v[100:103]
	v_mfma_f32_16x16x32_bf16 v[92:95], v[158:161], v[206:209], v[92:95]
	v_mfma_f32_16x16x32_bf16 v[84:87], v[166:169], v[206:209], v[84:87]
	v_mfma_f32_16x16x32_bf16 v[76:79], v[158:161], v[214:217], v[76:79]
	v_mfma_f32_16x16x32_bf16 v[68:71], v[166:169], v[214:217], v[68:71]
	v_mfma_f32_16x16x32_bf16 v[124:127], v[162:165], v[194:197], v[124:127]
	v_mfma_f32_16x16x32_bf16 v[116:119], v[170:173], v[194:197], v[116:119]
	v_mfma_f32_16x16x32_bf16 v[108:111], v[162:165], v[202:205], v[108:111]
	v_mfma_f32_16x16x32_bf16 v[100:103], v[170:173], v[202:205], v[100:103]
	v_mfma_f32_16x16x32_bf16 v[92:95], v[162:165], v[210:213], v[92:95]
	v_mfma_f32_16x16x32_bf16 v[84:87], v[170:173], v[210:213], v[84:87]
	v_mfma_f32_16x16x32_bf16 v[76:79], v[162:165], v[218:221], v[76:79]
	v_mfma_f32_16x16x32_bf16 v[68:71], v[170:173], v[218:221], v[68:71]
	v_mfma_f32_16x16x32_bf16 v[120:123], v[174:177], v[190:193], v[120:123]
	v_mfma_f32_16x16x32_bf16 v[112:115], v[182:185], v[190:193], v[112:115]
	v_mfma_f32_16x16x32_bf16 v[104:107], v[174:177], v[198:201], v[104:107]
	v_mfma_f32_16x16x32_bf16 v[96:99], v[182:185], v[198:201], v[96:99]
	v_mfma_f32_16x16x32_bf16 v[88:91], v[174:177], v[206:209], v[88:91]
	v_mfma_f32_16x16x32_bf16 v[80:83], v[182:185], v[206:209], v[80:83]
	v_mfma_f32_16x16x32_bf16 v[72:75], v[174:177], v[214:217], v[72:75]
	v_mfma_f32_16x16x32_bf16 v[64:67], v[182:185], v[214:217], v[64:67]
	v_mfma_f32_16x16x32_bf16 v[120:123], v[178:181], v[194:197], v[120:123]
	v_mfma_f32_16x16x32_bf16 v[112:115], v[186:189], v[194:197], v[112:115]
	v_mfma_f32_16x16x32_bf16 v[104:107], v[178:181], v[202:205], v[104:107]
	v_mfma_f32_16x16x32_bf16 v[96:99], v[186:189], v[202:205], v[96:99]
	v_mfma_f32_16x16x32_bf16 v[88:91], v[178:181], v[210:213], v[88:91]
	v_mfma_f32_16x16x32_bf16 v[80:83], v[186:189], v[210:213], v[80:83]
	v_mfma_f32_16x16x32_bf16 v[72:75], v[178:181], v[218:221], v[72:75]
	v_mfma_f32_16x16x32_bf16 v[64:67], v[186:189], v[218:221], v[64:67]
	s_setprio 0
	s_barrier
	s_add_i32 s28, s72, s57
	v_lshl_add_u64 v[138:139], v[138:139], 0, s[22:23]
	s_mov_b32 m0, s28
	ds_read_b128 v[190:193], v157 offset:49152
	ds_read_b128 v[194:197], v157 offset:50176
	ds_read_b128 v[198:201], v157 offset:51200
	ds_read_b128 v[202:205], v157 offset:52224
	ds_read_b128 v[206:209], v157 offset:53248
	ds_read_b128 v[210:213], v157 offset:54272
	ds_read_b128 v[214:217], v157 offset:55296
	ds_read_b128 v[218:221], v157 offset:56320
	global_load_lds_dwordx4 v[138:139], off
	s_add_i32 m0, s28, 0x2000
	s_add_u32 s28, s52, 0x40080
	v_lshl_add_u64 v[138:139], v[230:231], 0, s[22:23]
	s_addc_u32 s29, s53, 0
	s_add_i32 s52, s73, s57
	global_load_lds_dwordx4 v[138:139], off
	v_lshl_add_u64 v[138:139], s[28:29], 0, v[142:143]
	s_mov_b32 m0, s52
	s_nop 0
	global_load_lds_dwordx4 v[138:139], off
	v_lshl_add_u64 v[138:139], s[28:29], 0, v[128:129]
	s_add_i32 m0, s52, 0x2000
	s_nop 0
	global_load_lds_dwordx4 v[138:139], off
	v_lshl_add_u64 v[138:139], v[232:233], 0, s[22:23]
	s_mov_b32 m0, s62
	s_nop 0
	global_load_lds_dwordx4 v[138:139], off
	v_lshl_add_u64 v[138:139], v[234:235], 0, s[22:23]
	s_mov_b32 m0, s63
	s_nop 0
	global_load_lds_dwordx4 v[138:139], off
	s_waitcnt vmcnt(8)
	s_waitcnt lgkmcnt(0)
	s_barrier
	s_setprio 1
	s_waitcnt lgkmcnt(0)
	v_mfma_f32_16x16x32_bf16 v[60:63], v[158:161], v[190:193], v[60:63]
	v_mfma_f32_16x16x32_bf16 v[52:55], v[166:169], v[190:193], v[52:55]
	v_mfma_f32_16x16x32_bf16 v[44:47], v[158:161], v[198:201], v[44:47]
	v_mfma_f32_16x16x32_bf16 v[36:39], v[166:169], v[198:201], v[36:39]
	v_mfma_f32_16x16x32_bf16 v[28:31], v[158:161], v[206:209], v[28:31]
	v_mfma_f32_16x16x32_bf16 v[20:23], v[166:169], v[206:209], v[20:23]
	v_mfma_f32_16x16x32_bf16 v[12:15], v[158:161], v[214:217], v[12:15]
	v_mfma_f32_16x16x32_bf16 v[4:7], v[166:169], v[214:217], v[4:7]
	v_mfma_f32_16x16x32_bf16 v[60:63], v[162:165], v[194:197], v[60:63]
	v_mfma_f32_16x16x32_bf16 v[52:55], v[170:173], v[194:197], v[52:55]
	v_mfma_f32_16x16x32_bf16 v[44:47], v[162:165], v[202:205], v[44:47]
	v_mfma_f32_16x16x32_bf16 v[36:39], v[170:173], v[202:205], v[36:39]
	v_mfma_f32_16x16x32_bf16 v[28:31], v[162:165], v[210:213], v[28:31]
	v_mfma_f32_16x16x32_bf16 v[20:23], v[170:173], v[210:213], v[20:23]
	v_mfma_f32_16x16x32_bf16 v[12:15], v[162:165], v[218:221], v[12:15]
	v_mfma_f32_16x16x32_bf16 v[4:7], v[170:173], v[218:221], v[4:7]
	v_mfma_f32_16x16x32_bf16 v[56:59], v[174:177], v[190:193], v[56:59]
	v_mfma_f32_16x16x32_bf16 v[48:51], v[182:185], v[190:193], v[48:51]
	v_mfma_f32_16x16x32_bf16 v[40:43], v[174:177], v[198:201], v[40:43]
	v_mfma_f32_16x16x32_bf16 v[32:35], v[182:185], v[198:201], v[32:35]
	v_mfma_f32_16x16x32_bf16 v[24:27], v[174:177], v[206:209], v[24:27]
	v_mfma_f32_16x16x32_bf16 v[16:19], v[182:185], v[206:209], v[16:19]
	v_mfma_f32_16x16x32_bf16 v[8:11], v[174:177], v[214:217], v[8:11]
	v_mfma_f32_16x16x32_bf16 v[0:3], v[182:185], v[214:217], v[0:3]
	v_mfma_f32_16x16x32_bf16 v[56:59], v[178:181], v[194:197], v[56:59]
	v_mfma_f32_16x16x32_bf16 v[48:51], v[186:189], v[194:197], v[48:51]
	v_mfma_f32_16x16x32_bf16 v[40:43], v[178:181], v[202:205], v[40:43]
	v_mfma_f32_16x16x32_bf16 v[32:35], v[186:189], v[202:205], v[32:35]
	v_mfma_f32_16x16x32_bf16 v[24:27], v[178:181], v[210:213], v[24:27]
	v_mfma_f32_16x16x32_bf16 v[16:19], v[186:189], v[210:213], v[16:19]
	v_mfma_f32_16x16x32_bf16 v[8:11], v[178:181], v[218:221], v[8:11]
	v_mfma_f32_16x16x32_bf16 v[0:3], v[186:189], v[218:221], v[0:3]
	s_setprio 0
	s_barrier
	s_add_i32 s71, s71, 2
	s_add_u32 s50, s50, 0x100
	s_addc_u32 s51, s51, 0
	s_add_u32 s69, s69, 0x100
	s_addc_u32 s70, s70, 0
	s_cmp_gt_u32 s71, 13
	s_cbranch_scc0 .LBB0_180
	s_and_b64 vcc, exec, s[40:41]
	s_cbranch_vccz .LBB0_183
	s_barrier

.LBB0_276:
	s_add_u32 s40, s60, 0x100
	s_addc_u32 s41, s61, 0
	s_add_i32 s28, 0, 0x10000
	s_cmp_eq_u32 s59, 40
	s_cselect_b32 s65, s55, s41
	s_cselect_b32 s64, s54, s40
	v_add_u32_e32 v112, s28, v230
	s_cselect_b32 s63, s57, s37
	s_cselect_b32 s62, s56, s36
	s_add_i32 s79, 0, 0x14000
	ds_read_b128 v[108:111], v112
	ds_read_b128 v[130:133], v112 offset:1024
	ds_read_b128 v[134:137], v112 offset:2048
	ds_read_b128 v[180:183], v112 offset:3072
	v_add_u32_e32 v112, s79, v230
	ds_read_b128 v[184:187], v112
	ds_read_b128 v[188:191], v112 offset:1024
	ds_read_b128 v[192:195], v112 offset:2048
	ds_read_b128 v[196:199], v112 offset:3072
	v_lshl_add_u64 v[112:113], s[60:61], 0, v[176:177]
	s_add_i32 m0, s68, 0xc000
	ds_read_b128 v[200:203], v231
	ds_read_b128 v[204:207], v231 offset:1024
	ds_read_b128 v[208:211], v231 offset:2048
	ds_read_b128 v[212:215], v231 offset:3072
	ds_read_b128 v[216:219], v231 offset:4096
	ds_read_b128 v[232:235], v231 offset:5120
	ds_read_b128 v[236:239], v231 offset:6144
	ds_read_b128 v[240:243], v231 offset:7168
	global_load_lds_dwordx4 v[112:113], off
	v_lshl_add_u64 v[112:113], s[60:61], 0, v[178:179]
	s_add_i32 m0, s68, 0xe000
	s_nop 0
	global_load_lds_dwordx4 v[112:113], off
	s_waitcnt vmcnt(8)
	s_waitcnt lgkmcnt(0)
	s_barrier
	s_setprio 1
	s_waitcnt lgkmcnt(0)
	v_mfma_f32_16x16x32_bf16 v[138:141], v[108:111], v[200:203], v[138:141]
	v_mfma_f32_16x16x32_bf16 v[92:95], v[134:137], v[200:203], v[92:95]
	v_mfma_f32_16x16x32_bf16 v[126:129], v[108:111], v[208:211], v[126:129]
	v_mfma_f32_16x16x32_bf16 v[88:91], v[134:137], v[208:211], v[88:91]
	v_mfma_f32_16x16x32_bf16 v[122:125], v[108:111], v[216:219], v[122:125]
	v_mfma_f32_16x16x32_bf16 v[84:87], v[134:137], v[216:219], v[84:87]
	v_mfma_f32_16x16x32_bf16 v[118:121], v[108:111], v[236:239], v[118:121]
	v_mfma_f32_16x16x32_bf16 v[80:83], v[134:137], v[236:239], v[80:83]
	v_mfma_f32_16x16x32_bf16 v[138:141], v[130:133], v[204:207], v[138:141]
	v_mfma_f32_16x16x32_bf16 v[92:95], v[180:183], v[204:207], v[92:95]
	v_mfma_f32_16x16x32_bf16 v[126:129], v[130:133], v[212:215], v[126:129]
	v_mfma_f32_16x16x32_bf16 v[88:91], v[180:183], v[212:215], v[88:91]
	v_mfma_f32_16x16x32_bf16 v[122:125], v[130:133], v[232:235], v[122:125]
	v_mfma_f32_16x16x32_bf16 v[84:87], v[180:183], v[232:235], v[84:87]
	v_mfma_f32_16x16x32_bf16 v[118:121], v[130:133], v[240:243], v[118:121]
	v_mfma_f32_16x16x32_bf16 v[80:83], v[180:183], v[240:243], v[80:83]
	v_mfma_f32_16x16x32_bf16 v[60:63], v[184:187], v[200:203], v[60:63]
	v_mfma_f32_16x16x32_bf16 v[28:31], v[192:195], v[200:203], v[28:31]
	v_mfma_f32_16x16x32_bf16 v[56:59], v[184:187], v[208:211], v[56:59]
	v_mfma_f32_16x16x32_bf16 v[24:27], v[192:195], v[208:211], v[24:27]
	v_mfma_f32_16x16x32_bf16 v[52:55], v[184:187], v[216:219], v[52:55]
	v_mfma_f32_16x16x32_bf16 v[20:23], v[192:195], v[216:219], v[20:23]
	v_mfma_f32_16x16x32_bf16 v[48:51], v[184:187], v[236:239], v[48:51]
	v_mfma_f32_16x16x32_bf16 v[16:19], v[192:195], v[236:239], v[16:19]
	v_mfma_f32_16x16x32_bf16 v[60:63], v[188:191], v[204:207], v[60:63]
	v_mfma_f32_16x16x32_bf16 v[28:31], v[196:199], v[204:207], v[28:31]
	v_mfma_f32_16x16x32_bf16 v[56:59], v[188:191], v[212:215], v[56:59]
	v_mfma_f32_16x16x32_bf16 v[24:27], v[196:199], v[212:215], v[24:27]
	v_mfma_f32_16x16x32_bf16 v[52:55], v[188:191], v[232:235], v[52:55]
	v_mfma_f32_16x16x32_bf16 v[20:23], v[196:199], v[232:235], v[20:23]
	v_mfma_f32_16x16x32_bf16 v[48:51], v[188:191], v[240:243], v[48:51]
	v_mfma_f32_16x16x32_bf16 v[16:19], v[196:199], v[240:243], v[16:19]
	s_setprio 0
	s_barrier
	s_add_i32 s28, s28, s67
	v_lshl_add_u64 v[220:221], s[62:63], 0, v[142:143]
	s_mov_b32 m0, s28
	ds_read_b128 v[200:203], v231 offset:16384
	ds_read_b128 v[204:207], v231 offset:17408
	ds_read_b128 v[208:211], v231 offset:18432
	ds_read_b128 v[212:215], v231 offset:19456
	ds_read_b128 v[216:219], v231 offset:20480
	ds_read_b128 v[232:235], v231 offset:21504
	ds_read_b128 v[236:239], v231 offset:22528
	ds_read_b128 v[240:243], v231 offset:23552
	global_load_lds_dwordx4 v[220:221], off
	s_add_i32 m0, s28, 0x2000
	s_add_u32 s28, s62, 0xb0000
	v_lshl_add_u64 v[244:245], s[62:63], 0, v[156:157]
	s_addc_u32 s29, s63, 0
	s_add_i32 s60, s79, s67
	global_load_lds_dwordx4 v[244:245], off
	v_lshl_add_u64 v[112:113], s[28:29], 0, v[142:143]
	s_mov_b32 m0, s60
	v_lshl_add_u64 v[246:247], s[64:65], 0, v[142:143]
	global_load_lds_dwordx4 v[112:113], off
	v_lshl_add_u64 v[112:113], s[28:29], 0, v[156:157]
	s_add_i32 m0, s60, 0x2000
	v_lshl_add_u64 v[248:249], s[64:65], 0, v[156:157]
	global_load_lds_dwordx4 v[112:113], off
	s_mov_b32 m0, s68
	s_nop 0
	global_load_lds_dwordx4 v[246:247], off
	s_mov_b32 m0, s69
	s_nop 0
	global_load_lds_dwordx4 v[248:249], off
	s_waitcnt vmcnt(8)
	s_waitcnt lgkmcnt(0)
	s_barrier
	s_setprio 1
	s_waitcnt lgkmcnt(0)
	v_mfma_f32_16x16x32_bf16 v[112:115], v[108:111], v[200:203], v[114:117]
	v_mfma_f32_16x16x32_bf16 v[76:79], v[134:137], v[200:203], v[76:79]
	v_mfma_f32_16x16x32_bf16 v[104:107], v[108:111], v[208:211], v[104:107]
	v_mfma_f32_16x16x32_bf16 v[72:75], v[134:137], v[208:211], v[72:75]
	v_mfma_f32_16x16x32_bf16 v[100:103], v[108:111], v[216:219], v[100:103]
	v_mfma_f32_16x16x32_bf16 v[68:71], v[134:137], v[216:219], v[68:71]
	v_mfma_f32_16x16x32_bf16 v[96:99], v[108:111], v[236:239], v[96:99]
	v_mfma_f32_16x16x32_bf16 v[64:67], v[134:137], v[236:239], v[64:67]
	v_mfma_f32_16x16x32_bf16 v[112:115], v[130:133], v[204:207], v[112:115]
	v_mfma_f32_16x16x32_bf16 v[76:79], v[180:183], v[204:207], v[76:79]
	v_mfma_f32_16x16x32_bf16 v[104:107], v[130:133], v[212:215], v[104:107]
	v_mfma_f32_16x16x32_bf16 v[72:75], v[180:183], v[212:215], v[72:75]
	v_mfma_f32_16x16x32_bf16 v[100:103], v[130:133], v[232:235], v[100:103]
	v_mfma_f32_16x16x32_bf16 v[68:71], v[180:183], v[232:235], v[68:71]
	v_mfma_f32_16x16x32_bf16 v[96:99], v[130:133], v[240:243], v[96:99]
	v_mfma_f32_16x16x32_bf16 v[64:67], v[180:183], v[240:243], v[64:67]
	v_mfma_f32_16x16x32_bf16 v[44:47], v[184:187], v[200:203], v[44:47]
	v_mfma_f32_16x16x32_bf16 v[12:15], v[192:195], v[200:203], v[12:15]
	v_mfma_f32_16x16x32_bf16 v[40:43], v[184:187], v[208:211], v[40:43]
	v_mfma_f32_16x16x32_bf16 v[8:11], v[192:195], v[208:211], v[8:11]
	v_mfma_f32_16x16x32_bf16 v[36:39], v[184:187], v[216:219], v[36:39]
	v_mfma_f32_16x16x32_bf16 v[4:7], v[192:195], v[216:219], v[4:7]
	v_mfma_f32_16x16x32_bf16 v[32:35], v[184:187], v[236:239], v[32:35]
	v_mfma_f32_16x16x32_bf16 v[0:3], v[192:195], v[236:239], v[0:3]
	v_mfma_f32_16x16x32_bf16 v[44:47], v[188:191], v[204:207], v[44:47]
	v_mfma_f32_16x16x32_bf16 v[12:15], v[196:199], v[204:207], v[12:15]
	v_mfma_f32_16x16x32_bf16 v[40:43], v[188:191], v[212:215], v[40:43]
	v_mfma_f32_16x16x32_bf16 v[8:11], v[196:199], v[212:215], v[8:11]
	v_mfma_f32_16x16x32_bf16 v[36:39], v[188:191], v[232:235], v[36:39]
	v_mfma_f32_16x16x32_bf16 v[4:7], v[196:199], v[232:235], v[4:7]
	v_mfma_f32_16x16x32_bf16 v[32:35], v[188:191], v[240:243], v[32:35]
	v_mfma_f32_16x16x32_bf16 v[0:3], v[196:199], v[240:243], v[0:3]
	s_setprio 0
	s_barrier
	s_add_i32 s60, 0, 0x18000
	v_add_u32_e32 v116, s60, v230
	s_add_i32 s61, 0, 0x1c000
	ds_read_b128 v[108:111], v116
	ds_read_b128 v[130:133], v116 offset:1024
	ds_read_b128 v[134:137], v116 offset:2048
	ds_read_b128 v[180:183], v116 offset:3072
	v_add_u32_e32 v116, s61, v230
	ds_read_b128 v[184:187], v116
	ds_read_b128 v[188:191], v116 offset:1024
	ds_read_b128 v[192:195], v116 offset:2048
	ds_read_b128 v[196:199], v116 offset:3072
	s_add_u32 s28, s64, 0xb0000
	s_addc_u32 s29, s65, 0
	s_mov_b32 m0, s70
	v_lshl_add_u64 v[116:117], s[28:29], 0, v[142:143]
	ds_read_b128 v[200:203], v231 offset:32768
	ds_read_b128 v[204:207], v231 offset:33792
	ds_read_b128 v[208:211], v231 offset:34816
	ds_read_b128 v[212:215], v231 offset:35840
	ds_read_b128 v[216:219], v231 offset:36864
	ds_read_b128 v[232:235], v231 offset:37888
	ds_read_b128 v[236:239], v231 offset:38912
	ds_read_b128 v[240:243], v231 offset:39936
	global_load_lds_dwordx4 v[116:117], off
	v_lshl_add_u64 v[116:117], s[28:29], 0, v[156:157]
	s_mov_b32 m0, s71
	s_nop 0
	global_load_lds_dwordx4 v[116:117], off
	s_waitcnt vmcnt(8)
	s_waitcnt lgkmcnt(0)
	s_barrier
	s_setprio 1
	s_waitcnt lgkmcnt(0)
	v_mfma_f32_16x16x32_bf16 v[138:141], v[108:111], v[200:203], v[138:141]
	v_mfma_f32_16x16x32_bf16 v[92:95], v[134:137], v[200:203], v[92:95]
	v_mfma_f32_16x16x32_bf16 v[126:129], v[108:111], v[208:211], v[126:129]
	v_mfma_f32_16x16x32_bf16 v[88:91], v[134:137], v[208:211], v[88:91]
	v_mfma_f32_16x16x32_bf16 v[122:125], v[108:111], v[216:219], v[122:125]
	v_mfma_f32_16x16x32_bf16 v[84:87], v[134:137], v[216:219], v[84:87]
	v_mfma_f32_16x16x32_bf16 v[116:119], v[108:111], v[236:239], v[118:121]
	v_mfma_f32_16x16x32_bf16 v[80:83], v[134:137], v[236:239], v[80:83]
	v_mfma_f32_16x16x32_bf16 v[138:141], v[130:133], v[204:207], v[138:141]
	v_mfma_f32_16x16x32_bf16 v[92:95], v[180:183], v[204:207], v[92:95]
	v_mfma_f32_16x16x32_bf16 v[126:129], v[130:133], v[212:215], v[126:129]
	v_mfma_f32_16x16x32_bf16 v[88:91], v[180:183], v[212:215], v[88:91]
	v_mfma_f32_16x16x32_bf16 v[122:125], v[130:133], v[232:235], v[122:125]
	v_mfma_f32_16x16x32_bf16 v[84:87], v[180:183], v[232:235], v[84:87]
	v_mfma_f32_16x16x32_bf16 v[118:121], v[130:133], v[240:243], v[116:119]
	v_mfma_f32_16x16x32_bf16 v[80:83], v[180:183], v[240:243], v[80:83]
	v_mfma_f32_16x16x32_bf16 v[60:63], v[184:187], v[200:203], v[60:63]
	v_mfma_f32_16x16x32_bf16 v[28:31], v[192:195], v[200:203], v[28:31]
	v_mfma_f32_16x16x32_bf16 v[56:59], v[184:187], v[208:211], v[56:59]
	v_mfma_f32_16x16x32_bf16 v[24:27], v[192:195], v[208:211], v[24:27]
	v_mfma_f32_16x16x32_bf16 v[52:55], v[184:187], v[216:219], v[52:55]
	v_mfma_f32_16x16x32_bf16 v[20:23], v[192:195], v[216:219], v[20:23]
	v_mfma_f32_16x16x32_bf16 v[48:51], v[184:187], v[236:239], v[48:51]
	v_mfma_f32_16x16x32_bf16 v[16:19], v[192:195], v[236:239], v[16:19]
	v_mfma_f32_16x16x32_bf16 v[60:63], v[188:191], v[204:207], v[60:63]
	v_mfma_f32_16x16x32_bf16 v[28:31], v[196:199], v[204:207], v[28:31]
	v_mfma_f32_16x16x32_bf16 v[56:59], v[188:191], v[212:215], v[56:59]
	v_mfma_f32_16x16x32_bf16 v[24:27], v[196:199], v[212:215], v[24:27]
	v_mfma_f32_16x16x32_bf16 v[52:55], v[188:191], v[232:235], v[52:55]
	v_mfma_f32_16x16x32_bf16 v[20:23], v[196:199], v[232:235], v[20:23]
	v_mfma_f32_16x16x32_bf16 v[48:51], v[188:191], v[240:243], v[48:51]
	v_mfma_f32_16x16x32_bf16 v[16:19], v[196:199], v[240:243], v[16:19]
	s_setprio 0
	s_barrier
	s_add_i32 s28, s60, s67
	v_lshl_add_u64 v[116:117], v[220:221], 0, s[22:23]
	s_mov_b32 m0, s28
	ds_read_b128 v[200:203], v231 offset:49152
	ds_read_b128 v[204:207], v231 offset:50176
	ds_read_b128 v[208:211], v231 offset:51200
	ds_read_b128 v[212:215], v231 offset:52224
	ds_read_b128 v[216:219], v231 offset:53248
	ds_read_b128 v[232:235], v231 offset:54272
	ds_read_b128 v[236:239], v231 offset:55296
	ds_read_b128 v[240:243], v231 offset:56320
	global_load_lds_dwordx4 v[116:117], off
	s_add_i32 m0, s28, 0x2000
	s_add_u32 s28, s62, 0xb0080
	v_lshl_add_u64 v[116:117], v[244:245], 0, s[22:23]
	s_addc_u32 s29, s63, 0
	s_add_i32 s60, s61, s67
	global_load_lds_dwordx4 v[116:117], off
	v_lshl_add_u64 v[116:117], s[28:29], 0, v[142:143]
	s_mov_b32 m0, s60
	s_nop 0
	global_load_lds_dwordx4 v[116:117], off
	v_lshl_add_u64 v[116:117], s[28:29], 0, v[156:157]
	s_add_i32 m0, s60, 0x2000
	s_nop 0
	global_load_lds_dwordx4 v[116:117], off
	v_lshl_add_u64 v[116:117], v[246:247], 0, s[22:23]
	s_mov_b32 m0, s74
	s_nop 0
	global_load_lds_dwordx4 v[116:117], off
	v_lshl_add_u64 v[116:117], v[248:249], 0, s[22:23]
	s_mov_b32 m0, s75
	s_nop 0
	global_load_lds_dwordx4 v[116:117], off
	s_waitcnt vmcnt(8)
	s_waitcnt lgkmcnt(0)
	s_barrier
	s_setprio 1
	s_waitcnt lgkmcnt(0)
	v_mfma_f32_16x16x32_bf16 v[112:115], v[108:111], v[200:203], v[112:115]
	v_mfma_f32_16x16x32_bf16 v[76:79], v[134:137], v[200:203], v[76:79]
	v_mfma_f32_16x16x32_bf16 v[104:107], v[108:111], v[208:211], v[104:107]
	v_mfma_f32_16x16x32_bf16 v[72:75], v[134:137], v[208:211], v[72:75]
	v_mfma_f32_16x16x32_bf16 v[100:103], v[108:111], v[216:219], v[100:103]
	v_mfma_f32_16x16x32_bf16 v[68:71], v[134:137], v[216:219], v[68:71]
	v_mfma_f32_16x16x32_bf16 v[96:99], v[108:111], v[236:239], v[96:99]
	v_mfma_f32_16x16x32_bf16 v[64:67], v[134:137], v[236:239], v[64:67]
	v_mfma_f32_16x16x32_bf16 v[114:117], v[130:133], v[204:207], v[112:115]
	v_mfma_f32_16x16x32_bf16 v[76:79], v[180:183], v[204:207], v[76:79]
	v_mfma_f32_16x16x32_bf16 v[104:107], v[130:133], v[212:215], v[104:107]
	v_mfma_f32_16x16x32_bf16 v[72:75], v[180:183], v[212:215], v[72:75]
	v_mfma_f32_16x16x32_bf16 v[100:103], v[130:133], v[232:235], v[100:103]
	v_mfma_f32_16x16x32_bf16 v[68:71], v[180:183], v[232:235], v[68:71]
	v_mfma_f32_16x16x32_bf16 v[96:99], v[130:133], v[240:243], v[96:99]
	v_mfma_f32_16x16x32_bf16 v[64:67], v[180:183], v[240:243], v[64:67]
	v_mfma_f32_16x16x32_bf16 v[44:47], v[184:187], v[200:203], v[44:47]
	v_mfma_f32_16x16x32_bf16 v[12:15], v[192:195], v[200:203], v[12:15]
	v_mfma_f32_16x16x32_bf16 v[40:43], v[184:187], v[208:211], v[40:43]
	v_mfma_f32_16x16x32_bf16 v[8:11], v[192:195], v[208:211], v[8:11]
	v_mfma_f32_16x16x32_bf16 v[36:39], v[184:187], v[216:219], v[36:39]
	v_mfma_f32_16x16x32_bf16 v[4:7], v[192:195], v[216:219], v[4:7]
	v_mfma_f32_16x16x32_bf16 v[32:35], v[184:187], v[236:239], v[32:35]
	v_mfma_f32_16x16x32_bf16 v[0:3], v[192:195], v[236:239], v[0:3]
	v_mfma_f32_16x16x32_bf16 v[44:47], v[188:191], v[204:207], v[44:47]
	v_mfma_f32_16x16x32_bf16 v[12:15], v[196:199], v[204:207], v[12:15]
	v_mfma_f32_16x16x32_bf16 v[40:43], v[188:191], v[212:215], v[40:43]
	v_mfma_f32_16x16x32_bf16 v[8:11], v[196:199], v[212:215], v[8:11]
	v_mfma_f32_16x16x32_bf16 v[36:39], v[188:191], v[232:235], v[36:39]
	v_mfma_f32_16x16x32_bf16 v[4:7], v[196:199], v[232:235], v[4:7]
	v_mfma_f32_16x16x32_bf16 v[32:35], v[188:191], v[240:243], v[32:35]
	v_mfma_f32_16x16x32_bf16 v[0:3], v[196:199], v[240:243], v[0:3]
	s_setprio 0
	s_barrier
	s_add_i32 s59, s59, 2
	s_add_u32 s36, s36, 0x100
	s_addc_u32 s37, s37, 0
	s_cmp_gt_u32 s59, 41
	s_mov_b64 s[60:61], s[40:41]
	s_cbranch_scc0 .LBB0_276
	s_and_b64 vcc, exec, s[52:53]
	s_cbranch_vccz .LBB0_279
	s_barrier
.LBB0_279:
	v_readlane_b32 s28, v250, 53
	s_nop 3
	s_cmp_eq_u32 s28, 3
	s_cbranch_scc1 .Lepi_A_final
	v_lshl_add_u32 v108, s58, 8, v158
	v_cndmask_b32_e64 v109, 0, 1, s[80:81]
	v_mov_b32_e32 v202, 1.0
	v_mov_b32_e32 v200, 0
	v_cmp_ne_u32_e64 s[40:41], 1, v109
	s_andn2_b64 vcc, exec, s[80:81]
	v_ashrrev_i32_e32 v109, 31, v108
	v_mov_b32_e32 v208, 0
	v_mov_b32_e32 v210, 1.0
	s_cbranch_vccnz .LBB0_281
	v_lshl_add_u64 v[110:111], v[108:109], 3, s[92:93]
	global_load_dwordx2 v[208:209], v[110:111], off
	s_waitcnt vmcnt(0)
	v_mov_b32_e32 v210, v209

.Lepi_A_join:
	s_cbranch_vccnz .LBB0_264
	s_andn2_b64 vcc, exec, s[50:51]
	s_cbranch_vccnz .LBB0_263
	s_barrier
	s_branch .LBB0_263
.Lepi_A_final:
	s_mov_b64 s[40:41], 0
	v_lshl_add_u32 v248, s58, 8, v158
	v_lshl_or_b32 v249, s2, 8, v159
	v_lshlrev_b32_e32 v248, 3, v248
	v_lshlrev_b32_e32 v249, 2, v249
	s_mov_b32 s4, s58
	s_mov_b32 s5, s2
	s_ashr_i32 s59, s58, 31
	s_lshl_b64 s[28:29], s[58:59], 20
	s_add_u32 s60, s73, s28
	s_addc_u32 s61, s72, s29
	v_readlane_b32 s16, v252, 12
	v_readlane_b32 s17, v252, 13
	s_nop 3
	s_add_u32 s58, s16, s28
	s_addc_u32 s59, s17, s29
	v_mov_b32_e32 v214, 0
	v_mov_b32_e32 v215, 0
	v_mov_b32_e32 v216, 0
	v_mov_b32_e32 v217, 0
	v_mov_b32_e32 v218, 0
	v_mov_b32_e32 v219, 0
	v_mov_b32_e32 v220, 0
	v_mov_b32_e32 v221, 0
	v_mov_b32_e32 v232, 0
	v_mov_b32_e32 v233, 0
	v_mov_b32_e32 v234, 0
	v_mov_b32_e32 v235, 0
	v_mov_b32_e32 v236, 0
	v_mov_b32_e32 v237, 0
	v_mov_b32_e32 v238, 0
	v_mov_b32_e32 v239, 0
	global_load_dwordx2 v[112:113], v248, s[92:93]
	global_load_dwordx2 v[200:201], v248, s[92:93] offset:128
	global_load_dwordx2 v[202:203], v248, s[92:93] offset:256
	global_load_dwordx2 v[204:205], v248, s[92:93] offset:384
	global_load_dwordx2 v[206:207], v248, s[92:93] offset:1024
	global_load_dwordx2 v[208:209], v248, s[92:93] offset:1152
	global_load_dwordx2 v[210:211], v248, s[92:93] offset:1280
	global_load_dwordx2 v[212:213], v248, s[92:93] offset:1408
	global_load_dwordx4 v[184:187], v249, s[48:49]
	global_load_dwordx4 v[188:191], v249, s[84:85]
	v_lshl_add_u32 v240, v160, 2, v249
	v_lshl_add_u32 v241, v164, 2, v249
	v_lshl_add_u32 v242, v166, 2, v249
	v_lshl_add_u32 v243, v168, 2, v249
	v_lshl_add_u32 v244, v162, 2, v249
	v_lshl_add_u32 v245, v170, 2, v249
	v_lshl_add_u32 v246, v172, 2, v249
	v_lshl_add_u32 v247, v174, 2, v249
	global_load_dwordx4 v[108:111], v240, s[60:61]
	global_load_dwordx4 v[130:133], v241, s[60:61]
	global_load_dwordx4 v[134:137], v242, s[60:61]
	global_load_dwordx4 v[180:183], v243, s[60:61]
	global_load_dwordx4 v[192:195], v249, s[48:49] offset:512
	global_load_dwordx4 v[196:199], v249, s[84:85] offset:512
	s_waitcnt vmcnt(5)
	v_pk_add_f32 v[108:109], v[108:109], v[112:113] op_sel_hi:[1,0] neg_lo:[0,1] neg_hi:[0,1]
	v_pk_add_f32 v[110:111], v[110:111], v[112:113] op_sel_hi:[1,0] neg_lo:[0,1] neg_hi:[0,1]
	v_pk_mul_f32 v[108:109], v[108:109], v[112:113] op_sel:[0,1] op_sel_hi:[1,1]
	v_pk_mul_f32 v[110:111], v[110:111], v[112:113] op_sel:[0,1] op_sel_hi:[1,1]
	v_pk_fma_f32 v[108:109], v[184:185], v[108:109], v[188:189]
	v_pk_fma_f32 v[110:111], v[186:187], v[110:111], v[190:191]
	v_pk_mul_f32 v[108:109], v[108:109], s[82:83] op_sel_hi:[1,0]
	v_pk_mul_f32 v[110:111], v[110:111], s[82:83] op_sel_hi:[1,0]
	v_pk_fma_f32 v[138:139], v[138:139], 0.5, v[108:109] op_sel_hi:[1,0,1]
	v_pk_fma_f32 v[140:141], v[140:141], 0.5, v[110:111] op_sel_hi:[1,0,1]
	global_load_dwordx4 v[108:111], v244, s[60:61]
	v_add_f32_e32 v214, v214, v138
	v_add_f32_e32 v214, v214, v139
	v_add_f32_e32 v214, v214, v140
	v_add_f32_e32 v214, v214, v141
	v_fmac_f32_e32 v215, v138, v138
	v_fmac_f32_e32 v215, v139, v139
	v_fmac_f32_e32 v215, v140, v140
	v_fmac_f32_e32 v215, v141, v141
	s_waitcnt vmcnt(5)
	v_pk_add_f32 v[130:131], v[130:131], v[200:201] op_sel_hi:[1,0] neg_lo:[0,1] neg_hi:[0,1]
	v_pk_add_f32 v[132:133], v[132:133], v[200:201] op_sel_hi:[1,0] neg_lo:[0,1] neg_hi:[0,1]
	v_pk_mul_f32 v[130:131], v[130:131], v[200:201] op_sel:[0,1] op_sel_hi:[1,1]
	v_pk_mul_f32 v[132:133], v[132:133], v[200:201] op_sel:[0,1] op_sel_hi:[1,1]
	v_pk_fma_f32 v[130:131], v[184:185], v[130:131], v[188:189]
	v_pk_fma_f32 v[132:133], v[186:187], v[132:133], v[190:191]
	v_pk_mul_f32 v[130:131], v[130:131], s[82:83] op_sel_hi:[1,0]
	v_pk_mul_f32 v[132:133], v[132:133], s[82:83] op_sel_hi:[1,0]
	v_pk_fma_f32 v[126:127], v[126:127], 0.5, v[130:131] op_sel_hi:[1,0,1]
	v_pk_fma_f32 v[128:129], v[128:129], 0.5, v[132:133] op_sel_hi:[1,0,1]
	global_load_dwordx4 v[130:133], v245, s[60:61]
	v_add_f32_e32 v216, v216, v126
	v_add_f32_e32 v216, v216, v127
	v_add_f32_e32 v216, v216, v128
	v_add_f32_e32 v216, v216, v129
	v_fmac_f32_e32 v217, v126, v126
	v_fmac_f32_e32 v217, v127, v127
	v_fmac_f32_e32 v217, v128, v128
	v_fmac_f32_e32 v217, v129, v129
	s_waitcnt vmcnt(5)
	v_pk_add_f32 v[134:135], v[134:135], v[202:203] op_sel_hi:[1,0] neg_lo:[0,1] neg_hi:[0,1]
	v_pk_add_f32 v[136:137], v[136:137], v[202:203] op_sel_hi:[1,0] neg_lo:[0,1] neg_hi:[0,1]
	v_pk_mul_f32 v[134:135], v[134:135], v[202:203] op_sel:[0,1] op_sel_hi:[1,1]
	v_pk_mul_f32 v[136:137], v[136:137], v[202:203] op_sel:[0,1] op_sel_hi:[1,1]
	v_pk_fma_f32 v[134:135], v[184:185], v[134:135], v[188:189]
	v_pk_fma_f32 v[136:137], v[186:187], v[136:137], v[190:191]
	v_pk_mul_f32 v[134:135], v[134:135], s[82:83] op_sel_hi:[1,0]
	v_pk_mul_f32 v[136:137], v[136:137], s[82:83] op_sel_hi:[1,0]
	v_pk_fma_f32 v[122:123], v[122:123], 0.5, v[134:135] op_sel_hi:[1,0,1]
	v_pk_fma_f32 v[124:125], v[124:125], 0.5, v[136:137] op_sel_hi:[1,0,1]
	global_load_dwordx4 v[134:137], v246, s[60:61]
	v_add_f32_e32 v218, v218, v122
	v_add_f32_e32 v218, v218, v123
	v_add_f32_e32 v218, v218, v124
	v_add_f32_e32 v218, v218, v125
	v_fmac_f32_e32 v219, v122, v122
	v_fmac_f32_e32 v219, v123, v123
	v_fmac_f32_e32 v219, v124, v124
	v_fmac_f32_e32 v219, v125, v125
	s_waitcnt vmcnt(5)
	v_pk_add_f32 v[180:181], v[180:181], v[204:205] op_sel_hi:[1,0] neg_lo:[0,1] neg_hi:[0,1]
	v_pk_add_f32 v[182:183], v[182:183], v[204:205] op_sel_hi:[1,0] neg_lo:[0,1] neg_hi:[0,1]
	v_pk_mul_f32 v[180:181], v[180:181], v[204:205] op_sel:[0,1] op_sel_hi:[1,1]
	v_pk_mul_f32 v[182:183], v[182:183], v[204:205] op_sel:[0,1] op_sel_hi:[1,1]
	v_pk_fma_f32 v[180:181], v[184:185], v[180:181], v[188:189]
	v_pk_fma_f32 v[182:183], v[186:187], v[182:183], v[190:191]
	v_pk_mul_f32 v[180:181], v[180:181], s[82:83] op_sel_hi:[1,0]
	v_pk_mul_f32 v[182:183], v[182:183], s[82:83] op_sel_hi:[1,0]
	v_pk_fma_f32 v[118:119], v[118:119], 0.5, v[180:181] op_sel_hi:[1,0,1]
	v_pk_fma_f32 v[120:121], v[120:121], 0.5, v[182:183] op_sel_hi:[1,0,1]
	global_load_dwordx4 v[180:183], v247, s[60:61]
	v_add_f32_e32 v220, v220, v118
	v_add_f32_e32 v220, v220, v119
	v_add_f32_e32 v220, v220, v120
	v_add_f32_e32 v220, v220, v121
	v_fmac_f32_e32 v221, v118, v118
	v_fmac_f32_e32 v221, v119, v119
	v_fmac_f32_e32 v221, v120, v120
	v_fmac_f32_e32 v221, v121, v121
	s_waitcnt vmcnt(3)
	v_pk_add_f32 v[108:109], v[108:109], v[206:207] op_sel_hi:[1,0] neg_lo:[0,1] neg_hi:[0,1]
	v_pk_add_f32 v[110:111], v[110:111], v[206:207] op_sel_hi:[1,0] neg_lo:[0,1] neg_hi:[0,1]
	v_pk_mul_f32 v[108:109], v[108:109], v[206:207] op_sel:[0,1] op_sel_hi:[1,1]
	v_pk_mul_f32 v[110:111], v[110:111], v[206:207] op_sel:[0,1] op_sel_hi:[1,1]
	v_pk_fma_f32 v[108:109], v[184:185], v[108:109], v[188:189]
	v_pk_fma_f32 v[110:111], v[186:187], v[110:111], v[190:191]
	v_pk_mul_f32 v[108:109], v[108:109], s[82:83] op_sel_hi:[1,0]
	v_pk_mul_f32 v[110:111], v[110:111], s[82:83] op_sel_hi:[1,0]
	v_pk_fma_f32 v[114:115], v[114:115], 0.5, v[108:109] op_sel_hi:[1,0,1]
	v_pk_fma_f32 v[116:117], v[116:117], 0.5, v[110:111] op_sel_hi:[1,0,1]
	global_load_dwordx4 v[108:111], v240, s[60:61] offset:512
	v_add_f32_e32 v232, v232, v114
	v_add_f32_e32 v232, v232, v115
	v_add_f32_e32 v232, v232, v116
	v_add_f32_e32 v232, v232, v117
	v_fmac_f32_e32 v233, v114, v114
	v_fmac_f32_e32 v233, v115, v115
	v_fmac_f32_e32 v233, v116, v116
	v_fmac_f32_e32 v233, v117, v117
	s_waitcnt vmcnt(3)
	v_pk_add_f32 v[130:131], v[130:131], v[208:209] op_sel_hi:[1,0] neg_lo:[0,1] neg_hi:[0,1]
	v_pk_add_f32 v[132:133], v[132:133], v[208:209] op_sel_hi:[1,0] neg_lo:[0,1] neg_hi:[0,1]
	v_pk_mul_f32 v[130:131], v[130:131], v[208:209] op_sel:[0,1] op_sel_hi:[1,1]
	v_pk_mul_f32 v[132:133], v[132:133], v[208:209] op_sel:[0,1] op_sel_hi:[1,1]
	v_pk_fma_f32 v[130:131], v[184:185], v[130:131], v[188:189]
	v_pk_fma_f32 v[132:133], v[186:187], v[132:133], v[190:191]
	v_pk_mul_f32 v[130:131], v[130:131], s[82:83] op_sel_hi:[1,0]
	v_pk_mul_f32 v[132:133], v[132:133], s[82:83] op_sel_hi:[1,0]
	v_pk_fma_f32 v[104:105], v[104:105], 0.5, v[130:131] op_sel_hi:[1,0,1]
	v_pk_fma_f32 v[106:107], v[106:107], 0.5, v[132:133] op_sel_hi:[1,0,1]
	global_load_dwordx4 v[130:133], v241, s[60:61] offset:512
	v_add_f32_e32 v234, v234, v104
	v_add_f32_e32 v234, v234, v105
	v_add_f32_e32 v234, v234, v106
	v_add_f32_e32 v234, v234, v107
	v_fmac_f32_e32 v235, v104, v104
	v_fmac_f32_e32 v235, v105, v105
	v_fmac_f32_e32 v235, v106, v106
	v_fmac_f32_e32 v235, v107, v107
	s_waitcnt vmcnt(3)
	v_pk_add_f32 v[134:135], v[134:135], v[210:211] op_sel_hi:[1,0] neg_lo:[0,1] neg_hi:[0,1]
	v_pk_add_f32 v[136:137], v[136:137], v[210:211] op_sel_hi:[1,0] neg_lo:[0,1] neg_hi:[0,1]
	v_pk_mul_f32 v[134:135], v[134:135], v[210:211] op_sel:[0,1] op_sel_hi:[1,1]
	v_pk_mul_f32 v[136:137], v[136:137], v[210:211] op_sel:[0,1] op_sel_hi:[1,1]
	v_pk_fma_f32 v[134:135], v[184:185], v[134:135], v[188:189]
	v_pk_fma_f32 v[136:137], v[186:187], v[136:137], v[190:191]
	v_pk_mul_f32 v[134:135], v[134:135], s[82:83] op_sel_hi:[1,0]
	v_pk_mul_f32 v[136:137], v[136:137], s[82:83] op_sel_hi:[1,0]
	v_pk_fma_f32 v[100:101], v[100:101], 0.5, v[134:135] op_sel_hi:[1,0,1]
	v_pk_fma_f32 v[102:103], v[102:103], 0.5, v[136:137] op_sel_hi:[1,0,1]
	global_load_dwordx4 v[134:137], v242, s[60:61] offset:512
	v_add_f32_e32 v236, v236, v100
	v_add_f32_e32 v236, v236, v101
	v_add_f32_e32 v236, v236, v102
	v_add_f32_e32 v236, v236, v103
	v_fmac_f32_e32 v237, v100, v100
	v_fmac_f32_e32 v237, v101, v101
	v_fmac_f32_e32 v237, v102, v102
	v_fmac_f32_e32 v237, v103, v103
	s_waitcnt vmcnt(3)
	v_pk_add_f32 v[180:181], v[180:181], v[212:213] op_sel_hi:[1,0] neg_lo:[0,1] neg_hi:[0,1]
	v_pk_add_f32 v[182:183], v[182:183], v[212:213] op_sel_hi:[1,0] neg_lo:[0,1] neg_hi:[0,1]
	v_pk_mul_f32 v[180:181], v[180:181], v[212:213] op_sel:[0,1] op_sel_hi:[1,1]
	v_pk_mul_f32 v[182:183], v[182:183], v[212:213] op_sel:[0,1] op_sel_hi:[1,1]
	v_pk_fma_f32 v[180:181], v[184:185], v[180:181], v[188:189]
	v_pk_fma_f32 v[182:183], v[186:187], v[182:183], v[190:191]
	v_pk_mul_f32 v[180:181], v[180:181], s[82:83] op_sel_hi:[1,0]
	v_pk_mul_f32 v[182:183], v[182:183], s[82:83] op_sel_hi:[1,0]
	v_pk_fma_f32 v[96:97], v[96:97], 0.5, v[180:181] op_sel_hi:[1,0,1]
	v_pk_fma_f32 v[98:99], v[98:99], 0.5, v[182:183] op_sel_hi:[1,0,1]
	global_load_dwordx4 v[180:183], v243, s[60:61] offset:512
	v_add_f32_e32 v238, v238, v96
	v_add_f32_e32 v238, v238, v97
	v_add_f32_e32 v238, v238, v98
	v_add_f32_e32 v238, v238, v99
	v_fmac_f32_e32 v239, v96, v96
	v_fmac_f32_e32 v239, v97, v97
	v_fmac_f32_e32 v239, v98, v98
	v_fmac_f32_e32 v239, v99, v99
	global_load_dwordx4 v[184:187], v249, s[48:49] offset:64
	global_load_dwordx4 v[188:191], v249, s[84:85] offset:64
	s_waitcnt vmcnt(5)
	v_pk_add_f32 v[108:109], v[108:109], v[112:113] op_sel_hi:[1,0] neg_lo:[0,1] neg_hi:[0,1]
	v_pk_add_f32 v[110:111], v[110:111], v[112:113] op_sel_hi:[1,0] neg_lo:[0,1] neg_hi:[0,1]
	v_pk_mul_f32 v[108:109], v[108:109], v[112:113] op_sel:[0,1] op_sel_hi:[1,1]
	v_pk_mul_f32 v[110:111], v[110:111], v[112:113] op_sel:[0,1] op_sel_hi:[1,1]
	v_pk_fma_f32 v[108:109], v[192:193], v[108:109], v[196:197]
	v_pk_fma_f32 v[110:111], v[194:195], v[110:111], v[198:199]
	v_pk_mul_f32 v[108:109], v[108:109], s[82:83] op_sel_hi:[1,0]
	v_pk_mul_f32 v[110:111], v[110:111], s[82:83] op_sel_hi:[1,0]
	v_pk_fma_f32 v[60:61], v[60:61], 0.5, v[108:109] op_sel_hi:[1,0,1]
	v_pk_fma_f32 v[62:63], v[62:63], 0.5, v[110:111] op_sel_hi:[1,0,1]
	global_load_dwordx4 v[108:111], v244, s[60:61] offset:512
	v_add_f32_e32 v214, v214, v60
	v_add_f32_e32 v214, v214, v61
	v_add_f32_e32 v214, v214, v62
	v_add_f32_e32 v214, v214, v63
	v_fmac_f32_e32 v215, v60, v60
	v_fmac_f32_e32 v215, v61, v61
	v_fmac_f32_e32 v215, v62, v62
	v_fmac_f32_e32 v215, v63, v63
	s_waitcnt vmcnt(5)
	v_pk_add_f32 v[130:131], v[130:131], v[200:201] op_sel_hi:[1,0] neg_lo:[0,1] neg_hi:[0,1]
	v_pk_add_f32 v[132:133], v[132:133], v[200:201] op_sel_hi:[1,0] neg_lo:[0,1] neg_hi:[0,1]
	v_pk_mul_f32 v[130:131], v[130:131], v[200:201] op_sel:[0,1] op_sel_hi:[1,1]
	v_pk_mul_f32 v[132:133], v[132:133], v[200:201] op_sel:[0,1] op_sel_hi:[1,1]
	v_pk_fma_f32 v[130:131], v[192:193], v[130:131], v[196:197]
	v_pk_fma_f32 v[132:133], v[194:195], v[132:133], v[198:199]
	v_pk_mul_f32 v[130:131], v[130:131], s[82:83] op_sel_hi:[1,0]
	v_pk_mul_f32 v[132:133], v[132:133], s[82:83] op_sel_hi:[1,0]
	v_pk_fma_f32 v[56:57], v[56:57], 0.5, v[130:131] op_sel_hi:[1,0,1]
	v_pk_fma_f32 v[58:59], v[58:59], 0.5, v[132:133] op_sel_hi:[1,0,1]
	global_load_dwordx4 v[130:133], v245, s[60:61] offset:512
	v_add_f32_e32 v216, v216, v56
	v_add_f32_e32 v216, v216, v57
	v_add_f32_e32 v216, v216, v58
	v_add_f32_e32 v216, v216, v59
	v_fmac_f32_e32 v217, v56, v56
	v_fmac_f32_e32 v217, v57, v57
	v_fmac_f32_e32 v217, v58, v58
	v_fmac_f32_e32 v217, v59, v59
	s_waitcnt vmcnt(5)
	v_pk_add_f32 v[134:135], v[134:135], v[202:203] op_sel_hi:[1,0] neg_lo:[0,1] neg_hi:[0,1]
	v_pk_add_f32 v[136:137], v[136:137], v[202:203] op_sel_hi:[1,0] neg_lo:[0,1] neg_hi:[0,1]
	v_pk_mul_f32 v[134:135], v[134:135], v[202:203] op_sel:[0,1] op_sel_hi:[1,1]
	v_pk_mul_f32 v[136:137], v[136:137], v[202:203] op_sel:[0,1] op_sel_hi:[1,1]
	v_pk_fma_f32 v[134:135], v[192:193], v[134:135], v[196:197]
	v_pk_fma_f32 v[136:137], v[194:195], v[136:137], v[198:199]
	v_pk_mul_f32 v[134:135], v[134:135], s[82:83] op_sel_hi:[1,0]
	v_pk_mul_f32 v[136:137], v[136:137], s[82:83] op_sel_hi:[1,0]
	v_pk_fma_f32 v[52:53], v[52:53], 0.5, v[134:135] op_sel_hi:[1,0,1]
	v_pk_fma_f32 v[54:55], v[54:55], 0.5, v[136:137] op_sel_hi:[1,0,1]
	global_load_dwordx4 v[134:137], v246, s[60:61] offset:512
	v_add_f32_e32 v218, v218, v52
	v_add_f32_e32 v218, v218, v53
	v_add_f32_e32 v218, v218, v54
	v_add_f32_e32 v218, v218, v55
	v_fmac_f32_e32 v219, v52, v52
	v_fmac_f32_e32 v219, v53, v53
	v_fmac_f32_e32 v219, v54, v54
	v_fmac_f32_e32 v219, v55, v55
	s_waitcnt vmcnt(5)
	v_pk_add_f32 v[180:181], v[180:181], v[204:205] op_sel_hi:[1,0] neg_lo:[0,1] neg_hi:[0,1]
	v_pk_add_f32 v[182:183], v[182:183], v[204:205] op_sel_hi:[1,0] neg_lo:[0,1] neg_hi:[0,1]
	v_pk_mul_f32 v[180:181], v[180:181], v[204:205] op_sel:[0,1] op_sel_hi:[1,1]
	v_pk_mul_f32 v[182:183], v[182:183], v[204:205] op_sel:[0,1] op_sel_hi:[1,1]
	v_pk_fma_f32 v[180:181], v[192:193], v[180:181], v[196:197]
	v_pk_fma_f32 v[182:183], v[194:195], v[182:183], v[198:199]
	v_pk_mul_f32 v[180:181], v[180:181], s[82:83] op_sel_hi:[1,0]
	v_pk_mul_f32 v[182:183], v[182:183], s[82:83] op_sel_hi:[1,0]
	v_pk_fma_f32 v[48:49], v[48:49], 0.5, v[180:181] op_sel_hi:[1,0,1]
	v_pk_fma_f32 v[50:51], v[50:51], 0.5, v[182:183] op_sel_hi:[1,0,1]
	global_load_dwordx4 v[180:183], v247, s[60:61] offset:512
	v_add_f32_e32 v220, v220, v48
	v_add_f32_e32 v220, v220, v49
	v_add_f32_e32 v220, v220, v50
	v_add_f32_e32 v220, v220, v51
	v_fmac_f32_e32 v221, v48, v48
	v_fmac_f32_e32 v221, v49, v49
	v_fmac_f32_e32 v221, v50, v50
	v_fmac_f32_e32 v221, v51, v51
	s_waitcnt vmcnt(3)
	v_pk_add_f32 v[108:109], v[108:109], v[206:207] op_sel_hi:[1,0] neg_lo:[0,1] neg_hi:[0,1]
	v_pk_add_f32 v[110:111], v[110:111], v[206:207] op_sel_hi:[1,0] neg_lo:[0,1] neg_hi:[0,1]
	v_pk_mul_f32 v[108:109], v[108:109], v[206:207] op_sel:[0,1] op_sel_hi:[1,1]
	v_pk_mul_f32 v[110:111], v[110:111], v[206:207] op_sel:[0,1] op_sel_hi:[1,1]
	v_pk_fma_f32 v[108:109], v[192:193], v[108:109], v[196:197]
	v_pk_fma_f32 v[110:111], v[194:195], v[110:111], v[198:199]
	v_pk_mul_f32 v[108:109], v[108:109], s[82:83] op_sel_hi:[1,0]
	v_pk_mul_f32 v[110:111], v[110:111], s[82:83] op_sel_hi:[1,0]
	v_pk_fma_f32 v[44:45], v[44:45], 0.5, v[108:109] op_sel_hi:[1,0,1]
	v_pk_fma_f32 v[46:47], v[46:47], 0.5, v[110:111] op_sel_hi:[1,0,1]
	global_load_dwordx4 v[108:111], v240, s[60:61] offset:64
	v_add_f32_e32 v232, v232, v44
	v_add_f32_e32 v232, v232, v45
	v_add_f32_e32 v232, v232, v46
	v_add_f32_e32 v232, v232, v47
	v_fmac_f32_e32 v233, v44, v44
	v_fmac_f32_e32 v233, v45, v45
	v_fmac_f32_e32 v233, v46, v46
	v_fmac_f32_e32 v233, v47, v47
	s_waitcnt vmcnt(3)
	v_pk_add_f32 v[130:131], v[130:131], v[208:209] op_sel_hi:[1,0] neg_lo:[0,1] neg_hi:[0,1]
	v_pk_add_f32 v[132:133], v[132:133], v[208:209] op_sel_hi:[1,0] neg_lo:[0,1] neg_hi:[0,1]
	v_pk_mul_f32 v[130:131], v[130:131], v[208:209] op_sel:[0,1] op_sel_hi:[1,1]
	v_pk_mul_f32 v[132:133], v[132:133], v[208:209] op_sel:[0,1] op_sel_hi:[1,1]
	v_pk_fma_f32 v[130:131], v[192:193], v[130:131], v[196:197]
	v_pk_fma_f32 v[132:133], v[194:195], v[132:133], v[198:199]
	v_pk_mul_f32 v[130:131], v[130:131], s[82:83] op_sel_hi:[1,0]
	v_pk_mul_f32 v[132:133], v[132:133], s[82:83] op_sel_hi:[1,0]
	v_pk_fma_f32 v[40:41], v[40:41], 0.5, v[130:131] op_sel_hi:[1,0,1]
	v_pk_fma_f32 v[42:43], v[42:43], 0.5, v[132:133] op_sel_hi:[1,0,1]
	global_load_dwordx4 v[130:133], v241, s[60:61] offset:64
	v_add_f32_e32 v234, v234, v40
	v_add_f32_e32 v234, v234, v41
	v_add_f32_e32 v234, v234, v42
	v_add_f32_e32 v234, v234, v43
	v_fmac_f32_e32 v235, v40, v40
	v_fmac_f32_e32 v235, v41, v41
	v_fmac_f32_e32 v235, v42, v42
	v_fmac_f32_e32 v235, v43, v43
	s_waitcnt vmcnt(3)
	v_pk_add_f32 v[134:135], v[134:135], v[210:211] op_sel_hi:[1,0] neg_lo:[0,1] neg_hi:[0,1]
	v_pk_add_f32 v[136:137], v[136:137], v[210:211] op_sel_hi:[1,0] neg_lo:[0,1] neg_hi:[0,1]
	v_pk_mul_f32 v[134:135], v[134:135], v[210:211] op_sel:[0,1] op_sel_hi:[1,1]
	v_pk_mul_f32 v[136:137], v[136:137], v[210:211] op_sel:[0,1] op_sel_hi:[1,1]
	v_pk_fma_f32 v[134:135], v[192:193], v[134:135], v[196:197]
	v_pk_fma_f32 v[136:137], v[194:195], v[136:137], v[198:199]
	v_pk_mul_f32 v[134:135], v[134:135], s[82:83] op_sel_hi:[1,0]
	v_pk_mul_f32 v[136:137], v[136:137], s[82:83] op_sel_hi:[1,0]
	v_pk_fma_f32 v[36:37], v[36:37], 0.5, v[134:135] op_sel_hi:[1,0,1]
	v_pk_fma_f32 v[38:39], v[38:39], 0.5, v[136:137] op_sel_hi:[1,0,1]
	global_load_dwordx4 v[134:137], v242, s[60:61] offset:64
	v_add_f32_e32 v236, v236, v36
	v_add_f32_e32 v236, v236, v37
	v_add_f32_e32 v236, v236, v38
	v_add_f32_e32 v236, v236, v39
	v_fmac_f32_e32 v237, v36, v36
	v_fmac_f32_e32 v237, v37, v37
	v_fmac_f32_e32 v237, v38, v38
	v_fmac_f32_e32 v237, v39, v39
	s_waitcnt vmcnt(3)
	v_pk_add_f32 v[180:181], v[180:181], v[212:213] op_sel_hi:[1,0] neg_lo:[0,1] neg_hi:[0,1]
	v_pk_add_f32 v[182:183], v[182:183], v[212:213] op_sel_hi:[1,0] neg_lo:[0,1] neg_hi:[0,1]
	v_pk_mul_f32 v[180:181], v[180:181], v[212:213] op_sel:[0,1] op_sel_hi:[1,1]
	v_pk_mul_f32 v[182:183], v[182:183], v[212:213] op_sel:[0,1] op_sel_hi:[1,1]
	v_pk_fma_f32 v[180:181], v[192:193], v[180:181], v[196:197]
	v_pk_fma_f32 v[182:183], v[194:195], v[182:183], v[198:199]
	v_pk_mul_f32 v[180:181], v[180:181], s[82:83] op_sel_hi:[1,0]
	v_pk_mul_f32 v[182:183], v[182:183], s[82:83] op_sel_hi:[1,0]
	v_pk_fma_f32 v[32:33], v[32:33], 0.5, v[180:181] op_sel_hi:[1,0,1]
	v_pk_fma_f32 v[34:35], v[34:35], 0.5, v[182:183] op_sel_hi:[1,0,1]
	global_load_dwordx4 v[180:183], v243, s[60:61] offset:64
	v_add_f32_e32 v238, v238, v32
	v_add_f32_e32 v238, v238, v33
	v_add_f32_e32 v238, v238, v34
	v_add_f32_e32 v238, v238, v35
	v_fmac_f32_e32 v239, v32, v32
	v_fmac_f32_e32 v239, v33, v33
	v_fmac_f32_e32 v239, v34, v34
	v_fmac_f32_e32 v239, v35, v35
	global_load_dwordx4 v[192:195], v249, s[48:49] offset:576
	global_load_dwordx4 v[196:199], v249, s[84:85] offset:576
	s_waitcnt vmcnt(5)
	v_pk_add_f32 v[108:109], v[108:109], v[112:113] op_sel_hi:[1,0] neg_lo:[0,1] neg_hi:[0,1]
	v_pk_add_f32 v[110:111], v[110:111], v[112:113] op_sel_hi:[1,0] neg_lo:[0,1] neg_hi:[0,1]
	v_pk_mul_f32 v[108:109], v[108:109], v[112:113] op_sel:[0,1] op_sel_hi:[1,1]
	v_pk_mul_f32 v[110:111], v[110:111], v[112:113] op_sel:[0,1] op_sel_hi:[1,1]
	v_pk_fma_f32 v[108:109], v[184:185], v[108:109], v[188:189]
	v_pk_fma_f32 v[110:111], v[186:187], v[110:111], v[190:191]
	v_pk_mul_f32 v[108:109], v[108:109], s[82:83] op_sel_hi:[1,0]
	v_pk_mul_f32 v[110:111], v[110:111], s[82:83] op_sel_hi:[1,0]
	v_pk_fma_f32 v[92:93], v[92:93], 0.5, v[108:109] op_sel_hi:[1,0,1]
	v_pk_fma_f32 v[94:95], v[94:95], 0.5, v[110:111] op_sel_hi:[1,0,1]
	global_load_dwordx4 v[108:111], v244, s[60:61] offset:64
	v_add_f32_e32 v214, v214, v92
	v_add_f32_e32 v214, v214, v93
	v_add_f32_e32 v214, v214, v94
	v_add_f32_e32 v214, v214, v95
	v_fmac_f32_e32 v215, v92, v92
	v_fmac_f32_e32 v215, v93, v93
	v_fmac_f32_e32 v215, v94, v94
	v_fmac_f32_e32 v215, v95, v95
	s_waitcnt vmcnt(5)
	v_pk_add_f32 v[130:131], v[130:131], v[200:201] op_sel_hi:[1,0] neg_lo:[0,1] neg_hi:[0,1]
	v_pk_add_f32 v[132:133], v[132:133], v[200:201] op_sel_hi:[1,0] neg_lo:[0,1] neg_hi:[0,1]
	v_pk_mul_f32 v[130:131], v[130:131], v[200:201] op_sel:[0,1] op_sel_hi:[1,1]
	v_pk_mul_f32 v[132:133], v[132:133], v[200:201] op_sel:[0,1] op_sel_hi:[1,1]
	v_pk_fma_f32 v[130:131], v[184:185], v[130:131], v[188:189]
	v_pk_fma_f32 v[132:133], v[186:187], v[132:133], v[190:191]
	v_pk_mul_f32 v[130:131], v[130:131], s[82:83] op_sel_hi:[1,0]
	v_pk_mul_f32 v[132:133], v[132:133], s[82:83] op_sel_hi:[1,0]
	v_pk_fma_f32 v[88:89], v[88:89], 0.5, v[130:131] op_sel_hi:[1,0,1]
	v_pk_fma_f32 v[90:91], v[90:91], 0.5, v[132:133] op_sel_hi:[1,0,1]
	global_load_dwordx4 v[130:133], v245, s[60:61] offset:64
	v_add_f32_e32 v216, v216, v88
	v_add_f32_e32 v216, v216, v89
	v_add_f32_e32 v216, v216, v90
	v_add_f32_e32 v216, v216, v91
	v_fmac_f32_e32 v217, v88, v88
	v_fmac_f32_e32 v217, v89, v89
	v_fmac_f32_e32 v217, v90, v90
	v_fmac_f32_e32 v217, v91, v91
	s_waitcnt vmcnt(5)
	v_pk_add_f32 v[134:135], v[134:135], v[202:203] op_sel_hi:[1,0] neg_lo:[0,1] neg_hi:[0,1]
	v_pk_add_f32 v[136:137], v[136:137], v[202:203] op_sel_hi:[1,0] neg_lo:[0,1] neg_hi:[0,1]
	v_pk_mul_f32 v[134:135], v[134:135], v[202:203] op_sel:[0,1] op_sel_hi:[1,1]
	v_pk_mul_f32 v[136:137], v[136:137], v[202:203] op_sel:[0,1] op_sel_hi:[1,1]
	v_pk_fma_f32 v[134:135], v[184:185], v[134:135], v[188:189]
	v_pk_fma_f32 v[136:137], v[186:187], v[136:137], v[190:191]
	v_pk_mul_f32 v[134:135], v[134:135], s[82:83] op_sel_hi:[1,0]
	v_pk_mul_f32 v[136:137], v[136:137], s[82:83] op_sel_hi:[1,0]
	v_pk_fma_f32 v[84:85], v[84:85], 0.5, v[134:135] op_sel_hi:[1,0,1]
	v_pk_fma_f32 v[86:87], v[86:87], 0.5, v[136:137] op_sel_hi:[1,0,1]
	global_load_dwordx4 v[134:137], v246, s[60:61] offset:64
	v_add_f32_e32 v218, v218, v84
	v_add_f32_e32 v218, v218, v85
	v_add_f32_e32 v218, v218, v86
	v_add_f32_e32 v218, v218, v87
	v_fmac_f32_e32 v219, v84, v84
	v_fmac_f32_e32 v219, v85, v85
	v_fmac_f32_e32 v219, v86, v86
	v_fmac_f32_e32 v219, v87, v87
	s_waitcnt vmcnt(5)
	v_pk_add_f32 v[180:181], v[180:181], v[204:205] op_sel_hi:[1,0] neg_lo:[0,1] neg_hi:[0,1]
	v_pk_add_f32 v[182:183], v[182:183], v[204:205] op_sel_hi:[1,0] neg_lo:[0,1] neg_hi:[0,1]
	v_pk_mul_f32 v[180:181], v[180:181], v[204:205] op_sel:[0,1] op_sel_hi:[1,1]
	v_pk_mul_f32 v[182:183], v[182:183], v[204:205] op_sel:[0,1] op_sel_hi:[1,1]
	v_pk_fma_f32 v[180:181], v[184:185], v[180:181], v[188:189]
	v_pk_fma_f32 v[182:183], v[186:187], v[182:183], v[190:191]
	v_pk_mul_f32 v[180:181], v[180:181], s[82:83] op_sel_hi:[1,0]
	v_pk_mul_f32 v[182:183], v[182:183], s[82:83] op_sel_hi:[1,0]
	v_pk_fma_f32 v[80:81], v[80:81], 0.5, v[180:181] op_sel_hi:[1,0,1]
	v_pk_fma_f32 v[82:83], v[82:83], 0.5, v[182:183] op_sel_hi:[1,0,1]
	global_load_dwordx4 v[180:183], v247, s[60:61] offset:64
	v_add_f32_e32 v220, v220, v80
	v_add_f32_e32 v220, v220, v81
	v_add_f32_e32 v220, v220, v82
	v_add_f32_e32 v220, v220, v83
	v_fmac_f32_e32 v221, v80, v80
	v_fmac_f32_e32 v221, v81, v81
	v_fmac_f32_e32 v221, v82, v82
	v_fmac_f32_e32 v221, v83, v83
	s_waitcnt vmcnt(3)
	v_pk_add_f32 v[108:109], v[108:109], v[206:207] op_sel_hi:[1,0] neg_lo:[0,1] neg_hi:[0,1]
	v_pk_add_f32 v[110:111], v[110:111], v[206:207] op_sel_hi:[1,0] neg_lo:[0,1] neg_hi:[0,1]
	v_pk_mul_f32 v[108:109], v[108:109], v[206:207] op_sel:[0,1] op_sel_hi:[1,1]
	v_pk_mul_f32 v[110:111], v[110:111], v[206:207] op_sel:[0,1] op_sel_hi:[1,1]
	v_pk_fma_f32 v[108:109], v[184:185], v[108:109], v[188:189]
	v_pk_fma_f32 v[110:111], v[186:187], v[110:111], v[190:191]
	v_pk_mul_f32 v[108:109], v[108:109], s[82:83] op_sel_hi:[1,0]
	v_pk_mul_f32 v[110:111], v[110:111], s[82:83] op_sel_hi:[1,0]
	v_pk_fma_f32 v[76:77], v[76:77], 0.5, v[108:109] op_sel_hi:[1,0,1]
	v_pk_fma_f32 v[78:79], v[78:79], 0.5, v[110:111] op_sel_hi:[1,0,1]
	global_load_dwordx4 v[108:111], v240, s[60:61] offset:576
	v_add_f32_e32 v232, v232, v76
	v_add_f32_e32 v232, v232, v77
	v_add_f32_e32 v232, v232, v78
	v_add_f32_e32 v232, v232, v79
	v_fmac_f32_e32 v233, v76, v76
	v_fmac_f32_e32 v233, v77, v77
	v_fmac_f32_e32 v233, v78, v78
	v_fmac_f32_e32 v233, v79, v79
	s_waitcnt vmcnt(3)
	v_pk_add_f32 v[130:131], v[130:131], v[208:209] op_sel_hi:[1,0] neg_lo:[0,1] neg_hi:[0,1]
	v_pk_add_f32 v[132:133], v[132:133], v[208:209] op_sel_hi:[1,0] neg_lo:[0,1] neg_hi:[0,1]
	v_pk_mul_f32 v[130:131], v[130:131], v[208:209] op_sel:[0,1] op_sel_hi:[1,1]
	v_pk_mul_f32 v[132:133], v[132:133], v[208:209] op_sel:[0,1] op_sel_hi:[1,1]
	v_pk_fma_f32 v[130:131], v[184:185], v[130:131], v[188:189]
	v_pk_fma_f32 v[132:133], v[186:187], v[132:133], v[190:191]
	v_pk_mul_f32 v[130:131], v[130:131], s[82:83] op_sel_hi:[1,0]
	v_pk_mul_f32 v[132:133], v[132:133], s[82:83] op_sel_hi:[1,0]
	v_pk_fma_f32 v[72:73], v[72:73], 0.5, v[130:131] op_sel_hi:[1,0,1]
	v_pk_fma_f32 v[74:75], v[74:75], 0.5, v[132:133] op_sel_hi:[1,0,1]
	global_load_dwordx4 v[130:133], v241, s[60:61] offset:576
	v_add_f32_e32 v234, v234, v72
	v_add_f32_e32 v234, v234, v73
	v_add_f32_e32 v234, v234, v74
	v_add_f32_e32 v234, v234, v75
	v_fmac_f32_e32 v235, v72, v72
	v_fmac_f32_e32 v235, v73, v73
	v_fmac_f32_e32 v235, v74, v74
	v_fmac_f32_e32 v235, v75, v75
	s_waitcnt vmcnt(3)
	v_pk_add_f32 v[134:135], v[134:135], v[210:211] op_sel_hi:[1,0] neg_lo:[0,1] neg_hi:[0,1]
	v_pk_add_f32 v[136:137], v[136:137], v[210:211] op_sel_hi:[1,0] neg_lo:[0,1] neg_hi:[0,1]
	v_pk_mul_f32 v[134:135], v[134:135], v[210:211] op_sel:[0,1] op_sel_hi:[1,1]
	v_pk_mul_f32 v[136:137], v[136:137], v[210:211] op_sel:[0,1] op_sel_hi:[1,1]
	v_pk_fma_f32 v[134:135], v[184:185], v[134:135], v[188:189]
	v_pk_fma_f32 v[136:137], v[186:187], v[136:137], v[190:191]
	v_pk_mul_f32 v[134:135], v[134:135], s[82:83] op_sel_hi:[1,0]
	v_pk_mul_f32 v[136:137], v[136:137], s[82:83] op_sel_hi:[1,0]
	v_pk_fma_f32 v[68:69], v[68:69], 0.5, v[134:135] op_sel_hi:[1,0,1]
	v_pk_fma_f32 v[70:71], v[70:71], 0.5, v[136:137] op_sel_hi:[1,0,1]
	global_load_dwordx4 v[134:137], v242, s[60:61] offset:576
	v_add_f32_e32 v236, v236, v68
	v_add_f32_e32 v236, v236, v69
	v_add_f32_e32 v236, v236, v70
	v_add_f32_e32 v236, v236, v71
	v_fmac_f32_e32 v237, v68, v68
	v_fmac_f32_e32 v237, v69, v69
	v_fmac_f32_e32 v237, v70, v70
	v_fmac_f32_e32 v237, v71, v71
	s_waitcnt vmcnt(3)
	v_pk_add_f32 v[180:181], v[180:181], v[212:213] op_sel_hi:[1,0] neg_lo:[0,1] neg_hi:[0,1]
	v_pk_add_f32 v[182:183], v[182:183], v[212:213] op_sel_hi:[1,0] neg_lo:[0,1] neg_hi:[0,1]
	v_pk_mul_f32 v[180:181], v[180:181], v[212:213] op_sel:[0,1] op_sel_hi:[1,1]
	v_pk_mul_f32 v[182:183], v[182:183], v[212:213] op_sel:[0,1] op_sel_hi:[1,1]
	v_pk_fma_f32 v[180:181], v[184:185], v[180:181], v[188:189]
	v_pk_fma_f32 v[182:183], v[186:187], v[182:183], v[190:191]
	v_pk_mul_f32 v[180:181], v[180:181], s[82:83] op_sel_hi:[1,0]
	v_pk_mul_f32 v[182:183], v[182:183], s[82:83] op_sel_hi:[1,0]
	v_pk_fma_f32 v[64:65], v[64:65], 0.5, v[180:181] op_sel_hi:[1,0,1]
	v_pk_fma_f32 v[66:67], v[66:67], 0.5, v[182:183] op_sel_hi:[1,0,1]
	global_load_dwordx4 v[180:183], v243, s[60:61] offset:576
	v_add_f32_e32 v238, v238, v64
	v_add_f32_e32 v238, v238, v65
	v_add_f32_e32 v238, v238, v66
	v_add_f32_e32 v238, v238, v67
	v_fmac_f32_e32 v239, v64, v64
	v_fmac_f32_e32 v239, v65, v65
	v_fmac_f32_e32 v239, v66, v66
	v_fmac_f32_e32 v239, v67, v67
	s_waitcnt vmcnt(3)
	v_pk_add_f32 v[108:109], v[108:109], v[112:113] op_sel_hi:[1,0] neg_lo:[0,1] neg_hi:[0,1]
	v_pk_add_f32 v[110:111], v[110:111], v[112:113] op_sel_hi:[1,0] neg_lo:[0,1] neg_hi:[0,1]
	v_pk_mul_f32 v[108:109], v[108:109], v[112:113] op_sel:[0,1] op_sel_hi:[1,1]
	v_pk_mul_f32 v[110:111], v[110:111], v[112:113] op_sel:[0,1] op_sel_hi:[1,1]
	v_pk_fma_f32 v[108:109], v[192:193], v[108:109], v[196:197]
	v_pk_fma_f32 v[110:111], v[194:195], v[110:111], v[198:199]
	v_pk_mul_f32 v[108:109], v[108:109], s[82:83] op_sel_hi:[1,0]
	v_pk_mul_f32 v[110:111], v[110:111], s[82:83] op_sel_hi:[1,0]
	v_pk_fma_f32 v[28:29], v[28:29], 0.5, v[108:109] op_sel_hi:[1,0,1]
	v_pk_fma_f32 v[30:31], v[30:31], 0.5, v[110:111] op_sel_hi:[1,0,1]
	global_load_dwordx4 v[108:111], v244, s[60:61] offset:576
	v_add_f32_e32 v214, v214, v28
	v_add_f32_e32 v214, v214, v29
	v_add_f32_e32 v214, v214, v30
	v_add_f32_e32 v214, v214, v31
	v_fmac_f32_e32 v215, v28, v28
	v_fmac_f32_e32 v215, v29, v29
	v_fmac_f32_e32 v215, v30, v30
	v_fmac_f32_e32 v215, v31, v31
	s_waitcnt vmcnt(3)
	v_pk_add_f32 v[130:131], v[130:131], v[200:201] op_sel_hi:[1,0] neg_lo:[0,1] neg_hi:[0,1]
	v_pk_add_f32 v[132:133], v[132:133], v[200:201] op_sel_hi:[1,0] neg_lo:[0,1] neg_hi:[0,1]
	v_pk_mul_f32 v[130:131], v[130:131], v[200:201] op_sel:[0,1] op_sel_hi:[1,1]
	v_pk_mul_f32 v[132:133], v[132:133], v[200:201] op_sel:[0,1] op_sel_hi:[1,1]
	v_pk_fma_f32 v[130:131], v[192:193], v[130:131], v[196:197]
	v_pk_fma_f32 v[132:133], v[194:195], v[132:133], v[198:199]
	v_pk_mul_f32 v[130:131], v[130:131], s[82:83] op_sel_hi:[1,0]
	v_pk_mul_f32 v[132:133], v[132:133], s[82:83] op_sel_hi:[1,0]
	v_pk_fma_f32 v[24:25], v[24:25], 0.5, v[130:131] op_sel_hi:[1,0,1]
	v_pk_fma_f32 v[26:27], v[26:27], 0.5, v[132:133] op_sel_hi:[1,0,1]
	global_load_dwordx4 v[130:133], v245, s[60:61] offset:576
	v_add_f32_e32 v216, v216, v24
	v_add_f32_e32 v216, v216, v25
	v_add_f32_e32 v216, v216, v26
	v_add_f32_e32 v216, v216, v27
	v_fmac_f32_e32 v217, v24, v24
	v_fmac_f32_e32 v217, v25, v25
	v_fmac_f32_e32 v217, v26, v26
	v_fmac_f32_e32 v217, v27, v27
	s_waitcnt vmcnt(3)
	v_pk_add_f32 v[134:135], v[134:135], v[202:203] op_sel_hi:[1,0] neg_lo:[0,1] neg_hi:[0,1]
	v_pk_add_f32 v[136:137], v[136:137], v[202:203] op_sel_hi:[1,0] neg_lo:[0,1] neg_hi:[0,1]
	v_pk_mul_f32 v[134:135], v[134:135], v[202:203] op_sel:[0,1] op_sel_hi:[1,1]
	v_pk_mul_f32 v[136:137], v[136:137], v[202:203] op_sel:[0,1] op_sel_hi:[1,1]
	v_pk_fma_f32 v[134:135], v[192:193], v[134:135], v[196:197]
	v_pk_fma_f32 v[136:137], v[194:195], v[136:137], v[198:199]
	v_pk_mul_f32 v[134:135], v[134:135], s[82:83] op_sel_hi:[1,0]
	v_pk_mul_f32 v[136:137], v[136:137], s[82:83] op_sel_hi:[1,0]
	v_pk_fma_f32 v[20:21], v[20:21], 0.5, v[134:135] op_sel_hi:[1,0,1]
	v_pk_fma_f32 v[22:23], v[22:23], 0.5, v[136:137] op_sel_hi:[1,0,1]
	global_load_dwordx4 v[134:137], v246, s[60:61] offset:576
	v_add_f32_e32 v218, v218, v20
	v_add_f32_e32 v218, v218, v21
	v_add_f32_e32 v218, v218, v22
	v_add_f32_e32 v218, v218, v23
	v_fmac_f32_e32 v219, v20, v20
	v_fmac_f32_e32 v219, v21, v21
	v_fmac_f32_e32 v219, v22, v22
	v_fmac_f32_e32 v219, v23, v23
	s_waitcnt vmcnt(3)
	v_pk_add_f32 v[180:181], v[180:181], v[204:205] op_sel_hi:[1,0] neg_lo:[0,1] neg_hi:[0,1]
	v_pk_add_f32 v[182:183], v[182:183], v[204:205] op_sel_hi:[1,0] neg_lo:[0,1] neg_hi:[0,1]
	v_pk_mul_f32 v[180:181], v[180:181], v[204:205] op_sel:[0,1] op_sel_hi:[1,1]
	v_pk_mul_f32 v[182:183], v[182:183], v[204:205] op_sel:[0,1] op_sel_hi:[1,1]
	v_pk_fma_f32 v[180:181], v[192:193], v[180:181], v[196:197]
	v_pk_fma_f32 v[182:183], v[194:195], v[182:183], v[198:199]
	v_pk_mul_f32 v[180:181], v[180:181], s[82:83] op_sel_hi:[1,0]
	v_pk_mul_f32 v[182:183], v[182:183], s[82:83] op_sel_hi:[1,0]
	v_pk_fma_f32 v[16:17], v[16:17], 0.5, v[180:181] op_sel_hi:[1,0,1]
	v_pk_fma_f32 v[18:19], v[18:19], 0.5, v[182:183] op_sel_hi:[1,0,1]
	global_load_dwordx4 v[180:183], v247, s[60:61] offset:576
	v_add_f32_e32 v220, v220, v16
	v_add_f32_e32 v220, v220, v17
	v_add_f32_e32 v220, v220, v18
	v_add_f32_e32 v220, v220, v19
	v_fmac_f32_e32 v221, v16, v16
	v_fmac_f32_e32 v221, v17, v17
	v_fmac_f32_e32 v221, v18, v18
	v_fmac_f32_e32 v221, v19, v19
	s_waitcnt vmcnt(3)
	v_pk_add_f32 v[108:109], v[108:109], v[206:207] op_sel_hi:[1,0] neg_lo:[0,1] neg_hi:[0,1]
	v_pk_add_f32 v[110:111], v[110:111], v[206:207] op_sel_hi:[1,0] neg_lo:[0,1] neg_hi:[0,1]
	v_pk_mul_f32 v[108:109], v[108:109], v[206:207] op_sel:[0,1] op_sel_hi:[1,1]
	v_pk_mul_f32 v[110:111], v[110:111], v[206:207] op_sel:[0,1] op_sel_hi:[1,1]
	v_pk_fma_f32 v[108:109], v[192:193], v[108:109], v[196:197]
	v_pk_fma_f32 v[110:111], v[194:195], v[110:111], v[198:199]
	v_pk_mul_f32 v[108:109], v[108:109], s[82:83] op_sel_hi:[1,0]
	v_pk_mul_f32 v[110:111], v[110:111], s[82:83] op_sel_hi:[1,0]
	v_pk_fma_f32 v[12:13], v[12:13], 0.5, v[108:109] op_sel_hi:[1,0,1]
	v_pk_fma_f32 v[14:15], v[14:15], 0.5, v[110:111] op_sel_hi:[1,0,1]
	v_add_f32_e32 v232, v232, v12
	v_add_f32_e32 v232, v232, v13
	v_add_f32_e32 v232, v232, v14
	v_add_f32_e32 v232, v232, v15
	v_fmac_f32_e32 v233, v12, v12
	v_fmac_f32_e32 v233, v13, v13
	v_fmac_f32_e32 v233, v14, v14
	v_fmac_f32_e32 v233, v15, v15
	s_waitcnt vmcnt(2)
	v_pk_add_f32 v[130:131], v[130:131], v[208:209] op_sel_hi:[1,0] neg_lo:[0,1] neg_hi:[0,1]
	v_pk_add_f32 v[132:133], v[132:133], v[208:209] op_sel_hi:[1,0] neg_lo:[0,1] neg_hi:[0,1]
	v_pk_mul_f32 v[130:131], v[130:131], v[208:209] op_sel:[0,1] op_sel_hi:[1,1]
	v_pk_mul_f32 v[132:133], v[132:133], v[208:209] op_sel:[0,1] op_sel_hi:[1,1]
	v_pk_fma_f32 v[130:131], v[192:193], v[130:131], v[196:197]
	v_pk_fma_f32 v[132:133], v[194:195], v[132:133], v[198:199]
	v_pk_mul_f32 v[130:131], v[130:131], s[82:83] op_sel_hi:[1,0]
	v_pk_mul_f32 v[132:133], v[132:133], s[82:83] op_sel_hi:[1,0]
	v_pk_fma_f32 v[8:9], v[8:9], 0.5, v[130:131] op_sel_hi:[1,0,1]
	v_pk_fma_f32 v[10:11], v[10:11], 0.5, v[132:133] op_sel_hi:[1,0,1]
	v_add_f32_e32 v234, v234, v8
	v_add_f32_e32 v234, v234, v9
	v_add_f32_e32 v234, v234, v10
	v_add_f32_e32 v234, v234, v11
	v_fmac_f32_e32 v235, v8, v8
	v_fmac_f32_e32 v235, v9, v9
	v_fmac_f32_e32 v235, v10, v10
	v_fmac_f32_e32 v235, v11, v11
	s_waitcnt vmcnt(1)
	v_pk_add_f32 v[134:135], v[134:135], v[210:211] op_sel_hi:[1,0] neg_lo:[0,1] neg_hi:[0,1]
	v_pk_add_f32 v[136:137], v[136:137], v[210:211] op_sel_hi:[1,0] neg_lo:[0,1] neg_hi:[0,1]
	v_pk_mul_f32 v[134:135], v[134:135], v[210:211] op_sel:[0,1] op_sel_hi:[1,1]
	v_pk_mul_f32 v[136:137], v[136:137], v[210:211] op_sel:[0,1] op_sel_hi:[1,1]
	v_pk_fma_f32 v[134:135], v[192:193], v[134:135], v[196:197]
	v_pk_fma_f32 v[136:137], v[194:195], v[136:137], v[198:199]
	v_pk_mul_f32 v[134:135], v[134:135], s[82:83] op_sel_hi:[1,0]
	v_pk_mul_f32 v[136:137], v[136:137], s[82:83] op_sel_hi:[1,0]
	v_pk_fma_f32 v[4:5], v[4:5], 0.5, v[134:135] op_sel_hi:[1,0,1]
	v_pk_fma_f32 v[6:7], v[6:7], 0.5, v[136:137] op_sel_hi:[1,0,1]
	v_add_f32_e32 v236, v236, v4
	v_add_f32_e32 v236, v236, v5
	v_add_f32_e32 v236, v236, v6
	v_add_f32_e32 v236, v236, v7
	v_fmac_f32_e32 v237, v4, v4
	v_fmac_f32_e32 v237, v5, v5
	v_fmac_f32_e32 v237, v6, v6
	v_fmac_f32_e32 v237, v7, v7
	s_waitcnt vmcnt(0)
	v_pk_add_f32 v[180:181], v[180:181], v[212:213] op_sel_hi:[1,0] neg_lo:[0,1] neg_hi:[0,1]
	v_pk_add_f32 v[182:183], v[182:183], v[212:213] op_sel_hi:[1,0] neg_lo:[0,1] neg_hi:[0,1]
	v_pk_mul_f32 v[180:181], v[180:181], v[212:213] op_sel:[0,1] op_sel_hi:[1,1]
	v_pk_mul_f32 v[182:183], v[182:183], v[212:213] op_sel:[0,1] op_sel_hi:[1,1]
	v_pk_fma_f32 v[180:181], v[192:193], v[180:181], v[196:197]
	v_pk_fma_f32 v[182:183], v[194:195], v[182:183], v[198:199]
	v_pk_mul_f32 v[180:181], v[180:181], s[82:83] op_sel_hi:[1,0]
	v_pk_mul_f32 v[182:183], v[182:183], s[82:83] op_sel_hi:[1,0]
	v_pk_fma_f32 v[0:1], v[0:1], 0.5, v[180:181] op_sel_hi:[1,0,1]
	v_pk_fma_f32 v[2:3], v[2:3], 0.5, v[182:183] op_sel_hi:[1,0,1]
	v_add_f32_e32 v238, v238, v0
	v_add_f32_e32 v238, v238, v1
	v_add_f32_e32 v238, v238, v2
	v_add_f32_e32 v238, v238, v3
	v_fmac_f32_e32 v239, v0, v0
	v_fmac_f32_e32 v239, v1, v1
	v_fmac_f32_e32 v239, v2, v2
	v_fmac_f32_e32 v239, v3, v3
	ds_swizzle_b32 v108, v214 offset:swizzle(SWAP,16)
	ds_swizzle_b32 v109, v215 offset:swizzle(SWAP,16)
	ds_swizzle_b32 v110, v216 offset:swizzle(SWAP,16)
	ds_swizzle_b32 v111, v217 offset:swizzle(SWAP,16)
	ds_swizzle_b32 v130, v218 offset:swizzle(SWAP,16)
	ds_swizzle_b32 v131, v219 offset:swizzle(SWAP,16)
	ds_swizzle_b32 v132, v220 offset:swizzle(SWAP,16)
	ds_swizzle_b32 v133, v221 offset:swizzle(SWAP,16)
	ds_swizzle_b32 v134, v232 offset:swizzle(SWAP,16)
	ds_swizzle_b32 v135, v233 offset:swizzle(SWAP,16)
	ds_swizzle_b32 v136, v234 offset:swizzle(SWAP,16)
	ds_swizzle_b32 v137, v235 offset:swizzle(SWAP,16)
	ds_swizzle_b32 v180, v236 offset:swizzle(SWAP,16)
	ds_swizzle_b32 v181, v237 offset:swizzle(SWAP,16)
	ds_swizzle_b32 v182, v238 offset:swizzle(SWAP,16)
	ds_swizzle_b32 v183, v239 offset:swizzle(SWAP,16)
	s_waitcnt lgkmcnt(0)
	v_add_f32_e32 v214, v214, v108
	v_add_f32_e32 v215, v215, v109
	v_add_f32_e32 v216, v216, v110
	v_add_f32_e32 v217, v217, v111
	v_add_f32_e32 v218, v218, v130
	v_add_f32_e32 v219, v219, v131
	v_add_f32_e32 v220, v220, v132
	v_add_f32_e32 v221, v221, v133
	v_add_f32_e32 v232, v232, v134
	v_add_f32_e32 v233, v233, v135
	v_add_f32_e32 v234, v234, v136
	v_add_f32_e32 v235, v235, v137
	v_add_f32_e32 v236, v236, v180
	v_add_f32_e32 v237, v237, v181
	v_add_f32_e32 v238, v238, v182
	v_add_f32_e32 v239, v239, v183
	v_mov_b32_e32 v108, v214
	v_mov_b32_e32 v109, v215
	v_mov_b32_e32 v110, v216
	v_mov_b32_e32 v111, v217
	v_mov_b32_e32 v130, v218
	v_mov_b32_e32 v131, v219
	v_mov_b32_e32 v132, v220
	v_mov_b32_e32 v133, v221
	v_mov_b32_e32 v134, v232
	v_mov_b32_e32 v135, v233
	v_mov_b32_e32 v136, v234
	v_mov_b32_e32 v137, v235
	v_mov_b32_e32 v180, v236
	v_mov_b32_e32 v181, v237
	v_mov_b32_e32 v182, v238
	v_mov_b32_e32 v183, v239
	s_nop 1
	v_permlane32_swap_b32_e32 v108, v214
	v_permlane32_swap_b32_e32 v109, v215
	v_permlane32_swap_b32_e32 v110, v216
	v_permlane32_swap_b32_e32 v111, v217
	v_permlane32_swap_b32_e32 v130, v218
	v_permlane32_swap_b32_e32 v131, v219
	v_permlane32_swap_b32_e32 v132, v220
	v_permlane32_swap_b32_e32 v133, v221
	v_permlane32_swap_b32_e32 v134, v232
	v_permlane32_swap_b32_e32 v135, v233
	v_permlane32_swap_b32_e32 v136, v234
	v_permlane32_swap_b32_e32 v137, v235
	v_permlane32_swap_b32_e32 v180, v236
	v_permlane32_swap_b32_e32 v181, v237
	v_permlane32_swap_b32_e32 v182, v238
	v_permlane32_swap_b32_e32 v183, v239
	v_add_f32_e32 v214, v214, v108
	v_add_f32_e32 v215, v215, v109
	v_add_f32_e32 v216, v216, v110
	v_add_f32_e32 v217, v217, v111
	v_add_f32_e32 v218, v218, v130
	v_add_f32_e32 v219, v219, v131
	v_add_f32_e32 v220, v220, v132
	v_add_f32_e32 v221, v221, v133
	v_add_f32_e32 v232, v232, v134
	v_add_f32_e32 v233, v233, v135
	v_add_f32_e32 v234, v234, v136
	v_add_f32_e32 v235, v235, v137
	v_add_f32_e32 v236, v236, v180
	v_add_f32_e32 v237, v237, v181
	v_add_f32_e32 v238, v238, v182
	v_add_f32_e32 v239, v239, v183
	v_lshrrev_b32_e32 v108, 5, v159
	v_lshl_add_u32 v108, v108, 8, v158
	v_lshlrev_b32_e32 v108, 3, v108
	v_add_u32_e32 v108, 0x20000, v108
	ds_write_b64 v108, v[214:215]
	ds_write_b64 v108, v[216:217] offset:128
	ds_write_b64 v108, v[218:219] offset:256
	ds_write_b64 v108, v[220:221] offset:384
	ds_write_b64 v108, v[232:233] offset:1024
	ds_write_b64 v108, v[234:235] offset:1152
	ds_write_b64 v108, v[236:237] offset:1280
	ds_write_b64 v108, v[238:239] offset:1408
	s_waitcnt lgkmcnt(0)
	s_barrier
	v_readfirstlane_b32 s6, v222
	v_readlane_b32 s8, v252, 14
	v_readlane_b32 s9, v252, 15
	s_nop 3
	s_lshr_b32 s6, s6, 6
	s_lshl_b32 s7, s4, 13
	s_add_u32 s10, s8, 0x16740800
	s_addc_u32 s11, s9, 0
	s_add_u32 s10, s10, s7
	s_addc_u32 s11, s11, 0
	s_lshl_b32 s7, s4, 2
	s_add_u32 s12, s8, 0x1daca000
	s_addc_u32 s13, s9, 0
	s_add_u32 s12, s12, s7
	s_addc_u32 s13, s13, 0
	s_cmp_gt_u32 s6, 3
	s_cbranch_scc1 .LfeAf_1
	v_lshlrev_b32_e32 v110, 3, v222
	v_add_u32_e32 v183, 0x20000, v110
	ds_read_b64 v[130:131], v183
	ds_read_b64 v[132:133], v183 offset:2048
	ds_read_b64 v[134:135], v183 offset:4096
	ds_read_b64 v[136:137], v183 offset:6144
	s_waitcnt lgkmcnt(0)
	v_add_f32_e32 v130, v130, v132
	v_add_f32_e32 v131, v131, v133
	v_add_f32_e32 v134, v134, v136
	v_add_f32_e32 v135, v135, v137
	v_add_f32_e32 v130, v130, v134
	v_add_f32_e32 v131, v131, v135
	v_lshl_add_u32 v111, s5, 11, v110
	global_store_dwordx2 v111, v[130:131], s[10:11] sc1
.LfeAf_1:
	s_waitcnt vmcnt(0)
	s_barrier
	s_cmp_lg_u32 s6, 0
	s_cbranch_scc1 .LfeAf_3
	s_mov_b64 s[14:15], exec
	s_mov_b64 exec, 1
	v_mov_b32_e32 v180, 0
	v_mov_b32_e32 v181, 1
	global_atomic_add v182, v180, v181, s[12:13] sc0
	s_waitcnt vmcnt(0)
	v_and_b32_e32 v182, -4, v182
	v_add_u32_e32 v182, 4, v182
	s_mov_b32 s7, 0
.LfeAf_2:
	global_load_dword v181, v180, s[12:13] sc1
	s_waitcnt vmcnt(0)
	v_cmp_ge_u32_e32 vcc, v181, v182
	s_add_u32 s7, s7, 1
	s_cbranch_vccnz .LfeAf_4
	s_sleep 1
	s_cmp_lt_u32 s7, 0x80000
	s_cbranch_scc1 .LfeAf_2
.LfeAf_4:
	s_mov_b64 exec, s[14:15]
.LfeAf_3:
	s_barrier
	s_cmp_gt_u32 s6, 3
	s_cbranch_scc1 .LfeAf_5
	s_add_u32 s12, s10, 0x1000
	s_addc_u32 s13, s11, 0
	global_load_dwordx2 v[130:131], v110, s[10:11] sc1
	global_load_dwordx2 v[132:133], v110, s[10:11] offset:2048 sc1
	global_load_dwordx2 v[134:135], v110, s[12:13] sc1
	global_load_dwordx2 v[136:137], v110, s[12:13] offset:2048 sc1
	s_waitcnt vmcnt(0)
	v_add_f32_e32 v130, v130, v132
	v_add_f32_e32 v131, v131, v133
	v_add_f32_e32 v134, v134, v136
	v_add_f32_e32 v135, v135, v137
	v_add_f32_e32 v130, v130, v134
	v_add_f32_e32 v131, v131, v135
	v_mul_f32_e32 v130, 0x3a800000, v130
	v_mul_f32_e32 v131, 0x3a800000, v131
	v_fma_f32 v131, -v130, v130, v131
	v_max_f32_e32 v131, 0, v131
	v_add_f32_e32 v131, 0x3727c5ac, v131
	v_rsq_f32_e32 v132, v131
	s_nop 0
	v_mul_f32_e32 v133, v131, v132
	v_mul_f32_e32 v133, v133, v132
	v_fmaak_f32 v133, -0.5, v133, 0x3fc00000
	v_mul_f32_e32 v131, v132, v133
	ds_write_b64 v183, v[130:131] offset:8192
.LfeAf_5:
	s_waitcnt lgkmcnt(0)
	s_barrier
	v_lshlrev_b32_e32 v108, 3, v158
	v_add_u32_e32 v108, 0x22000, v108
	ds_read_b64 v[112:113], v108
	ds_read_b64 v[200:201], v108 offset:128
	ds_read_b64 v[202:203], v108 offset:256
	ds_read_b64 v[204:205], v108 offset:384
	ds_read_b64 v[206:207], v108 offset:1024
	ds_read_b64 v[208:209], v108 offset:1152
	ds_read_b64 v[210:211], v108 offset:1280
	ds_read_b64 v[212:213], v108 offset:1408
	s_add_u32 s8, s48, 0x1000
	s_addc_u32 s9, s49, 0
	s_add_u32 s12, s84, 0x1000
	s_addc_u32 s13, s85, 0
	global_load_dwordx4 v[108:111], v249, s[8:9]
	global_load_dwordx4 v[130:133], v249, s[12:13]
	global_load_dwordx4 v[134:137], v249, s[8:9] offset:64
	global_load_dwordx4 v[180:183], v249, s[12:13] offset:64
	global_load_dwordx4 v[184:187], v249, s[8:9] offset:512
	global_load_dwordx4 v[192:195], v249, s[12:13] offset:512
	global_load_dwordx4 v[188:191], v249, s[8:9] offset:576
	global_load_dwordx4 v[196:199], v249, s[12:13] offset:576
	v_lshrrev_b32_e32 v236, 4, v222
	v_and_b32_e32 v236, 1, v236
	v_mul_u32_u24_e32 v236, 24, v236
	s_lshl_b32 s7, s4, 19
	s_add_u32 s16, s96, s7
	s_addc_u32 s17, s97, 0
	s_waitcnt vmcnt(0) lgkmcnt(0)
	v_pk_add_f32 v[138:139], v[138:139], v[112:113] op_sel_hi:[1,0] neg_lo:[0,1] neg_hi:[0,1]
	v_pk_add_f32 v[140:141], v[140:141], v[112:113] op_sel_hi:[1,0] neg_lo:[0,1] neg_hi:[0,1]
	v_pk_mul_f32 v[138:139], v[138:139], v[112:113] op_sel:[0,1] op_sel_hi:[1,1]
	v_pk_mul_f32 v[140:141], v[140:141], v[112:113] op_sel:[0,1] op_sel_hi:[1,1]
	v_pk_fma_f32 v[138:139], v[108:109], v[138:139], v[130:131]
	v_pk_fma_f32 v[140:141], v[110:111], v[140:141], v[132:133]
	s_nop 0
	global_store_dwordx4 v240, v[138:141], s[58:59]
	v_pk_add_f32 v[92:93], v[92:93], v[112:113] op_sel_hi:[1,0] neg_lo:[0,1] neg_hi:[0,1]
	v_pk_add_f32 v[94:95], v[94:95], v[112:113] op_sel_hi:[1,0] neg_lo:[0,1] neg_hi:[0,1]
	v_pk_mul_f32 v[92:93], v[92:93], v[112:113] op_sel:[0,1] op_sel_hi:[1,1]
	v_pk_mul_f32 v[94:95], v[94:95], v[112:113] op_sel:[0,1] op_sel_hi:[1,1]
	v_pk_fma_f32 v[92:93], v[134:135], v[92:93], v[180:181]
	v_pk_fma_f32 v[94:95], v[136:137], v[94:95], v[182:183]
	s_nop 0
	global_store_dwordx4 v240, v[92:95], s[58:59] offset:64
	v_pk_add_f32 v[60:61], v[60:61], v[112:113] op_sel_hi:[1,0] neg_lo:[0,1] neg_hi:[0,1]
	v_pk_add_f32 v[62:63], v[62:63], v[112:113] op_sel_hi:[1,0] neg_lo:[0,1] neg_hi:[0,1]
	v_pk_mul_f32 v[60:61], v[60:61], v[112:113] op_sel:[0,1] op_sel_hi:[1,1]
	v_pk_mul_f32 v[62:63], v[62:63], v[112:113] op_sel:[0,1] op_sel_hi:[1,1]
	v_pk_fma_f32 v[60:61], v[184:185], v[60:61], v[192:193]
	v_pk_fma_f32 v[62:63], v[186:187], v[62:63], v[194:195]
	s_nop 0
	global_store_dwordx4 v240, v[60:63], s[58:59] offset:512
	v_pk_add_f32 v[28:29], v[28:29], v[112:113] op_sel_hi:[1,0] neg_lo:[0,1] neg_hi:[0,1]
	v_pk_add_f32 v[30:31], v[30:31], v[112:113] op_sel_hi:[1,0] neg_lo:[0,1] neg_hi:[0,1]
	v_pk_mul_f32 v[28:29], v[28:29], v[112:113] op_sel:[0,1] op_sel_hi:[1,1]
	v_pk_mul_f32 v[30:31], v[30:31], v[112:113] op_sel:[0,1] op_sel_hi:[1,1]
	v_pk_fma_f32 v[28:29], v[188:189], v[28:29], v[196:197]
	v_pk_fma_f32 v[30:31], v[190:191], v[30:31], v[198:199]
	s_nop 0
	global_store_dwordx4 v240, v[28:31], s[58:59] offset:576
	v_pk_add_f32 v[126:127], v[126:127], v[200:201] op_sel_hi:[1,0] neg_lo:[0,1] neg_hi:[0,1]
	v_pk_add_f32 v[128:129], v[128:129], v[200:201] op_sel_hi:[1,0] neg_lo:[0,1] neg_hi:[0,1]
	v_pk_mul_f32 v[126:127], v[126:127], v[200:201] op_sel:[0,1] op_sel_hi:[1,1]
	v_pk_mul_f32 v[128:129], v[128:129], v[200:201] op_sel:[0,1] op_sel_hi:[1,1]
	v_pk_fma_f32 v[126:127], v[108:109], v[126:127], v[130:131]
	v_pk_fma_f32 v[128:129], v[110:111], v[128:129], v[132:133]
	s_nop 0
	global_store_dwordx4 v241, v[126:129], s[58:59]
	v_pk_add_f32 v[88:89], v[88:89], v[200:201] op_sel_hi:[1,0] neg_lo:[0,1] neg_hi:[0,1]
	v_pk_add_f32 v[90:91], v[90:91], v[200:201] op_sel_hi:[1,0] neg_lo:[0,1] neg_hi:[0,1]
	v_pk_mul_f32 v[88:89], v[88:89], v[200:201] op_sel:[0,1] op_sel_hi:[1,1]
	v_pk_mul_f32 v[90:91], v[90:91], v[200:201] op_sel:[0,1] op_sel_hi:[1,1]
	v_pk_fma_f32 v[88:89], v[134:135], v[88:89], v[180:181]
	v_pk_fma_f32 v[90:91], v[136:137], v[90:91], v[182:183]
	s_nop 0
	global_store_dwordx4 v241, v[88:91], s[58:59] offset:64
	v_pk_add_f32 v[56:57], v[56:57], v[200:201] op_sel_hi:[1,0] neg_lo:[0,1] neg_hi:[0,1]
	v_pk_add_f32 v[58:59], v[58:59], v[200:201] op_sel_hi:[1,0] neg_lo:[0,1] neg_hi:[0,1]
	v_pk_mul_f32 v[56:57], v[56:57], v[200:201] op_sel:[0,1] op_sel_hi:[1,1]
	v_pk_mul_f32 v[58:59], v[58:59], v[200:201] op_sel:[0,1] op_sel_hi:[1,1]
	v_pk_fma_f32 v[56:57], v[184:185], v[56:57], v[192:193]
	v_pk_fma_f32 v[58:59], v[186:187], v[58:59], v[194:195]
	s_nop 0
	global_store_dwordx4 v241, v[56:59], s[58:59] offset:512
	v_pk_add_f32 v[24:25], v[24:25], v[200:201] op_sel_hi:[1,0] neg_lo:[0,1] neg_hi:[0,1]
	v_pk_add_f32 v[26:27], v[26:27], v[200:201] op_sel_hi:[1,0] neg_lo:[0,1] neg_hi:[0,1]
	v_pk_mul_f32 v[24:25], v[24:25], v[200:201] op_sel:[0,1] op_sel_hi:[1,1]
	v_pk_mul_f32 v[26:27], v[26:27], v[200:201] op_sel:[0,1] op_sel_hi:[1,1]
	v_pk_fma_f32 v[24:25], v[188:189], v[24:25], v[196:197]
	v_pk_fma_f32 v[26:27], v[190:191], v[26:27], v[198:199]
	s_nop 0
	global_store_dwordx4 v241, v[24:27], s[58:59] offset:576
	v_pk_add_f32 v[122:123], v[122:123], v[202:203] op_sel_hi:[1,0] neg_lo:[0,1] neg_hi:[0,1]
	v_pk_add_f32 v[124:125], v[124:125], v[202:203] op_sel_hi:[1,0] neg_lo:[0,1] neg_hi:[0,1]
	v_pk_mul_f32 v[122:123], v[122:123], v[202:203] op_sel:[0,1] op_sel_hi:[1,1]
	v_pk_mul_f32 v[124:125], v[124:125], v[202:203] op_sel:[0,1] op_sel_hi:[1,1]
	v_pk_fma_f32 v[122:123], v[108:109], v[122:123], v[130:131]
	v_pk_fma_f32 v[124:125], v[110:111], v[124:125], v[132:133]
	s_nop 0
	global_store_dwordx4 v242, v[122:125], s[58:59]
	v_pk_add_f32 v[84:85], v[84:85], v[202:203] op_sel_hi:[1,0] neg_lo:[0,1] neg_hi:[0,1]
	v_pk_add_f32 v[86:87], v[86:87], v[202:203] op_sel_hi:[1,0] neg_lo:[0,1] neg_hi:[0,1]
	v_pk_mul_f32 v[84:85], v[84:85], v[202:203] op_sel:[0,1] op_sel_hi:[1,1]
	v_pk_mul_f32 v[86:87], v[86:87], v[202:203] op_sel:[0,1] op_sel_hi:[1,1]
	v_pk_fma_f32 v[84:85], v[134:135], v[84:85], v[180:181]
	v_pk_fma_f32 v[86:87], v[136:137], v[86:87], v[182:183]
	s_nop 0
	global_store_dwordx4 v242, v[84:87], s[58:59] offset:64
	v_pk_add_f32 v[52:53], v[52:53], v[202:203] op_sel_hi:[1,0] neg_lo:[0,1] neg_hi:[0,1]
	v_pk_add_f32 v[54:55], v[54:55], v[202:203] op_sel_hi:[1,0] neg_lo:[0,1] neg_hi:[0,1]
	v_pk_mul_f32 v[52:53], v[52:53], v[202:203] op_sel:[0,1] op_sel_hi:[1,1]
	v_pk_mul_f32 v[54:55], v[54:55], v[202:203] op_sel:[0,1] op_sel_hi:[1,1]
	v_pk_fma_f32 v[52:53], v[184:185], v[52:53], v[192:193]
	v_pk_fma_f32 v[54:55], v[186:187], v[54:55], v[194:195]
	s_nop 0
	global_store_dwordx4 v242, v[52:55], s[58:59] offset:512
	v_pk_add_f32 v[20:21], v[20:21], v[202:203] op_sel_hi:[1,0] neg_lo:[0,1] neg_hi:[0,1]
	v_pk_add_f32 v[22:23], v[22:23], v[202:203] op_sel_hi:[1,0] neg_lo:[0,1] neg_hi:[0,1]
	v_pk_mul_f32 v[20:21], v[20:21], v[202:203] op_sel:[0,1] op_sel_hi:[1,1]
	v_pk_mul_f32 v[22:23], v[22:23], v[202:203] op_sel:[0,1] op_sel_hi:[1,1]
	v_pk_fma_f32 v[20:21], v[188:189], v[20:21], v[196:197]
	v_pk_fma_f32 v[22:23], v[190:191], v[22:23], v[198:199]
	s_nop 0
	global_store_dwordx4 v242, v[20:23], s[58:59] offset:576
	v_pk_add_f32 v[118:119], v[118:119], v[204:205] op_sel_hi:[1,0] neg_lo:[0,1] neg_hi:[0,1]
	v_pk_add_f32 v[120:121], v[120:121], v[204:205] op_sel_hi:[1,0] neg_lo:[0,1] neg_hi:[0,1]
	v_pk_mul_f32 v[118:119], v[118:119], v[204:205] op_sel:[0,1] op_sel_hi:[1,1]
	v_pk_mul_f32 v[120:121], v[120:121], v[204:205] op_sel:[0,1] op_sel_hi:[1,1]
	v_pk_fma_f32 v[118:119], v[108:109], v[118:119], v[130:131]
	v_pk_fma_f32 v[120:121], v[110:111], v[120:121], v[132:133]
	s_nop 0
	global_store_dwordx4 v243, v[118:121], s[58:59]
	v_pk_add_f32 v[80:81], v[80:81], v[204:205] op_sel_hi:[1,0] neg_lo:[0,1] neg_hi:[0,1]
	v_pk_add_f32 v[82:83], v[82:83], v[204:205] op_sel_hi:[1,0] neg_lo:[0,1] neg_hi:[0,1]
	v_pk_mul_f32 v[80:81], v[80:81], v[204:205] op_sel:[0,1] op_sel_hi:[1,1]
	v_pk_mul_f32 v[82:83], v[82:83], v[204:205] op_sel:[0,1] op_sel_hi:[1,1]
	v_pk_fma_f32 v[80:81], v[134:135], v[80:81], v[180:181]
	v_pk_fma_f32 v[82:83], v[136:137], v[82:83], v[182:183]
	s_nop 0
	global_store_dwordx4 v243, v[80:83], s[58:59] offset:64
	v_pk_add_f32 v[48:49], v[48:49], v[204:205] op_sel_hi:[1,0] neg_lo:[0,1] neg_hi:[0,1]
	v_pk_add_f32 v[50:51], v[50:51], v[204:205] op_sel_hi:[1,0] neg_lo:[0,1] neg_hi:[0,1]
	v_pk_mul_f32 v[48:49], v[48:49], v[204:205] op_sel:[0,1] op_sel_hi:[1,1]
	v_pk_mul_f32 v[50:51], v[50:51], v[204:205] op_sel:[0,1] op_sel_hi:[1,1]
	v_pk_fma_f32 v[48:49], v[184:185], v[48:49], v[192:193]
	v_pk_fma_f32 v[50:51], v[186:187], v[50:51], v[194:195]
	s_nop 0
	global_store_dwordx4 v243, v[48:51], s[58:59] offset:512
	v_pk_add_f32 v[16:17], v[16:17], v[204:205] op_sel_hi:[1,0] neg_lo:[0,1] neg_hi:[0,1]
	v_pk_add_f32 v[18:19], v[18:19], v[204:205] op_sel_hi:[1,0] neg_lo:[0,1] neg_hi:[0,1]
	v_pk_mul_f32 v[16:17], v[16:17], v[204:205] op_sel:[0,1] op_sel_hi:[1,1]
	v_pk_mul_f32 v[18:19], v[18:19], v[204:205] op_sel:[0,1] op_sel_hi:[1,1]
	v_pk_fma_f32 v[16:17], v[188:189], v[16:17], v[196:197]
	v_pk_fma_f32 v[18:19], v[190:191], v[18:19], v[198:199]
	s_nop 0
	global_store_dwordx4 v243, v[16:19], s[58:59] offset:576
	v_pk_add_f32 v[114:115], v[114:115], v[206:207] op_sel_hi:[1,0] neg_lo:[0,1] neg_hi:[0,1]
	v_pk_add_f32 v[116:117], v[116:117], v[206:207] op_sel_hi:[1,0] neg_lo:[0,1] neg_hi:[0,1]
	v_pk_mul_f32 v[114:115], v[114:115], v[206:207] op_sel:[0,1] op_sel_hi:[1,1]
	v_pk_mul_f32 v[116:117], v[116:117], v[206:207] op_sel:[0,1] op_sel_hi:[1,1]
	v_pk_fma_f32 v[114:115], v[108:109], v[114:115], v[130:131]
	v_pk_fma_f32 v[116:117], v[110:111], v[116:117], v[132:133]
	s_nop 0
	global_store_dwordx4 v244, v[114:117], s[58:59]
	v_pk_add_f32 v[76:77], v[76:77], v[206:207] op_sel_hi:[1,0] neg_lo:[0,1] neg_hi:[0,1]
	v_pk_add_f32 v[78:79], v[78:79], v[206:207] op_sel_hi:[1,0] neg_lo:[0,1] neg_hi:[0,1]
	v_pk_mul_f32 v[76:77], v[76:77], v[206:207] op_sel:[0,1] op_sel_hi:[1,1]
	v_pk_mul_f32 v[78:79], v[78:79], v[206:207] op_sel:[0,1] op_sel_hi:[1,1]
	v_pk_fma_f32 v[76:77], v[134:135], v[76:77], v[180:181]
	v_pk_fma_f32 v[78:79], v[136:137], v[78:79], v[182:183]
	s_nop 0
	global_store_dwordx4 v244, v[76:79], s[58:59] offset:64
	v_pk_add_f32 v[44:45], v[44:45], v[206:207] op_sel_hi:[1,0] neg_lo:[0,1] neg_hi:[0,1]
	v_pk_add_f32 v[46:47], v[46:47], v[206:207] op_sel_hi:[1,0] neg_lo:[0,1] neg_hi:[0,1]
	v_pk_mul_f32 v[44:45], v[44:45], v[206:207] op_sel:[0,1] op_sel_hi:[1,1]
	v_pk_mul_f32 v[46:47], v[46:47], v[206:207] op_sel:[0,1] op_sel_hi:[1,1]
	v_pk_fma_f32 v[44:45], v[184:185], v[44:45], v[192:193]
	v_pk_fma_f32 v[46:47], v[186:187], v[46:47], v[194:195]
	s_nop 0
	global_store_dwordx4 v244, v[44:47], s[58:59] offset:512
	v_pk_add_f32 v[12:13], v[12:13], v[206:207] op_sel_hi:[1,0] neg_lo:[0,1] neg_hi:[0,1]
	v_pk_add_f32 v[14:15], v[14:15], v[206:207] op_sel_hi:[1,0] neg_lo:[0,1] neg_hi:[0,1]
	v_pk_mul_f32 v[12:13], v[12:13], v[206:207] op_sel:[0,1] op_sel_hi:[1,1]
	v_pk_mul_f32 v[14:15], v[14:15], v[206:207] op_sel:[0,1] op_sel_hi:[1,1]
	v_pk_fma_f32 v[12:13], v[188:189], v[12:13], v[196:197]
	v_pk_fma_f32 v[14:15], v[190:191], v[14:15], v[198:199]
	s_nop 0
	global_store_dwordx4 v244, v[12:15], s[58:59] offset:576
	v_pk_add_f32 v[104:105], v[104:105], v[208:209] op_sel_hi:[1,0] neg_lo:[0,1] neg_hi:[0,1]
	v_pk_add_f32 v[106:107], v[106:107], v[208:209] op_sel_hi:[1,0] neg_lo:[0,1] neg_hi:[0,1]
	v_pk_mul_f32 v[104:105], v[104:105], v[208:209] op_sel:[0,1] op_sel_hi:[1,1]
	v_pk_mul_f32 v[106:107], v[106:107], v[208:209] op_sel:[0,1] op_sel_hi:[1,1]
	v_pk_fma_f32 v[104:105], v[108:109], v[104:105], v[130:131]
	v_pk_fma_f32 v[106:107], v[110:111], v[106:107], v[132:133]
	s_nop 0
	global_store_dwordx4 v245, v[104:107], s[58:59]
	v_pk_add_f32 v[72:73], v[72:73], v[208:209] op_sel_hi:[1,0] neg_lo:[0,1] neg_hi:[0,1]
	v_pk_add_f32 v[74:75], v[74:75], v[208:209] op_sel_hi:[1,0] neg_lo:[0,1] neg_hi:[0,1]
	v_pk_mul_f32 v[72:73], v[72:73], v[208:209] op_sel:[0,1] op_sel_hi:[1,1]
	v_pk_mul_f32 v[74:75], v[74:75], v[208:209] op_sel:[0,1] op_sel_hi:[1,1]
	v_pk_fma_f32 v[72:73], v[134:135], v[72:73], v[180:181]
	v_pk_fma_f32 v[74:75], v[136:137], v[74:75], v[182:183]
	s_nop 0
	global_store_dwordx4 v245, v[72:75], s[58:59] offset:64
	v_pk_add_f32 v[40:41], v[40:41], v[208:209] op_sel_hi:[1,0] neg_lo:[0,1] neg_hi:[0,1]
	v_pk_add_f32 v[42:43], v[42:43], v[208:209] op_sel_hi:[1,0] neg_lo:[0,1] neg_hi:[0,1]
	v_pk_mul_f32 v[40:41], v[40:41], v[208:209] op_sel:[0,1] op_sel_hi:[1,1]
	v_pk_mul_f32 v[42:43], v[42:43], v[208:209] op_sel:[0,1] op_sel_hi:[1,1]
	v_pk_fma_f32 v[40:41], v[184:185], v[40:41], v[192:193]
	v_pk_fma_f32 v[42:43], v[186:187], v[42:43], v[194:195]
	s_nop 0
	global_store_dwordx4 v245, v[40:43], s[58:59] offset:512
	v_pk_add_f32 v[8:9], v[8:9], v[208:209] op_sel_hi:[1,0] neg_lo:[0,1] neg_hi:[0,1]
	v_pk_add_f32 v[10:11], v[10:11], v[208:209] op_sel_hi:[1,0] neg_lo:[0,1] neg_hi:[0,1]
	v_pk_mul_f32 v[8:9], v[8:9], v[208:209] op_sel:[0,1] op_sel_hi:[1,1]
	v_pk_mul_f32 v[10:11], v[10:11], v[208:209] op_sel:[0,1] op_sel_hi:[1,1]
	v_pk_fma_f32 v[8:9], v[188:189], v[8:9], v[196:197]
	v_pk_fma_f32 v[10:11], v[190:191], v[10:11], v[198:199]
	s_nop 0
	global_store_dwordx4 v245, v[8:11], s[58:59] offset:576
	v_pk_add_f32 v[100:101], v[100:101], v[210:211] op_sel_hi:[1,0] neg_lo:[0,1] neg_hi:[0,1]
	v_pk_add_f32 v[102:103], v[102:103], v[210:211] op_sel_hi:[1,0] neg_lo:[0,1] neg_hi:[0,1]
	v_pk_mul_f32 v[100:101], v[100:101], v[210:211] op_sel:[0,1] op_sel_hi:[1,1]
	v_pk_mul_f32 v[102:103], v[102:103], v[210:211] op_sel:[0,1] op_sel_hi:[1,1]
	v_pk_fma_f32 v[100:101], v[108:109], v[100:101], v[130:131]
	v_pk_fma_f32 v[102:103], v[110:111], v[102:103], v[132:133]
	s_nop 0
	global_store_dwordx4 v246, v[100:103], s[58:59]
	v_pk_add_f32 v[68:69], v[68:69], v[210:211] op_sel_hi:[1,0] neg_lo:[0,1] neg_hi:[0,1]
	v_pk_add_f32 v[70:71], v[70:71], v[210:211] op_sel_hi:[1,0] neg_lo:[0,1] neg_hi:[0,1]
	v_pk_mul_f32 v[68:69], v[68:69], v[210:211] op_sel:[0,1] op_sel_hi:[1,1]
	v_pk_mul_f32 v[70:71], v[70:71], v[210:211] op_sel:[0,1] op_sel_hi:[1,1]
	v_pk_fma_f32 v[68:69], v[134:135], v[68:69], v[180:181]
	v_pk_fma_f32 v[70:71], v[136:137], v[70:71], v[182:183]
	s_nop 0
	global_store_dwordx4 v246, v[68:71], s[58:59] offset:64
	v_pk_add_f32 v[36:37], v[36:37], v[210:211] op_sel_hi:[1,0] neg_lo:[0,1] neg_hi:[0,1]
	v_pk_add_f32 v[38:39], v[38:39], v[210:211] op_sel_hi:[1,0] neg_lo:[0,1] neg_hi:[0,1]
	v_pk_mul_f32 v[36:37], v[36:37], v[210:211] op_sel:[0,1] op_sel_hi:[1,1]
	v_pk_mul_f32 v[38:39], v[38:39], v[210:211] op_sel:[0,1] op_sel_hi:[1,1]
	v_pk_fma_f32 v[36:37], v[184:185], v[36:37], v[192:193]
	v_pk_fma_f32 v[38:39], v[186:187], v[38:39], v[194:195]
	s_nop 0
	global_store_dwordx4 v246, v[36:39], s[58:59] offset:512
	v_pk_add_f32 v[4:5], v[4:5], v[210:211] op_sel_hi:[1,0] neg_lo:[0,1] neg_hi:[0,1]
	v_pk_add_f32 v[6:7], v[6:7], v[210:211] op_sel_hi:[1,0] neg_lo:[0,1] neg_hi:[0,1]
	v_pk_mul_f32 v[4:5], v[4:5], v[210:211] op_sel:[0,1] op_sel_hi:[1,1]
	v_pk_mul_f32 v[6:7], v[6:7], v[210:211] op_sel:[0,1] op_sel_hi:[1,1]
	v_pk_fma_f32 v[4:5], v[188:189], v[4:5], v[196:197]
	v_pk_fma_f32 v[6:7], v[190:191], v[6:7], v[198:199]
	s_nop 0
	global_store_dwordx4 v246, v[4:7], s[58:59] offset:576
	v_pk_add_f32 v[96:97], v[96:97], v[212:213] op_sel_hi:[1,0] neg_lo:[0,1] neg_hi:[0,1]
	v_pk_add_f32 v[98:99], v[98:99], v[212:213] op_sel_hi:[1,0] neg_lo:[0,1] neg_hi:[0,1]
	v_pk_mul_f32 v[96:97], v[96:97], v[212:213] op_sel:[0,1] op_sel_hi:[1,1]
	v_pk_mul_f32 v[98:99], v[98:99], v[212:213] op_sel:[0,1] op_sel_hi:[1,1]
	v_pk_fma_f32 v[96:97], v[108:109], v[96:97], v[130:131]
	v_pk_fma_f32 v[98:99], v[110:111], v[98:99], v[132:133]
	s_nop 0
	global_store_dwordx4 v247, v[96:99], s[58:59]
	v_pk_add_f32 v[64:65], v[64:65], v[212:213] op_sel_hi:[1,0] neg_lo:[0,1] neg_hi:[0,1]
	v_pk_add_f32 v[66:67], v[66:67], v[212:213] op_sel_hi:[1,0] neg_lo:[0,1] neg_hi:[0,1]
	v_pk_mul_f32 v[64:65], v[64:65], v[212:213] op_sel:[0,1] op_sel_hi:[1,1]
	v_pk_mul_f32 v[66:67], v[66:67], v[212:213] op_sel:[0,1] op_sel_hi:[1,1]
	v_pk_fma_f32 v[64:65], v[134:135], v[64:65], v[180:181]
	v_pk_fma_f32 v[66:67], v[136:137], v[66:67], v[182:183]
	s_nop 0
	global_store_dwordx4 v247, v[64:67], s[58:59] offset:64
	v_pk_add_f32 v[32:33], v[32:33], v[212:213] op_sel_hi:[1,0] neg_lo:[0,1] neg_hi:[0,1]
	v_pk_add_f32 v[34:35], v[34:35], v[212:213] op_sel_hi:[1,0] neg_lo:[0,1] neg_hi:[0,1]
	v_pk_mul_f32 v[32:33], v[32:33], v[212:213] op_sel:[0,1] op_sel_hi:[1,1]
	v_pk_mul_f32 v[34:35], v[34:35], v[212:213] op_sel:[0,1] op_sel_hi:[1,1]
	v_pk_fma_f32 v[32:33], v[184:185], v[32:33], v[192:193]
	v_pk_fma_f32 v[34:35], v[186:187], v[34:35], v[194:195]
	s_nop 0
	global_store_dwordx4 v247, v[32:35], s[58:59] offset:512
	v_pk_add_f32 v[0:1], v[0:1], v[212:213] op_sel_hi:[1,0] neg_lo:[0,1] neg_hi:[0,1]
	v_pk_add_f32 v[2:3], v[2:3], v[212:213] op_sel_hi:[1,0] neg_lo:[0,1] neg_hi:[0,1]
	v_pk_mul_f32 v[0:1], v[0:1], v[212:213] op_sel:[0,1] op_sel_hi:[1,1]
	v_pk_mul_f32 v[2:3], v[2:3], v[212:213] op_sel:[0,1] op_sel_hi:[1,1]
	v_pk_fma_f32 v[0:1], v[188:189], v[0:1], v[196:197]
	v_pk_fma_f32 v[2:3], v[190:191], v[2:3], v[198:199]
	s_nop 0
	global_store_dwordx4 v247, v[0:3], s[58:59] offset:576
	v_readlane_b32 s4, v252, 0
	v_readlane_b32 s5, v252, 1
	v_readlane_b32 s6, v252, 2
	v_readlane_b32 s7, v252, 3
	v_readlane_b32 s8, v252, 4
	v_readlane_b32 s9, v252, 5
	v_readlane_b32 s10, v252, 6
	v_readlane_b32 s11, v252, 7
	v_readlane_b32 s12, v252, 8
	v_readlane_b32 s13, v252, 9
	v_readlane_b32 s14, v252, 10
	v_readlane_b32 s15, v252, 11
	v_readlane_b32 s16, v252, 12
	v_readlane_b32 s17, v252, 13
	s_mov_b64 s[4:5], s[8:9]
	v_readlane_b32 s18, v252, 14
	v_readlane_b32 s19, v252, 15
	s_mov_b64 s[6:7], s[10:11]
	s_mov_b64 s[8:9], s[12:13]
	s_mov_b64 s[12:13], s[16:17]
	s_mov_b64 s[14:15], s[18:19]
	s_and_b64 vcc, exec, s[38:39]
	s_mov_b64 s[38:39], -1
	s_branch .Lepi_A_join

.LBB0_307:
	v_readlane_b32 s28, v250, 53
	s_nop 3
	s_cmp_eq_u32 s28, 3
	s_cbranch_scc1 .Ltramp_exit
	s_waitcnt vmcnt(0)
	s_barrier
	s_mov_b64 s[38:39], exec
	v_readlane_b32 s28, v252, 16
	v_readlane_b32 s29, v252, 17
	v_readlane_b32 s52, v252, 0
	s_and_b64 s[28:29], s[38:39], s[28:29]
	v_readlane_b32 s60, v252, 8
	v_readlane_b32 s61, v252, 9
	v_readlane_b32 s64, v252, 12
	v_readlane_b32 s65, v252, 13
	v_readlane_b32 s66, v252, 14
	v_readlane_b32 s67, v252, 15
	v_readlane_b32 s53, v252, 1
	v_readlane_b32 s54, v252, 2
	v_readlane_b32 s55, v252, 3
	v_readlane_b32 s56, v252, 4
	v_readlane_b32 s57, v252, 5
	v_readlane_b32 s58, v252, 6
	v_readlane_b32 s59, v252, 7
	v_readlane_b32 s62, v252, 10
	v_readlane_b32 s63, v252, 11
	s_mov_b64 exec, s[28:29]
	s_cbranch_execz .LBB0_359
	v_readlane_b32 s2, v250, 41
	s_waitcnt vmcnt(0) expcnt(0) lgkmcnt(0)
	buffer_inv sc1
	s_waitcnt vmcnt(0)
	v_mov_b32_e32 v0, s2
	ds_read_b32 v2, v0
	v_readlane_b32 s2, v250, 42
	s_waitcnt lgkmcnt(0)
	v_cmp_ne_u32_e32 vcc, 0, v2
	v_mov_b32_e32 v0, s2
	ds_read_b32 v0, v0
	s_cbranch_vccnz .LBB0_323
	s_mov_b32 s2, 1
	s_branch .LBB0_311

.LBB0_383:
	s_and_b64 vcc, exec, s[38:39]
	s_cbranch_vccz .LBB0_454
	v_mov_b32_e32 v0, v222
	s_nop 0
	v_readfirstlane_b32 s2, v0
	s_ashr_i32 s2, s2, 6
	s_add_i32 s38, s2, s95
	s_add_i32 s38, s38, 0x8000
	s_cmpk_gt_i32 s38, 0x7fff
	s_cbranch_scc1 .LBB0_410
	v_lshlrev_b32_e32 v0, 4, v0
	v_and_b32_e32 v142, 0x3f0, v0
	v_readlane_b32 s4, v251, 3
	v_readlane_b32 s6, v251, 5
	v_readlane_b32 s5, v251, 4
	v_readlane_b32 s7, v251, 6
	v_or_b32_e32 v12, 0x400, v142
	v_or_b32_e32 v20, 0x800, v142
	v_or_b32_e32 v28, 0xc00, v142
	v_and_b32_e32 v32, 64, v227
	global_load_dwordx4 v[0:3], v142, s[4:5]
	global_load_dwordx4 v[4:7], v142, s[6:7]
	global_load_dwordx4 v[8:11], v12, s[4:5]
	s_nop 0
	global_load_dwordx4 v[12:15], v12, s[6:7]
	s_nop 0
	global_load_dwordx4 v[16:19], v20, s[4:5]
	s_nop 0
	global_load_dwordx4 v[20:23], v20, s[6:7]
	s_nop 0
	global_load_dwordx4 v[24:27], v28, s[4:5]
	s_nop 0
	global_load_dwordx4 v[28:31], v28, s[6:7]
	v_add_u32_e32 v32, 64, v32
	v_xor_b32_e32 v33, 1, v227
	v_cmp_lt_i32_e32 vcc, v33, v32
	v_lshl_add_u64 v[96:97], s[64:65], 0, v[142:143]
	s_nop 0
	v_cndmask_b32_e32 v33, v227, v33, vcc
	v_lshlrev_b32_e32 v114, 2, v33
	v_xor_b32_e32 v33, 2, v227
	v_cmp_lt_i32_e32 vcc, v33, v32
	s_nop 1
	v_cndmask_b32_e32 v33, v227, v33, vcc
	v_lshlrev_b32_e32 v115, 2, v33
	v_xor_b32_e32 v33, 4, v227
	v_cmp_lt_i32_e32 vcc, v33, v32
	s_nop 1
	v_cndmask_b32_e32 v33, v227, v33, vcc
	v_lshlrev_b32_e32 v116, 2, v33
	v_xor_b32_e32 v33, 8, v227
	v_cmp_lt_i32_e32 vcc, v33, v32
	s_nop 1
	v_cndmask_b32_e32 v33, v227, v33, vcc
	v_lshlrev_b32_e32 v117, 2, v33
	v_xor_b32_e32 v33, 16, v227
	v_cmp_lt_i32_e32 vcc, v33, v32
	s_nop 1
	v_cndmask_b32_e32 v33, v227, v33, vcc
	v_lshlrev_b32_e32 v118, 2, v33
	v_xor_b32_e32 v33, 32, v227
	v_cmp_lt_i32_e32 vcc, v33, v32
	s_nop 1
	v_cndmask_b32_e32 v32, v227, v33, vcc
	v_lshlrev_b32_e32 v119, 2, v32
	s_branch .LBB0_387

.LBB0_502:
	s_add_u32 s28, s40, 0xfffc0080
	s_addc_u32 s29, s41, -1
	s_add_i32 s69, 0, 0x10000
	s_cmp_eq_u32 s61, 12
	s_cselect_b32 s57, s37, s29
	s_cselect_b32 s56, s49, s28
	s_cselect_b32 s55, s47, s60
	s_cselect_b32 s54, s58, s59
	s_add_i32 s70, 0, 0x14000
	v_add_u32_e32 v168, s69, v157
	v_add_u32_e32 v184, s70, v157
	ds_read_b128 v[138:141], v168
	ds_read_b128 v[160:163], v168 offset:1024
	ds_read_b128 v[164:167], v168 offset:2048
	ds_read_b128 v[168:171], v168 offset:3072
	ds_read_b128 v[172:175], v184
	ds_read_b128 v[176:179], v184 offset:1024
	ds_read_b128 v[180:183], v184 offset:2048
	ds_read_b128 v[184:187], v184 offset:3072
	v_lshl_add_u64 v[220:221], s[40:41], 0, v[134:135]
	s_add_i32 m0, s62, 0xc000
	ds_read_b128 v[188:191], v159
	ds_read_b128 v[192:195], v159 offset:1024
	ds_read_b128 v[196:199], v159 offset:2048
	ds_read_b128 v[200:203], v159 offset:3072
	ds_read_b128 v[204:207], v159 offset:4096
	ds_read_b128 v[208:211], v159 offset:5120
	ds_read_b128 v[212:215], v159 offset:6144
	ds_read_b128 v[216:219], v159 offset:7168
	global_load_lds_dwordx4 v[220:221], off
	v_lshl_add_u64 v[220:221], s[40:41], 0, v[136:137]
	s_add_i32 m0, s62, 0xe000
	s_nop 0
	global_load_lds_dwordx4 v[220:221], off
	s_waitcnt vmcnt(8)
	s_waitcnt lgkmcnt(0)
	s_barrier
	s_setprio 1
	s_waitcnt lgkmcnt(0)
	v_mfma_f32_16x16x32_bf16 v[124:127], v[138:141], v[188:191], v[124:127]
	v_mfma_f32_16x16x32_bf16 v[120:123], v[164:167], v[188:191], v[120:123]
	v_mfma_f32_16x16x32_bf16 v[108:111], v[138:141], v[196:199], v[108:111]
	v_mfma_f32_16x16x32_bf16 v[104:107], v[164:167], v[196:199], v[104:107]
	v_mfma_f32_16x16x32_bf16 v[92:95], v[138:141], v[204:207], v[92:95]
	v_mfma_f32_16x16x32_bf16 v[88:91], v[164:167], v[204:207], v[88:91]
	v_mfma_f32_16x16x32_bf16 v[76:79], v[138:141], v[212:215], v[76:79]
	v_mfma_f32_16x16x32_bf16 v[72:75], v[164:167], v[212:215], v[72:75]
	v_mfma_f32_16x16x32_bf16 v[124:127], v[160:163], v[192:195], v[124:127]
	v_mfma_f32_16x16x32_bf16 v[120:123], v[168:171], v[192:195], v[120:123]
	v_mfma_f32_16x16x32_bf16 v[108:111], v[160:163], v[200:203], v[108:111]
	v_mfma_f32_16x16x32_bf16 v[104:107], v[168:171], v[200:203], v[104:107]
	v_mfma_f32_16x16x32_bf16 v[92:95], v[160:163], v[208:211], v[92:95]
	v_mfma_f32_16x16x32_bf16 v[88:91], v[168:171], v[208:211], v[88:91]
	v_mfma_f32_16x16x32_bf16 v[76:79], v[160:163], v[216:219], v[76:79]
	v_mfma_f32_16x16x32_bf16 v[72:75], v[168:171], v[216:219], v[72:75]
	v_mfma_f32_16x16x32_bf16 v[116:119], v[172:175], v[188:191], v[116:119]
	v_mfma_f32_16x16x32_bf16 v[112:115], v[180:183], v[188:191], v[112:115]
	v_mfma_f32_16x16x32_bf16 v[100:103], v[172:175], v[196:199], v[100:103]
	v_mfma_f32_16x16x32_bf16 v[96:99], v[180:183], v[196:199], v[96:99]
	v_mfma_f32_16x16x32_bf16 v[84:87], v[172:175], v[204:207], v[84:87]
	v_mfma_f32_16x16x32_bf16 v[80:83], v[180:183], v[204:207], v[80:83]
	v_mfma_f32_16x16x32_bf16 v[68:71], v[172:175], v[212:215], v[68:71]
	v_mfma_f32_16x16x32_bf16 v[64:67], v[180:183], v[212:215], v[64:67]
	v_mfma_f32_16x16x32_bf16 v[116:119], v[176:179], v[192:195], v[116:119]
	v_mfma_f32_16x16x32_bf16 v[112:115], v[184:187], v[192:195], v[112:115]
	v_mfma_f32_16x16x32_bf16 v[100:103], v[176:179], v[200:203], v[100:103]
	v_mfma_f32_16x16x32_bf16 v[96:99], v[184:187], v[200:203], v[96:99]
	v_mfma_f32_16x16x32_bf16 v[84:87], v[176:179], v[208:211], v[84:87]
	v_mfma_f32_16x16x32_bf16 v[80:83], v[184:187], v[208:211], v[80:83]
	v_mfma_f32_16x16x32_bf16 v[68:71], v[176:179], v[216:219], v[68:71]
	v_mfma_f32_16x16x32_bf16 v[64:67], v[184:187], v[216:219], v[64:67]
	s_setprio 0
	s_barrier
	s_add_i32 s28, s69, s20
	v_lshl_add_u64 v[220:221], s[54:55], 0, v[142:143]
	s_mov_b32 m0, s28
	ds_read_b128 v[188:191], v159 offset:16384
	ds_read_b128 v[192:195], v159 offset:17408
	ds_read_b128 v[196:199], v159 offset:18432
	ds_read_b128 v[200:203], v159 offset:19456
	ds_read_b128 v[204:207], v159 offset:20480
	ds_read_b128 v[208:211], v159 offset:21504
	ds_read_b128 v[212:215], v159 offset:22528
	ds_read_b128 v[216:219], v159 offset:23552
	global_load_lds_dwordx4 v[220:221], off
	s_add_i32 m0, s28, 0x2000
	s_add_u32 s28, s54, 0x40000
	v_lshl_add_u64 v[230:231], s[54:55], 0, v[128:129]
	s_addc_u32 s29, s55, 0
	s_add_i32 s69, s70, s20
	global_load_lds_dwordx4 v[230:231], off
	v_lshl_add_u64 v[232:233], s[28:29], 0, v[142:143]
	s_mov_b32 m0, s69
	v_lshl_add_u64 v[234:235], s[56:57], 0, v[130:131]
	global_load_lds_dwordx4 v[232:233], off
	v_lshl_add_u64 v[232:233], s[28:29], 0, v[128:129]
	s_add_i32 m0, s69, 0x2000
	s_nop 0
	global_load_lds_dwordx4 v[232:233], off
	v_lshl_add_u64 v[232:233], s[56:57], 0, v[132:133]
	s_mov_b32 m0, s62
	s_nop 0
	global_load_lds_dwordx4 v[232:233], off
	s_mov_b32 m0, s63
	s_nop 0
	global_load_lds_dwordx4 v[234:235], off
	s_waitcnt vmcnt(8)
	s_waitcnt lgkmcnt(0)
	s_barrier
	s_setprio 1
	s_waitcnt lgkmcnt(0)
	v_mfma_f32_16x16x32_bf16 v[60:63], v[138:141], v[188:191], v[60:63]
	v_mfma_f32_16x16x32_bf16 v[56:59], v[164:167], v[188:191], v[56:59]
	v_mfma_f32_16x16x32_bf16 v[44:47], v[138:141], v[196:199], v[44:47]
	v_mfma_f32_16x16x32_bf16 v[40:43], v[164:167], v[196:199], v[40:43]
	v_mfma_f32_16x16x32_bf16 v[28:31], v[138:141], v[204:207], v[28:31]
	v_mfma_f32_16x16x32_bf16 v[24:27], v[164:167], v[204:207], v[24:27]
	v_mfma_f32_16x16x32_bf16 v[12:15], v[138:141], v[212:215], v[12:15]
	v_mfma_f32_16x16x32_bf16 v[8:11], v[164:167], v[212:215], v[8:11]
	v_mfma_f32_16x16x32_bf16 v[60:63], v[160:163], v[192:195], v[60:63]
	v_mfma_f32_16x16x32_bf16 v[56:59], v[168:171], v[192:195], v[56:59]
	v_mfma_f32_16x16x32_bf16 v[44:47], v[160:163], v[200:203], v[44:47]
	v_mfma_f32_16x16x32_bf16 v[40:43], v[168:171], v[200:203], v[40:43]
	v_mfma_f32_16x16x32_bf16 v[28:31], v[160:163], v[208:211], v[28:31]
	v_mfma_f32_16x16x32_bf16 v[24:27], v[168:171], v[208:211], v[24:27]
	v_mfma_f32_16x16x32_bf16 v[12:15], v[160:163], v[216:219], v[12:15]
	v_mfma_f32_16x16x32_bf16 v[8:11], v[168:171], v[216:219], v[8:11]
	v_mfma_f32_16x16x32_bf16 v[52:55], v[172:175], v[188:191], v[52:55]
	v_mfma_f32_16x16x32_bf16 v[48:51], v[180:183], v[188:191], v[48:51]
	v_mfma_f32_16x16x32_bf16 v[36:39], v[172:175], v[196:199], v[36:39]
	v_mfma_f32_16x16x32_bf16 v[32:35], v[180:183], v[196:199], v[32:35]
	v_mfma_f32_16x16x32_bf16 v[20:23], v[172:175], v[204:207], v[20:23]
	v_mfma_f32_16x16x32_bf16 v[16:19], v[180:183], v[204:207], v[16:19]
	v_mfma_f32_16x16x32_bf16 v[4:7], v[172:175], v[212:215], v[4:7]
	v_mfma_f32_16x16x32_bf16 v[0:3], v[180:183], v[212:215], v[0:3]
	v_mfma_f32_16x16x32_bf16 v[52:55], v[176:179], v[192:195], v[52:55]
	v_mfma_f32_16x16x32_bf16 v[48:51], v[184:187], v[192:195], v[48:51]
	v_mfma_f32_16x16x32_bf16 v[36:39], v[176:179], v[200:203], v[36:39]
	v_mfma_f32_16x16x32_bf16 v[32:35], v[184:187], v[200:203], v[32:35]
	v_mfma_f32_16x16x32_bf16 v[20:23], v[176:179], v[208:211], v[20:23]
	v_mfma_f32_16x16x32_bf16 v[16:19], v[184:187], v[208:211], v[16:19]
	v_mfma_f32_16x16x32_bf16 v[4:7], v[176:179], v[216:219], v[4:7]
	v_mfma_f32_16x16x32_bf16 v[0:3], v[184:187], v[216:219], v[0:3]
	s_setprio 0
	s_barrier
	s_add_i32 s69, 0, 0x18000
	s_add_i32 s70, 0, 0x1c000
	v_add_u32_e32 v168, s69, v157
	v_add_u32_e32 v184, s70, v157
	ds_read_b128 v[138:141], v168
	ds_read_b128 v[160:163], v168 offset:1024
	ds_read_b128 v[164:167], v168 offset:2048
	ds_read_b128 v[168:171], v168 offset:3072
	ds_read_b128 v[172:175], v184
	ds_read_b128 v[176:179], v184 offset:1024
	ds_read_b128 v[180:183], v184 offset:2048
	ds_read_b128 v[184:187], v184 offset:3072
	s_add_u32 s28, s56, 0x40000
	s_addc_u32 s29, s57, 0
	s_mov_b32 m0, s64
	v_lshl_add_u64 v[236:237], s[28:29], 0, v[132:133]
	ds_read_b128 v[188:191], v159 offset:32768
	ds_read_b128 v[192:195], v159 offset:33792
	ds_read_b128 v[196:199], v159 offset:34816
	ds_read_b128 v[200:203], v159 offset:35840
	ds_read_b128 v[204:207], v159 offset:36864
	ds_read_b128 v[208:211], v159 offset:37888
	ds_read_b128 v[212:215], v159 offset:38912
	ds_read_b128 v[216:219], v159 offset:39936
	global_load_lds_dwordx4 v[236:237], off
	v_lshl_add_u64 v[236:237], s[28:29], 0, v[130:131]
	s_mov_b32 m0, s65
	s_nop 0
	global_load_lds_dwordx4 v[236:237], off
	s_waitcnt vmcnt(8)
	s_waitcnt lgkmcnt(0)
	s_barrier
	s_setprio 1
	s_waitcnt lgkmcnt(0)
	v_mfma_f32_16x16x32_bf16 v[124:127], v[138:141], v[188:191], v[124:127]
	v_mfma_f32_16x16x32_bf16 v[120:123], v[164:167], v[188:191], v[120:123]
	v_mfma_f32_16x16x32_bf16 v[108:111], v[138:141], v[196:199], v[108:111]
	v_mfma_f32_16x16x32_bf16 v[104:107], v[164:167], v[196:199], v[104:107]
	v_mfma_f32_16x16x32_bf16 v[92:95], v[138:141], v[204:207], v[92:95]
	v_mfma_f32_16x16x32_bf16 v[88:91], v[164:167], v[204:207], v[88:91]
	v_mfma_f32_16x16x32_bf16 v[76:79], v[138:141], v[212:215], v[76:79]
	v_mfma_f32_16x16x32_bf16 v[72:75], v[164:167], v[212:215], v[72:75]
	v_mfma_f32_16x16x32_bf16 v[124:127], v[160:163], v[192:195], v[124:127]
	v_mfma_f32_16x16x32_bf16 v[120:123], v[168:171], v[192:195], v[120:123]
	v_mfma_f32_16x16x32_bf16 v[108:111], v[160:163], v[200:203], v[108:111]
	v_mfma_f32_16x16x32_bf16 v[104:107], v[168:171], v[200:203], v[104:107]
	v_mfma_f32_16x16x32_bf16 v[92:95], v[160:163], v[208:211], v[92:95]
	v_mfma_f32_16x16x32_bf16 v[88:91], v[168:171], v[208:211], v[88:91]
	v_mfma_f32_16x16x32_bf16 v[76:79], v[160:163], v[216:219], v[76:79]
	v_mfma_f32_16x16x32_bf16 v[72:75], v[168:171], v[216:219], v[72:75]
	v_mfma_f32_16x16x32_bf16 v[116:119], v[172:175], v[188:191], v[116:119]
	v_mfma_f32_16x16x32_bf16 v[112:115], v[180:183], v[188:191], v[112:115]
	v_mfma_f32_16x16x32_bf16 v[100:103], v[172:175], v[196:199], v[100:103]
	v_mfma_f32_16x16x32_bf16 v[96:99], v[180:183], v[196:199], v[96:99]
	v_mfma_f32_16x16x32_bf16 v[84:87], v[172:175], v[204:207], v[84:87]
	v_mfma_f32_16x16x32_bf16 v[80:83], v[180:183], v[204:207], v[80:83]
	v_mfma_f32_16x16x32_bf16 v[68:71], v[172:175], v[212:215], v[68:71]
	v_mfma_f32_16x16x32_bf16 v[64:67], v[180:183], v[212:215], v[64:67]
	v_mfma_f32_16x16x32_bf16 v[116:119], v[176:179], v[192:195], v[116:119]
	v_mfma_f32_16x16x32_bf16 v[112:115], v[184:187], v[192:195], v[112:115]
	v_mfma_f32_16x16x32_bf16 v[100:103], v[176:179], v[200:203], v[100:103]
	v_mfma_f32_16x16x32_bf16 v[96:99], v[184:187], v[200:203], v[96:99]
	v_mfma_f32_16x16x32_bf16 v[84:87], v[176:179], v[208:211], v[84:87]
	v_mfma_f32_16x16x32_bf16 v[80:83], v[184:187], v[208:211], v[80:83]
	v_mfma_f32_16x16x32_bf16 v[68:71], v[176:179], v[216:219], v[68:71]
	v_mfma_f32_16x16x32_bf16 v[64:67], v[184:187], v[216:219], v[64:67]
	s_setprio 0
	s_barrier
	s_add_i32 s28, s69, s20
	v_lshl_add_u64 v[220:221], v[220:221], 0, s[22:23]
	s_mov_b32 m0, s28
	ds_read_b128 v[188:191], v159 offset:49152
	ds_read_b128 v[192:195], v159 offset:50176
	ds_read_b128 v[196:199], v159 offset:51200
	ds_read_b128 v[200:203], v159 offset:52224
	ds_read_b128 v[204:207], v159 offset:53248
	ds_read_b128 v[208:211], v159 offset:54272
	ds_read_b128 v[212:215], v159 offset:55296
	ds_read_b128 v[216:219], v159 offset:56320
	global_load_lds_dwordx4 v[220:221], off
	s_add_i32 m0, s28, 0x2000
	s_add_u32 s28, s54, 0x40080
	v_lshl_add_u64 v[220:221], v[230:231], 0, s[22:23]
	s_addc_u32 s29, s55, 0
	s_add_i32 s54, s70, s20
	global_load_lds_dwordx4 v[220:221], off
	v_lshl_add_u64 v[220:221], s[28:29], 0, v[142:143]
	s_mov_b32 m0, s54
	s_nop 0
	global_load_lds_dwordx4 v[220:221], off
	v_lshl_add_u64 v[220:221], s[28:29], 0, v[128:129]
	s_add_i32 m0, s54, 0x2000
	s_nop 0
	global_load_lds_dwordx4 v[220:221], off
	v_lshl_add_u64 v[220:221], v[232:233], 0, s[22:23]
	s_mov_b32 m0, s66
	s_nop 0
	global_load_lds_dwordx4 v[220:221], off
	v_lshl_add_u64 v[220:221], v[234:235], 0, s[22:23]
	s_mov_b32 m0, s67
	s_nop 0
	global_load_lds_dwordx4 v[220:221], off
	s_waitcnt vmcnt(8)
	s_waitcnt lgkmcnt(0)
	s_barrier
	s_setprio 1
	s_waitcnt lgkmcnt(0)
	v_mfma_f32_16x16x32_bf16 v[60:63], v[138:141], v[188:191], v[60:63]
	v_mfma_f32_16x16x32_bf16 v[56:59], v[164:167], v[188:191], v[56:59]
	v_mfma_f32_16x16x32_bf16 v[44:47], v[138:141], v[196:199], v[44:47]
	v_mfma_f32_16x16x32_bf16 v[40:43], v[164:167], v[196:199], v[40:43]
	v_mfma_f32_16x16x32_bf16 v[28:31], v[138:141], v[204:207], v[28:31]
	v_mfma_f32_16x16x32_bf16 v[24:27], v[164:167], v[204:207], v[24:27]
	v_mfma_f32_16x16x32_bf16 v[12:15], v[138:141], v[212:215], v[12:15]
	v_mfma_f32_16x16x32_bf16 v[8:11], v[164:167], v[212:215], v[8:11]
	v_mfma_f32_16x16x32_bf16 v[60:63], v[160:163], v[192:195], v[60:63]
	v_mfma_f32_16x16x32_bf16 v[56:59], v[168:171], v[192:195], v[56:59]
	v_mfma_f32_16x16x32_bf16 v[44:47], v[160:163], v[200:203], v[44:47]
	v_mfma_f32_16x16x32_bf16 v[40:43], v[168:171], v[200:203], v[40:43]
	v_mfma_f32_16x16x32_bf16 v[28:31], v[160:163], v[208:211], v[28:31]
	v_mfma_f32_16x16x32_bf16 v[24:27], v[168:171], v[208:211], v[24:27]
	v_mfma_f32_16x16x32_bf16 v[12:15], v[160:163], v[216:219], v[12:15]
	v_mfma_f32_16x16x32_bf16 v[8:11], v[168:171], v[216:219], v[8:11]
	v_mfma_f32_16x16x32_bf16 v[52:55], v[172:175], v[188:191], v[52:55]
	v_mfma_f32_16x16x32_bf16 v[48:51], v[180:183], v[188:191], v[48:51]
	v_mfma_f32_16x16x32_bf16 v[36:39], v[172:175], v[196:199], v[36:39]
	v_mfma_f32_16x16x32_bf16 v[32:35], v[180:183], v[196:199], v[32:35]
	v_mfma_f32_16x16x32_bf16 v[20:23], v[172:175], v[204:207], v[20:23]
	v_mfma_f32_16x16x32_bf16 v[16:19], v[180:183], v[204:207], v[16:19]
	v_mfma_f32_16x16x32_bf16 v[4:7], v[172:175], v[212:215], v[4:7]
	v_mfma_f32_16x16x32_bf16 v[0:3], v[180:183], v[212:215], v[0:3]
	v_mfma_f32_16x16x32_bf16 v[52:55], v[176:179], v[192:195], v[52:55]
	v_mfma_f32_16x16x32_bf16 v[48:51], v[184:187], v[192:195], v[48:51]
	v_mfma_f32_16x16x32_bf16 v[36:39], v[176:179], v[200:203], v[36:39]
	v_mfma_f32_16x16x32_bf16 v[32:35], v[184:187], v[200:203], v[32:35]
	v_mfma_f32_16x16x32_bf16 v[20:23], v[176:179], v[208:211], v[20:23]
	v_mfma_f32_16x16x32_bf16 v[16:19], v[184:187], v[208:211], v[16:19]
	v_mfma_f32_16x16x32_bf16 v[4:7], v[176:179], v[216:219], v[4:7]
	v_mfma_f32_16x16x32_bf16 v[0:3], v[184:187], v[216:219], v[0:3]
	s_setprio 0
	s_barrier
	s_add_i32 s61, s61, 2
	s_add_u32 s40, s40, 0x100
	s_addc_u32 s41, s41, 0
	s_add_u32 s59, s59, 0x100
	s_addc_u32 s60, s60, 0
	s_cmp_gt_u32 s61, 13
	s_cbranch_scc0 .LBB0_502
	s_and_b64 vcc, exec, s[44:45]
	s_cbranch_vccz .LBB0_505
	s_barrier

.Ltramp_156:
	s_branch .LBB0_156

.Ltramp_exit:
	s_endpgm
.LBB0_592:
	s_xor_b64 s[28:29], s[50:51], -1
	s_and_b64 s[36:37], exec, s[48:49]
	s_or_b64 s[44:45], s[36:37], s[44:45]
	s_andn2_b64 s[36:37], s[46:47], exec
	s_and_b64 s[28:29], s[28:29], exec
	s_or_b64 s[46:47], s[36:37], s[28:29]
	s_andn2_b64 exec, exec, s[44:45]
	s_cbranch_execz .LBB0_599

.LBB0_895:
	s_add_u32 s28, s52, 0xfffc0080
	s_addc_u32 s29, s53, -1
	s_add_i32 s69, 0, 0x10000
	s_cmp_eq_u32 s68, 12
	s_cselect_b32 s57, s47, s29
	s_cselect_b32 s56, s64, s28
	v_add_u32_e32 v140, s69, v167
	s_cselect_b32 s55, s45, s67
	s_cselect_b32 s54, s65, s66
	s_add_i32 s70, 0, 0x14000
	ds_read_b128 v[156:159], v140
	ds_read_b128 v[160:163], v140 offset:1024
	ds_read_b128 v[172:175], v140 offset:2048
	ds_read_b128 v[176:179], v140 offset:3072
	v_add_u32_e32 v140, s70, v167
	ds_read_b128 v[180:183], v140
	ds_read_b128 v[184:187], v140 offset:1024
	ds_read_b128 v[188:191], v140 offset:2048
	ds_read_b128 v[192:195], v140 offset:3072
	v_lshl_add_u64 v[140:141], s[52:53], 0, v[136:137]
	s_add_i32 m0, s20, 0xc000
	ds_read_b128 v[196:199], v170
	ds_read_b128 v[200:203], v170 offset:1024
	ds_read_b128 v[204:207], v170 offset:2048
	ds_read_b128 v[208:211], v170 offset:3072
	ds_read_b128 v[212:215], v170 offset:4096
	ds_read_b128 v[216:219], v170 offset:5120
	ds_read_b128 v[230:233], v170 offset:6144
	ds_read_b128 v[234:237], v170 offset:7168
	global_load_lds_dwordx4 v[140:141], off
	v_lshl_add_u64 v[140:141], s[52:53], 0, v[138:139]
	s_add_i32 m0, s20, 0xe000
	s_nop 0
	global_load_lds_dwordx4 v[140:141], off
	s_waitcnt vmcnt(8)
	s_waitcnt lgkmcnt(0)
	s_barrier
	s_setprio 1
	s_waitcnt lgkmcnt(0)
	v_mfma_f32_16x16x32_bf16 v[124:127], v[156:159], v[196:199], v[124:127]
	v_mfma_f32_16x16x32_bf16 v[120:123], v[172:175], v[196:199], v[120:123]
	v_mfma_f32_16x16x32_bf16 v[108:111], v[156:159], v[204:207], v[108:111]
	v_mfma_f32_16x16x32_bf16 v[104:107], v[172:175], v[204:207], v[104:107]
	v_mfma_f32_16x16x32_bf16 v[92:95], v[156:159], v[212:215], v[92:95]
	v_mfma_f32_16x16x32_bf16 v[88:91], v[172:175], v[212:215], v[88:91]
	v_mfma_f32_16x16x32_bf16 v[76:79], v[156:159], v[230:233], v[76:79]
	v_mfma_f32_16x16x32_bf16 v[72:75], v[172:175], v[230:233], v[72:75]
	v_mfma_f32_16x16x32_bf16 v[124:127], v[160:163], v[200:203], v[124:127]
	v_mfma_f32_16x16x32_bf16 v[120:123], v[176:179], v[200:203], v[120:123]
	v_mfma_f32_16x16x32_bf16 v[108:111], v[160:163], v[208:211], v[108:111]
	v_mfma_f32_16x16x32_bf16 v[104:107], v[176:179], v[208:211], v[104:107]
	v_mfma_f32_16x16x32_bf16 v[92:95], v[160:163], v[216:219], v[92:95]
	v_mfma_f32_16x16x32_bf16 v[88:91], v[176:179], v[216:219], v[88:91]
	v_mfma_f32_16x16x32_bf16 v[76:79], v[160:163], v[234:237], v[76:79]
	v_mfma_f32_16x16x32_bf16 v[72:75], v[176:179], v[234:237], v[72:75]
	v_mfma_f32_16x16x32_bf16 v[116:119], v[180:183], v[196:199], v[116:119]
	v_mfma_f32_16x16x32_bf16 v[112:115], v[188:191], v[196:199], v[112:115]
	v_mfma_f32_16x16x32_bf16 v[100:103], v[180:183], v[204:207], v[100:103]
	v_mfma_f32_16x16x32_bf16 v[96:99], v[188:191], v[204:207], v[96:99]
	v_mfma_f32_16x16x32_bf16 v[84:87], v[180:183], v[212:215], v[84:87]
	v_mfma_f32_16x16x32_bf16 v[80:83], v[188:191], v[212:215], v[80:83]
	v_mfma_f32_16x16x32_bf16 v[68:71], v[180:183], v[230:233], v[68:71]
	v_mfma_f32_16x16x32_bf16 v[64:67], v[188:191], v[230:233], v[64:67]
	v_mfma_f32_16x16x32_bf16 v[116:119], v[184:187], v[200:203], v[116:119]
	v_mfma_f32_16x16x32_bf16 v[112:115], v[192:195], v[200:203], v[112:115]
	v_mfma_f32_16x16x32_bf16 v[100:103], v[184:187], v[208:211], v[100:103]
	v_mfma_f32_16x16x32_bf16 v[96:99], v[192:195], v[208:211], v[96:99]
	v_mfma_f32_16x16x32_bf16 v[84:87], v[184:187], v[216:219], v[84:87]
	v_mfma_f32_16x16x32_bf16 v[80:83], v[192:195], v[216:219], v[80:83]
	v_mfma_f32_16x16x32_bf16 v[68:71], v[184:187], v[234:237], v[68:71]
	v_mfma_f32_16x16x32_bf16 v[64:67], v[192:195], v[234:237], v[64:67]
	s_setprio 0
	s_barrier
	s_add_i32 s28, s69, s2
	v_lshl_add_u64 v[140:141], s[54:55], 0, v[132:133]
	s_mov_b32 m0, s28
	ds_read_b128 v[196:199], v170 offset:16384
	ds_read_b128 v[200:203], v170 offset:17408
	ds_read_b128 v[204:207], v170 offset:18432
	ds_read_b128 v[208:211], v170 offset:19456
	ds_read_b128 v[212:215], v170 offset:20480
	ds_read_b128 v[216:219], v170 offset:21504
	ds_read_b128 v[230:233], v170 offset:22528
	ds_read_b128 v[234:237], v170 offset:23552
	global_load_lds_dwordx4 v[140:141], off
	s_add_i32 m0, s28, 0x2000
	s_add_u32 s28, s54, 0x40000
	v_lshl_add_u64 v[164:165], s[54:55], 0, v[128:129]
	s_addc_u32 s29, s55, 0
	s_add_i32 s69, s70, s2
	global_load_lds_dwordx4 v[164:165], off
	v_lshl_add_u64 v[220:221], s[28:29], 0, v[132:133]
	s_mov_b32 m0, s69
	v_lshl_add_u64 v[238:239], s[56:57], 0, v[130:131]
	global_load_lds_dwordx4 v[220:221], off
	v_lshl_add_u64 v[220:221], s[28:29], 0, v[128:129]
	s_add_i32 m0, s69, 0x2000
	s_nop 0
	global_load_lds_dwordx4 v[220:221], off
	v_lshl_add_u64 v[220:221], s[56:57], 0, v[134:135]
	s_mov_b32 m0, s20
	s_nop 0
	global_load_lds_dwordx4 v[220:221], off
	s_mov_b32 m0, s36
	s_nop 0
	global_load_lds_dwordx4 v[238:239], off
	s_waitcnt vmcnt(8)
	s_waitcnt lgkmcnt(0)
	s_barrier
	s_setprio 1
	s_waitcnt lgkmcnt(0)
	v_mfma_f32_16x16x32_bf16 v[60:63], v[156:159], v[196:199], v[60:63]
	v_mfma_f32_16x16x32_bf16 v[56:59], v[172:175], v[196:199], v[56:59]
	v_mfma_f32_16x16x32_bf16 v[48:51], v[156:159], v[204:207], v[48:51]
	v_mfma_f32_16x16x32_bf16 v[40:43], v[172:175], v[204:207], v[40:43]
	v_mfma_f32_16x16x32_bf16 v[32:35], v[156:159], v[212:215], v[32:35]
	v_mfma_f32_16x16x32_bf16 v[24:27], v[172:175], v[212:215], v[24:27]
	v_mfma_f32_16x16x32_bf16 v[16:19], v[156:159], v[230:233], v[16:19]
	v_mfma_f32_16x16x32_bf16 v[8:11], v[172:175], v[230:233], v[8:11]
	v_mfma_f32_16x16x32_bf16 v[60:63], v[160:163], v[200:203], v[60:63]
	v_mfma_f32_16x16x32_bf16 v[56:59], v[176:179], v[200:203], v[56:59]
	v_mfma_f32_16x16x32_bf16 v[48:51], v[160:163], v[208:211], v[48:51]
	v_mfma_f32_16x16x32_bf16 v[40:43], v[176:179], v[208:211], v[40:43]
	v_mfma_f32_16x16x32_bf16 v[32:35], v[160:163], v[216:219], v[32:35]
	v_mfma_f32_16x16x32_bf16 v[24:27], v[176:179], v[216:219], v[24:27]
	v_mfma_f32_16x16x32_bf16 v[16:19], v[160:163], v[234:237], v[16:19]
	v_mfma_f32_16x16x32_bf16 v[8:11], v[176:179], v[234:237], v[8:11]
	v_mfma_f32_16x16x32_bf16 v[52:55], v[180:183], v[196:199], v[52:55]
	v_mfma_f32_16x16x32_bf16 v[44:47], v[188:191], v[196:199], v[44:47]
	v_mfma_f32_16x16x32_bf16 v[36:39], v[180:183], v[204:207], v[36:39]
	v_mfma_f32_16x16x32_bf16 v[28:31], v[188:191], v[204:207], v[28:31]
	v_mfma_f32_16x16x32_bf16 v[20:23], v[180:183], v[212:215], v[20:23]
	v_mfma_f32_16x16x32_bf16 v[12:15], v[188:191], v[212:215], v[12:15]
	v_mfma_f32_16x16x32_bf16 v[4:7], v[180:183], v[230:233], v[4:7]
	v_mfma_f32_16x16x32_bf16 v[0:3], v[188:191], v[230:233], v[0:3]
	v_mfma_f32_16x16x32_bf16 v[52:55], v[184:187], v[200:203], v[52:55]
	v_mfma_f32_16x16x32_bf16 v[44:47], v[192:195], v[200:203], v[44:47]
	v_mfma_f32_16x16x32_bf16 v[36:39], v[184:187], v[208:211], v[36:39]
	v_mfma_f32_16x16x32_bf16 v[28:31], v[192:195], v[208:211], v[28:31]
	v_mfma_f32_16x16x32_bf16 v[20:23], v[184:187], v[216:219], v[20:23]
	v_mfma_f32_16x16x32_bf16 v[12:15], v[192:195], v[216:219], v[12:15]
	v_mfma_f32_16x16x32_bf16 v[4:7], v[184:187], v[234:237], v[4:7]
	v_mfma_f32_16x16x32_bf16 v[0:3], v[192:195], v[234:237], v[0:3]
	s_setprio 0
	s_barrier
	s_add_i32 s69, 0, 0x18000
	v_add_u32_e32 v142, s69, v167
	s_add_i32 s70, 0, 0x1c000
	ds_read_b128 v[156:159], v142
	ds_read_b128 v[160:163], v142 offset:1024
	ds_read_b128 v[172:175], v142 offset:2048
	ds_read_b128 v[176:179], v142 offset:3072
	v_add_u32_e32 v142, s70, v167
	ds_read_b128 v[180:183], v142
	ds_read_b128 v[184:187], v142 offset:1024
	ds_read_b128 v[188:191], v142 offset:2048
	ds_read_b128 v[192:195], v142 offset:3072
	s_add_u32 s28, s56, 0x40000
	s_addc_u32 s29, s57, 0
	s_mov_b32 m0, s37
	v_lshl_add_u64 v[240:241], s[28:29], 0, v[134:135]
	ds_read_b128 v[196:199], v170 offset:32768
	ds_read_b128 v[200:203], v170 offset:33792
	ds_read_b128 v[204:207], v170 offset:34816
	ds_read_b128 v[208:211], v170 offset:35840
	ds_read_b128 v[212:215], v170 offset:36864
	ds_read_b128 v[216:219], v170 offset:37888
	ds_read_b128 v[230:233], v170 offset:38912
	ds_read_b128 v[234:237], v170 offset:39936
	global_load_lds_dwordx4 v[240:241], off
	v_lshl_add_u64 v[240:241], s[28:29], 0, v[130:131]
	s_mov_b32 m0, s58
	s_nop 0
	global_load_lds_dwordx4 v[240:241], off
	s_waitcnt vmcnt(8)
	s_waitcnt lgkmcnt(0)
	s_barrier
	s_setprio 1
	s_waitcnt lgkmcnt(0)
	v_mfma_f32_16x16x32_bf16 v[124:127], v[156:159], v[196:199], v[124:127]
	v_mfma_f32_16x16x32_bf16 v[120:123], v[172:175], v[196:199], v[120:123]
	v_mfma_f32_16x16x32_bf16 v[108:111], v[156:159], v[204:207], v[108:111]
	v_mfma_f32_16x16x32_bf16 v[104:107], v[172:175], v[204:207], v[104:107]
	v_mfma_f32_16x16x32_bf16 v[92:95], v[156:159], v[212:215], v[92:95]
	v_mfma_f32_16x16x32_bf16 v[88:91], v[172:175], v[212:215], v[88:91]
	v_mfma_f32_16x16x32_bf16 v[76:79], v[156:159], v[230:233], v[76:79]
	v_mfma_f32_16x16x32_bf16 v[72:75], v[172:175], v[230:233], v[72:75]
	v_mfma_f32_16x16x32_bf16 v[124:127], v[160:163], v[200:203], v[124:127]
	v_mfma_f32_16x16x32_bf16 v[120:123], v[176:179], v[200:203], v[120:123]
	v_mfma_f32_16x16x32_bf16 v[108:111], v[160:163], v[208:211], v[108:111]
	v_mfma_f32_16x16x32_bf16 v[104:107], v[176:179], v[208:211], v[104:107]
	v_mfma_f32_16x16x32_bf16 v[92:95], v[160:163], v[216:219], v[92:95]
	v_mfma_f32_16x16x32_bf16 v[88:91], v[176:179], v[216:219], v[88:91]
	v_mfma_f32_16x16x32_bf16 v[76:79], v[160:163], v[234:237], v[76:79]
	v_mfma_f32_16x16x32_bf16 v[72:75], v[176:179], v[234:237], v[72:75]
	v_mfma_f32_16x16x32_bf16 v[116:119], v[180:183], v[196:199], v[116:119]
	v_mfma_f32_16x16x32_bf16 v[112:115], v[188:191], v[196:199], v[112:115]
	v_mfma_f32_16x16x32_bf16 v[100:103], v[180:183], v[204:207], v[100:103]
	v_mfma_f32_16x16x32_bf16 v[96:99], v[188:191], v[204:207], v[96:99]
	v_mfma_f32_16x16x32_bf16 v[84:87], v[180:183], v[212:215], v[84:87]
	v_mfma_f32_16x16x32_bf16 v[80:83], v[188:191], v[212:215], v[80:83]
	v_mfma_f32_16x16x32_bf16 v[68:71], v[180:183], v[230:233], v[68:71]
	v_mfma_f32_16x16x32_bf16 v[64:67], v[188:191], v[230:233], v[64:67]
	v_mfma_f32_16x16x32_bf16 v[116:119], v[184:187], v[200:203], v[116:119]
	v_mfma_f32_16x16x32_bf16 v[112:115], v[192:195], v[200:203], v[112:115]
	v_mfma_f32_16x16x32_bf16 v[100:103], v[184:187], v[208:211], v[100:103]
	v_mfma_f32_16x16x32_bf16 v[96:99], v[192:195], v[208:211], v[96:99]
	v_mfma_f32_16x16x32_bf16 v[84:87], v[184:187], v[216:219], v[84:87]
	v_mfma_f32_16x16x32_bf16 v[80:83], v[192:195], v[216:219], v[80:83]
	v_mfma_f32_16x16x32_bf16 v[68:71], v[184:187], v[234:237], v[68:71]
	v_mfma_f32_16x16x32_bf16 v[64:67], v[192:195], v[234:237], v[64:67]
	s_setprio 0
	s_barrier
	s_add_i32 s28, s69, s2
	v_lshl_add_u64 v[140:141], v[140:141], 0, s[22:23]
	s_mov_b32 m0, s28
	ds_read_b128 v[196:199], v170 offset:49152
	ds_read_b128 v[200:203], v170 offset:50176
	ds_read_b128 v[204:207], v170 offset:51200
	ds_read_b128 v[208:211], v170 offset:52224
	ds_read_b128 v[212:215], v170 offset:53248
	ds_read_b128 v[216:219], v170 offset:54272
	ds_read_b128 v[230:233], v170 offset:55296
	ds_read_b128 v[234:237], v170 offset:56320
	global_load_lds_dwordx4 v[140:141], off
	s_add_i32 m0, s28, 0x2000
	s_add_u32 s28, s54, 0x40080
	v_lshl_add_u64 v[140:141], v[164:165], 0, s[22:23]
	s_addc_u32 s29, s55, 0
	s_add_i32 s54, s70, s2
	global_load_lds_dwordx4 v[140:141], off
	v_lshl_add_u64 v[140:141], s[28:29], 0, v[132:133]
	s_mov_b32 m0, s54
	s_nop 0
	global_load_lds_dwordx4 v[140:141], off
	v_lshl_add_u64 v[140:141], s[28:29], 0, v[128:129]
	s_add_i32 m0, s54, 0x2000
	s_nop 0
	global_load_lds_dwordx4 v[140:141], off
	v_lshl_add_u64 v[140:141], v[220:221], 0, s[22:23]
	s_mov_b32 m0, s59
	s_nop 0
	global_load_lds_dwordx4 v[140:141], off
	v_lshl_add_u64 v[140:141], v[238:239], 0, s[22:23]
	s_mov_b32 m0, s60
	s_nop 0
	global_load_lds_dwordx4 v[140:141], off
	s_waitcnt vmcnt(8)
	s_waitcnt lgkmcnt(0)
	s_barrier
	s_setprio 1
	s_waitcnt lgkmcnt(0)
	v_mfma_f32_16x16x32_bf16 v[60:63], v[156:159], v[196:199], v[60:63]
	v_mfma_f32_16x16x32_bf16 v[56:59], v[172:175], v[196:199], v[56:59]
	v_mfma_f32_16x16x32_bf16 v[48:51], v[156:159], v[204:207], v[48:51]
	v_mfma_f32_16x16x32_bf16 v[40:43], v[172:175], v[204:207], v[40:43]
	v_mfma_f32_16x16x32_bf16 v[32:35], v[156:159], v[212:215], v[32:35]
	v_mfma_f32_16x16x32_bf16 v[24:27], v[172:175], v[212:215], v[24:27]
	v_mfma_f32_16x16x32_bf16 v[16:19], v[156:159], v[230:233], v[16:19]
	v_mfma_f32_16x16x32_bf16 v[8:11], v[172:175], v[230:233], v[8:11]
	v_mfma_f32_16x16x32_bf16 v[60:63], v[160:163], v[200:203], v[60:63]
	v_mfma_f32_16x16x32_bf16 v[56:59], v[176:179], v[200:203], v[56:59]
	v_mfma_f32_16x16x32_bf16 v[48:51], v[160:163], v[208:211], v[48:51]
	v_mfma_f32_16x16x32_bf16 v[40:43], v[176:179], v[208:211], v[40:43]
	v_mfma_f32_16x16x32_bf16 v[32:35], v[160:163], v[216:219], v[32:35]
	v_mfma_f32_16x16x32_bf16 v[24:27], v[176:179], v[216:219], v[24:27]
	v_mfma_f32_16x16x32_bf16 v[16:19], v[160:163], v[234:237], v[16:19]
	v_mfma_f32_16x16x32_bf16 v[8:11], v[176:179], v[234:237], v[8:11]
	v_mfma_f32_16x16x32_bf16 v[52:55], v[180:183], v[196:199], v[52:55]
	v_mfma_f32_16x16x32_bf16 v[44:47], v[188:191], v[196:199], v[44:47]
	v_mfma_f32_16x16x32_bf16 v[36:39], v[180:183], v[204:207], v[36:39]
	v_mfma_f32_16x16x32_bf16 v[28:31], v[188:191], v[204:207], v[28:31]
	v_mfma_f32_16x16x32_bf16 v[20:23], v[180:183], v[212:215], v[20:23]
	v_mfma_f32_16x16x32_bf16 v[12:15], v[188:191], v[212:215], v[12:15]
	v_mfma_f32_16x16x32_bf16 v[4:7], v[180:183], v[230:233], v[4:7]
	v_mfma_f32_16x16x32_bf16 v[0:3], v[188:191], v[230:233], v[0:3]
	v_mfma_f32_16x16x32_bf16 v[52:55], v[184:187], v[200:203], v[52:55]
	v_mfma_f32_16x16x32_bf16 v[44:47], v[192:195], v[200:203], v[44:47]
	v_mfma_f32_16x16x32_bf16 v[36:39], v[184:187], v[208:211], v[36:39]
	v_mfma_f32_16x16x32_bf16 v[28:31], v[192:195], v[208:211], v[28:31]
	v_mfma_f32_16x16x32_bf16 v[20:23], v[184:187], v[216:219], v[20:23]
	v_mfma_f32_16x16x32_bf16 v[12:15], v[192:195], v[216:219], v[12:15]
	v_mfma_f32_16x16x32_bf16 v[4:7], v[184:187], v[234:237], v[4:7]
	v_mfma_f32_16x16x32_bf16 v[0:3], v[192:195], v[234:237], v[0:3]
	s_setprio 0
	s_barrier
	s_add_i32 s68, s68, 2
	s_add_u32 s52, s52, 0x100
	s_addc_u32 s53, s53, 0
	s_add_u32 s66, s66, 0x100
	s_addc_u32 s67, s67, 0
	s_cmp_gt_u32 s68, 13
	s_cbranch_scc0 .LBB0_895
	s_and_b64 vcc, exec, s[42:43]
	s_cbranch_vccz .LBB0_898
	s_barrier

.LBB0_1083:
	s_add_u32 s64, s62, 0x100
	s_addc_u32 s65, s63, 0
	s_add_i32 s28, 0, 0x10000
	s_cmp_eq_u32 s79, 12
	s_cselect_b32 s69, s55, s65
	s_cselect_b32 s68, s61, s64
	s_cselect_b32 s67, s53, s78
	s_cselect_b32 s66, s76, s77
	s_add_i32 s80, 0, 0x14000
	v_add_u32_e32 v178, s28, v198
	v_add_u32_e32 v194, s80, v198
	ds_read_b128 v[124:127], v178
	ds_read_b128 v[128:131], v178 offset:1024
	ds_read_b128 v[174:177], v178 offset:2048
	ds_read_b128 v[178:181], v178 offset:3072
	ds_read_b128 v[182:185], v194
	ds_read_b128 v[186:189], v194 offset:1024
	ds_read_b128 v[190:193], v194 offset:2048
	ds_read_b128 v[194:197], v194 offset:3072
	v_lshl_add_u64 v[220:221], s[62:63], 0, v[170:171]
	s_add_i32 m0, s20, 0xc000
	ds_read_b128 v[200:203], v199
	ds_read_b128 v[204:207], v199 offset:1024
	ds_read_b128 v[208:211], v199 offset:2048
	ds_read_b128 v[212:215], v199 offset:3072
	ds_read_b128 v[216:219], v199 offset:4096
	ds_read_b128 v[230:233], v199 offset:5120
	ds_read_b128 v[234:237], v199 offset:6144
	ds_read_b128 v[238:241], v199 offset:7168
	global_load_lds_dwordx4 v[220:221], off
	v_lshl_add_u64 v[220:221], s[62:63], 0, v[172:173]
	s_add_i32 m0, s20, 0xe000
	s_nop 0
	global_load_lds_dwordx4 v[220:221], off
	s_waitcnt vmcnt(8)
	s_waitcnt lgkmcnt(0)
	s_barrier
	s_setprio 1
	s_waitcnt lgkmcnt(0)
	v_mfma_f32_16x16x32_bf16 v[132:135], v[124:127], v[200:203], v[132:135]
	v_mfma_f32_16x16x32_bf16 v[96:99], v[174:177], v[200:203], v[96:99]
	v_mfma_f32_16x16x32_bf16 v[120:123], v[124:127], v[208:211], v[120:123]
	v_mfma_f32_16x16x32_bf16 v[88:91], v[174:177], v[208:211], v[88:91]
	v_mfma_f32_16x16x32_bf16 v[116:119], v[124:127], v[216:219], v[116:119]
	v_mfma_f32_16x16x32_bf16 v[84:87], v[174:177], v[216:219], v[84:87]
	v_mfma_f32_16x16x32_bf16 v[112:115], v[124:127], v[234:237], v[112:115]
	v_mfma_f32_16x16x32_bf16 v[80:83], v[174:177], v[234:237], v[80:83]
	v_mfma_f32_16x16x32_bf16 v[132:135], v[128:131], v[204:207], v[132:135]
	v_mfma_f32_16x16x32_bf16 v[96:99], v[178:181], v[204:207], v[96:99]
	v_mfma_f32_16x16x32_bf16 v[120:123], v[128:131], v[212:215], v[120:123]
	v_mfma_f32_16x16x32_bf16 v[88:91], v[178:181], v[212:215], v[88:91]
	v_mfma_f32_16x16x32_bf16 v[116:119], v[128:131], v[230:233], v[116:119]
	v_mfma_f32_16x16x32_bf16 v[84:87], v[178:181], v[230:233], v[84:87]
	v_mfma_f32_16x16x32_bf16 v[112:115], v[128:131], v[238:241], v[112:115]
	v_mfma_f32_16x16x32_bf16 v[80:83], v[178:181], v[238:241], v[80:83]
	v_mfma_f32_16x16x32_bf16 v[64:67], v[182:185], v[200:203], v[64:67]
	v_mfma_f32_16x16x32_bf16 v[32:35], v[190:193], v[200:203], v[32:35]
	v_mfma_f32_16x16x32_bf16 v[56:59], v[182:185], v[208:211], v[56:59]
	v_mfma_f32_16x16x32_bf16 v[24:27], v[190:193], v[208:211], v[24:27]
	v_mfma_f32_16x16x32_bf16 v[52:55], v[182:185], v[216:219], v[52:55]
	v_mfma_f32_16x16x32_bf16 v[20:23], v[190:193], v[216:219], v[20:23]
	v_mfma_f32_16x16x32_bf16 v[48:51], v[182:185], v[234:237], v[48:51]
	v_mfma_f32_16x16x32_bf16 v[16:19], v[190:193], v[234:237], v[16:19]
	v_mfma_f32_16x16x32_bf16 v[64:67], v[186:189], v[204:207], v[64:67]
	v_mfma_f32_16x16x32_bf16 v[32:35], v[194:197], v[204:207], v[32:35]
	v_mfma_f32_16x16x32_bf16 v[56:59], v[186:189], v[212:215], v[56:59]
	v_mfma_f32_16x16x32_bf16 v[24:27], v[194:197], v[212:215], v[24:27]
	v_mfma_f32_16x16x32_bf16 v[52:55], v[186:189], v[230:233], v[52:55]
	v_mfma_f32_16x16x32_bf16 v[20:23], v[194:197], v[230:233], v[20:23]
	v_mfma_f32_16x16x32_bf16 v[48:51], v[186:189], v[238:241], v[48:51]
	v_mfma_f32_16x16x32_bf16 v[16:19], v[194:197], v[238:241], v[16:19]
	s_setprio 0
	s_barrier
	s_add_i32 s28, s28, s2
	v_lshl_add_u64 v[220:221], s[66:67], 0, v[142:143]
	s_mov_b32 m0, s28
	ds_read_b128 v[200:203], v199 offset:16384
	ds_read_b128 v[204:207], v199 offset:17408
	ds_read_b128 v[208:211], v199 offset:18432
	ds_read_b128 v[212:215], v199 offset:19456
	ds_read_b128 v[216:219], v199 offset:20480
	ds_read_b128 v[230:233], v199 offset:21504
	ds_read_b128 v[234:237], v199 offset:22528
	ds_read_b128 v[238:241], v199 offset:23552
	global_load_lds_dwordx4 v[220:221], off
	s_add_i32 m0, s28, 0x2000
	s_add_u32 s28, s66, 0x40000
	v_lshl_add_u64 v[242:243], s[66:67], 0, v[136:137]
	s_addc_u32 s29, s67, 0
	s_add_i32 s62, s80, s2
	global_load_lds_dwordx4 v[242:243], off
	v_lshl_add_u64 v[244:245], s[28:29], 0, v[142:143]
	s_mov_b32 m0, s62
	v_lshl_add_u64 v[246:247], s[68:69], 0, v[136:137]
	global_load_lds_dwordx4 v[244:245], off
	v_lshl_add_u64 v[244:245], s[28:29], 0, v[136:137]
	s_add_i32 m0, s62, 0x2000
	s_nop 0
	global_load_lds_dwordx4 v[244:245], off
	v_lshl_add_u64 v[244:245], s[68:69], 0, v[142:143]
	s_mov_b32 m0, s20
	s_nop 0
	global_load_lds_dwordx4 v[244:245], off
	s_mov_b32 m0, s39
	s_nop 0
	global_load_lds_dwordx4 v[246:247], off
	s_waitcnt vmcnt(8)
	s_waitcnt lgkmcnt(0)
	s_barrier
	s_setprio 1
	s_waitcnt lgkmcnt(0)
	v_mfma_f32_16x16x32_bf16 v[108:111], v[124:127], v[200:203], v[108:111]
	v_mfma_f32_16x16x32_bf16 v[76:79], v[174:177], v[200:203], v[76:79]
	v_mfma_f32_16x16x32_bf16 v[104:107], v[124:127], v[208:211], v[104:107]
	v_mfma_f32_16x16x32_bf16 v[72:75], v[174:177], v[208:211], v[72:75]
	v_mfma_f32_16x16x32_bf16 v[100:103], v[124:127], v[216:219], v[100:103]
	v_mfma_f32_16x16x32_bf16 v[68:71], v[174:177], v[216:219], v[68:71]
	v_mfma_f32_16x16x32_bf16 v[92:95], v[124:127], v[234:237], v[92:95]
	v_mfma_f32_16x16x32_bf16 v[60:63], v[174:177], v[234:237], v[60:63]
	v_mfma_f32_16x16x32_bf16 v[108:111], v[128:131], v[204:207], v[108:111]
	v_mfma_f32_16x16x32_bf16 v[76:79], v[178:181], v[204:207], v[76:79]
	v_mfma_f32_16x16x32_bf16 v[104:107], v[128:131], v[212:215], v[104:107]
	v_mfma_f32_16x16x32_bf16 v[72:75], v[178:181], v[212:215], v[72:75]
	v_mfma_f32_16x16x32_bf16 v[100:103], v[128:131], v[230:233], v[100:103]
	v_mfma_f32_16x16x32_bf16 v[68:71], v[178:181], v[230:233], v[68:71]
	v_mfma_f32_16x16x32_bf16 v[92:95], v[128:131], v[238:241], v[92:95]
	v_mfma_f32_16x16x32_bf16 v[60:63], v[178:181], v[238:241], v[60:63]
	v_mfma_f32_16x16x32_bf16 v[44:47], v[182:185], v[200:203], v[44:47]
	v_mfma_f32_16x16x32_bf16 v[12:15], v[190:193], v[200:203], v[12:15]
	v_mfma_f32_16x16x32_bf16 v[40:43], v[182:185], v[208:211], v[40:43]
	v_mfma_f32_16x16x32_bf16 v[8:11], v[190:193], v[208:211], v[8:11]
	v_mfma_f32_16x16x32_bf16 v[36:39], v[182:185], v[216:219], v[36:39]
	v_mfma_f32_16x16x32_bf16 v[4:7], v[190:193], v[216:219], v[4:7]
	v_mfma_f32_16x16x32_bf16 v[28:31], v[182:185], v[234:237], v[28:31]
	v_mfma_f32_16x16x32_bf16 v[0:3], v[190:193], v[234:237], v[0:3]
	v_mfma_f32_16x16x32_bf16 v[44:47], v[186:189], v[204:207], v[44:47]
	v_mfma_f32_16x16x32_bf16 v[12:15], v[194:197], v[204:207], v[12:15]
	v_mfma_f32_16x16x32_bf16 v[40:43], v[186:189], v[212:215], v[40:43]
	v_mfma_f32_16x16x32_bf16 v[8:11], v[194:197], v[212:215], v[8:11]
	v_mfma_f32_16x16x32_bf16 v[36:39], v[186:189], v[230:233], v[36:39]
	v_mfma_f32_16x16x32_bf16 v[4:7], v[194:197], v[230:233], v[4:7]
	v_mfma_f32_16x16x32_bf16 v[28:31], v[186:189], v[238:241], v[28:31]
	v_mfma_f32_16x16x32_bf16 v[0:3], v[194:197], v[238:241], v[0:3]
	s_setprio 0
	s_barrier
	s_add_i32 s62, 0, 0x18000
	s_add_i32 s63, 0, 0x1c000
	v_add_u32_e32 v178, s62, v198
	v_add_u32_e32 v194, s63, v198
	ds_read_b128 v[124:127], v178
	ds_read_b128 v[128:131], v178 offset:1024
	ds_read_b128 v[174:177], v178 offset:2048
	ds_read_b128 v[178:181], v178 offset:3072
	ds_read_b128 v[182:185], v194
	ds_read_b128 v[186:189], v194 offset:1024
	ds_read_b128 v[190:193], v194 offset:2048
	ds_read_b128 v[194:197], v194 offset:3072
	s_add_u32 s28, s68, 0x40000
	s_addc_u32 s29, s69, 0
	s_mov_b32 m0, s70
	v_lshl_add_u64 v[248:249], s[28:29], 0, v[142:143]
	ds_read_b128 v[200:203], v199 offset:32768
	ds_read_b128 v[204:207], v199 offset:33792
	ds_read_b128 v[208:211], v199 offset:34816
	ds_read_b128 v[212:215], v199 offset:35840
	ds_read_b128 v[216:219], v199 offset:36864
	ds_read_b128 v[230:233], v199 offset:37888
	ds_read_b128 v[234:237], v199 offset:38912
	ds_read_b128 v[238:241], v199 offset:39936
	global_load_lds_dwordx4 v[248:249], off
	v_lshl_add_u64 v[248:249], s[28:29], 0, v[136:137]
	s_mov_b32 m0, s71
	s_nop 0
	global_load_lds_dwordx4 v[248:249], off
	s_waitcnt vmcnt(8)
	s_waitcnt lgkmcnt(0)
	s_barrier
	s_setprio 1
	s_waitcnt lgkmcnt(0)
	v_mfma_f32_16x16x32_bf16 v[132:135], v[124:127], v[200:203], v[132:135]
	v_mfma_f32_16x16x32_bf16 v[96:99], v[174:177], v[200:203], v[96:99]
	v_mfma_f32_16x16x32_bf16 v[120:123], v[124:127], v[208:211], v[120:123]
	v_mfma_f32_16x16x32_bf16 v[88:91], v[174:177], v[208:211], v[88:91]
	v_mfma_f32_16x16x32_bf16 v[116:119], v[124:127], v[216:219], v[116:119]
	v_mfma_f32_16x16x32_bf16 v[84:87], v[174:177], v[216:219], v[84:87]
	v_mfma_f32_16x16x32_bf16 v[112:115], v[124:127], v[234:237], v[112:115]
	v_mfma_f32_16x16x32_bf16 v[80:83], v[174:177], v[234:237], v[80:83]
	v_mfma_f32_16x16x32_bf16 v[132:135], v[128:131], v[204:207], v[132:135]
	v_mfma_f32_16x16x32_bf16 v[96:99], v[178:181], v[204:207], v[96:99]
	v_mfma_f32_16x16x32_bf16 v[120:123], v[128:131], v[212:215], v[120:123]
	v_mfma_f32_16x16x32_bf16 v[88:91], v[178:181], v[212:215], v[88:91]
	v_mfma_f32_16x16x32_bf16 v[116:119], v[128:131], v[230:233], v[116:119]
	v_mfma_f32_16x16x32_bf16 v[84:87], v[178:181], v[230:233], v[84:87]
	v_mfma_f32_16x16x32_bf16 v[112:115], v[128:131], v[238:241], v[112:115]
	v_mfma_f32_16x16x32_bf16 v[80:83], v[178:181], v[238:241], v[80:83]
	v_mfma_f32_16x16x32_bf16 v[64:67], v[182:185], v[200:203], v[64:67]
	v_mfma_f32_16x16x32_bf16 v[32:35], v[190:193], v[200:203], v[32:35]
	v_mfma_f32_16x16x32_bf16 v[56:59], v[182:185], v[208:211], v[56:59]
	v_mfma_f32_16x16x32_bf16 v[24:27], v[190:193], v[208:211], v[24:27]
	v_mfma_f32_16x16x32_bf16 v[52:55], v[182:185], v[216:219], v[52:55]
	v_mfma_f32_16x16x32_bf16 v[20:23], v[190:193], v[216:219], v[20:23]
	v_mfma_f32_16x16x32_bf16 v[48:51], v[182:185], v[234:237], v[48:51]
	v_mfma_f32_16x16x32_bf16 v[16:19], v[190:193], v[234:237], v[16:19]
	v_mfma_f32_16x16x32_bf16 v[64:67], v[186:189], v[204:207], v[64:67]
	v_mfma_f32_16x16x32_bf16 v[32:35], v[194:197], v[204:207], v[32:35]
	v_mfma_f32_16x16x32_bf16 v[56:59], v[186:189], v[212:215], v[56:59]
	v_mfma_f32_16x16x32_bf16 v[24:27], v[194:197], v[212:215], v[24:27]
	v_mfma_f32_16x16x32_bf16 v[52:55], v[186:189], v[230:233], v[52:55]
	v_mfma_f32_16x16x32_bf16 v[20:23], v[194:197], v[230:233], v[20:23]
	v_mfma_f32_16x16x32_bf16 v[48:51], v[186:189], v[238:241], v[48:51]
	v_mfma_f32_16x16x32_bf16 v[16:19], v[194:197], v[238:241], v[16:19]
	s_setprio 0
	s_barrier
	s_add_i32 s28, s62, s2
	v_lshl_add_u64 v[220:221], v[220:221], 0, s[22:23]
	s_mov_b32 m0, s28
	ds_read_b128 v[200:203], v199 offset:49152
	ds_read_b128 v[204:207], v199 offset:50176
	ds_read_b128 v[208:211], v199 offset:51200
	ds_read_b128 v[212:215], v199 offset:52224
	ds_read_b128 v[216:219], v199 offset:53248
	ds_read_b128 v[230:233], v199 offset:54272
	ds_read_b128 v[234:237], v199 offset:55296
	ds_read_b128 v[238:241], v199 offset:56320
	global_load_lds_dwordx4 v[220:221], off
	s_add_i32 m0, s28, 0x2000
	s_add_u32 s28, s66, 0x40080
	v_lshl_add_u64 v[220:221], v[242:243], 0, s[22:23]
	s_addc_u32 s29, s67, 0
	s_add_i32 s62, s63, s2
	global_load_lds_dwordx4 v[220:221], off
	v_lshl_add_u64 v[220:221], s[28:29], 0, v[142:143]
	s_mov_b32 m0, s62
	s_nop 0
	global_load_lds_dwordx4 v[220:221], off
	v_lshl_add_u64 v[220:221], s[28:29], 0, v[136:137]
	s_add_i32 m0, s62, 0x2000
	s_nop 0
	global_load_lds_dwordx4 v[220:221], off
	v_lshl_add_u64 v[220:221], v[244:245], 0, s[22:23]
	s_mov_b32 m0, s72
	s_nop 0
	global_load_lds_dwordx4 v[220:221], off
	v_lshl_add_u64 v[220:221], v[246:247], 0, s[22:23]
	s_mov_b32 m0, s73
	s_nop 0
	global_load_lds_dwordx4 v[220:221], off
	s_waitcnt vmcnt(8)
	s_waitcnt lgkmcnt(0)
	s_barrier
	s_setprio 1
	s_waitcnt lgkmcnt(0)
	v_mfma_f32_16x16x32_bf16 v[108:111], v[124:127], v[200:203], v[108:111]
	v_mfma_f32_16x16x32_bf16 v[76:79], v[174:177], v[200:203], v[76:79]
	v_mfma_f32_16x16x32_bf16 v[104:107], v[124:127], v[208:211], v[104:107]
	v_mfma_f32_16x16x32_bf16 v[72:75], v[174:177], v[208:211], v[72:75]
	v_mfma_f32_16x16x32_bf16 v[100:103], v[124:127], v[216:219], v[100:103]
	v_mfma_f32_16x16x32_bf16 v[68:71], v[174:177], v[216:219], v[68:71]
	v_mfma_f32_16x16x32_bf16 v[92:95], v[124:127], v[234:237], v[92:95]
	v_mfma_f32_16x16x32_bf16 v[60:63], v[174:177], v[234:237], v[60:63]
	v_mfma_f32_16x16x32_bf16 v[108:111], v[128:131], v[204:207], v[108:111]
	v_mfma_f32_16x16x32_bf16 v[76:79], v[178:181], v[204:207], v[76:79]
	v_mfma_f32_16x16x32_bf16 v[104:107], v[128:131], v[212:215], v[104:107]
	v_mfma_f32_16x16x32_bf16 v[72:75], v[178:181], v[212:215], v[72:75]
	v_mfma_f32_16x16x32_bf16 v[100:103], v[128:131], v[230:233], v[100:103]
	v_mfma_f32_16x16x32_bf16 v[68:71], v[178:181], v[230:233], v[68:71]
	v_mfma_f32_16x16x32_bf16 v[92:95], v[128:131], v[238:241], v[92:95]
	v_mfma_f32_16x16x32_bf16 v[60:63], v[178:181], v[238:241], v[60:63]
	v_mfma_f32_16x16x32_bf16 v[44:47], v[182:185], v[200:203], v[44:47]
	v_mfma_f32_16x16x32_bf16 v[12:15], v[190:193], v[200:203], v[12:15]
	v_mfma_f32_16x16x32_bf16 v[40:43], v[182:185], v[208:211], v[40:43]
	v_mfma_f32_16x16x32_bf16 v[8:11], v[190:193], v[208:211], v[8:11]
	v_mfma_f32_16x16x32_bf16 v[36:39], v[182:185], v[216:219], v[36:39]
	v_mfma_f32_16x16x32_bf16 v[4:7], v[190:193], v[216:219], v[4:7]
	v_mfma_f32_16x16x32_bf16 v[28:31], v[182:185], v[234:237], v[28:31]
	v_mfma_f32_16x16x32_bf16 v[0:3], v[190:193], v[234:237], v[0:3]
	v_mfma_f32_16x16x32_bf16 v[44:47], v[186:189], v[204:207], v[44:47]
	v_mfma_f32_16x16x32_bf16 v[12:15], v[194:197], v[204:207], v[12:15]
	v_mfma_f32_16x16x32_bf16 v[40:43], v[186:189], v[212:215], v[40:43]
	v_mfma_f32_16x16x32_bf16 v[8:11], v[194:197], v[212:215], v[8:11]
	v_mfma_f32_16x16x32_bf16 v[36:39], v[186:189], v[230:233], v[36:39]
	v_mfma_f32_16x16x32_bf16 v[4:7], v[194:197], v[230:233], v[4:7]
	v_mfma_f32_16x16x32_bf16 v[28:31], v[186:189], v[238:241], v[28:31]
	v_mfma_f32_16x16x32_bf16 v[0:3], v[194:197], v[238:241], v[0:3]
	s_setprio 0
	s_barrier
	s_add_i32 s79, s79, 2
	s_add_u32 s77, s77, 0x100
	s_addc_u32 s78, s78, 0
	s_cmp_gt_u32 s79, 13
	s_mov_b64 s[62:63], s[64:65]
	s_cbranch_scc0 .LBB0_1083
	s_and_b64 vcc, exec, s[50:51]
	s_cbranch_vccz .LBB0_1086
	s_barrier
